# v59 with the 112 s_nop slots (former s_setprio in GEMM K-loops) deleted
# speedup vs baseline: 1.0011x; 1.0011x over previous
.LBB0_154:
	ds_read_b128 v[130:133], v139
	ds_read_b128 v[134:137], v139 offset:1024
	ds_read_b128 v[150:153], v139 offset:2048
	ds_read_b128 v[154:157], v139 offset:3072
	s_add_u32 s6, s2, 0xfffc0080
	s_addc_u32 s7, s3, -1
	s_cmp_eq_u32 s15, 12
	s_cselect_b32 s9, s1, s7
	s_cselect_b32 s8, s10, s6
	s_cselect_b32 s7, s11, s14
	s_cselect_b32 s6, s12, s13
	v_lshl_add_u64 v[174:175], s[2:3], 0, v[142:143]
	s_add_i32 m0, s47, 0xc000
	ds_read_b128 v[158:161], v176
	ds_read_b128 v[162:165], v176 offset:1024
	ds_read_b128 v[166:169], v176 offset:2048
	ds_read_b128 v[170:173], v176 offset:3072
	ds_read_b128 v[184:187], v176 offset:4096
	ds_read_b128 v[188:191], v176 offset:5120
	ds_read_b128 v[192:195], v176 offset:6144
	ds_read_b128 v[196:199], v176 offset:7168
	global_load_lds_dwordx4 v[174:175], off
	v_lshl_add_u64 v[174:175], s[2:3], 0, v[144:145]
	s_add_i32 m0, s47, 0xe000
	s_nop 0
	global_load_lds_dwordx4 v[174:175], off
	s_waitcnt lgkmcnt(8)
	s_barrier
	s_waitcnt lgkmcnt(0)
	s_waitcnt lgkmcnt(0)
	v_mfma_f32_16x16x32_bf16 v[126:129], v[130:133], v[158:161], v[126:129]
	v_mfma_f32_16x16x32_bf16 v[118:121], v[150:153], v[158:161], v[118:121]
	v_mfma_f32_16x16x32_bf16 v[110:113], v[130:133], v[166:169], v[110:113]
	v_mfma_f32_16x16x32_bf16 v[102:105], v[150:153], v[166:169], v[102:105]
	v_mfma_f32_16x16x32_bf16 v[94:97], v[130:133], v[184:187], v[94:97]
	v_mfma_f32_16x16x32_bf16 v[86:89], v[150:153], v[184:187], v[86:89]
	v_mfma_f32_16x16x32_bf16 v[78:81], v[130:133], v[192:195], v[78:81]
	v_mfma_f32_16x16x32_bf16 v[70:73], v[150:153], v[192:195], v[70:73]
	v_mfma_f32_16x16x32_bf16 v[126:129], v[134:137], v[162:165], v[126:129]
	v_mfma_f32_16x16x32_bf16 v[118:121], v[154:157], v[162:165], v[118:121]
	v_mfma_f32_16x16x32_bf16 v[110:113], v[134:137], v[170:173], v[110:113]
	v_mfma_f32_16x16x32_bf16 v[102:105], v[154:157], v[170:173], v[102:105]
	v_mfma_f32_16x16x32_bf16 v[94:97], v[134:137], v[188:191], v[94:97]
	v_mfma_f32_16x16x32_bf16 v[86:89], v[154:157], v[188:191], v[86:89]
	v_mfma_f32_16x16x32_bf16 v[78:81], v[134:137], v[196:199], v[78:81]
	v_mfma_f32_16x16x32_bf16 v[70:73], v[154:157], v[196:199], v[70:73]
	s_barrier
	s_add_i32 s33, s60, s48
	v_lshl_add_u64 v[174:175], s[6:7], 0, v[226:227]
	s_mov_b32 m0, s33
	ds_read_b128 v[200:203], v177
	ds_read_b128 v[204:207], v177 offset:1024
	ds_read_b128 v[208:211], v177 offset:2048
	ds_read_b128 v[212:215], v177 offset:3072
	global_load_lds_dwordx4 v[174:175], off
	v_lshl_add_u64 v[216:217], s[6:7], 0, v[228:229]
	s_add_i32 m0, s33, 0x2000
	s_nop 0
	global_load_lds_dwordx4 v[216:217], off
	s_barrier
	s_waitcnt lgkmcnt(0)
	s_waitcnt lgkmcnt(0)
	v_mfma_f32_16x16x32_bf16 v[122:125], v[200:203], v[158:161], v[122:125]
	v_mfma_f32_16x16x32_bf16 v[114:117], v[208:211], v[158:161], v[114:117]
	v_mfma_f32_16x16x32_bf16 v[106:109], v[200:203], v[166:169], v[106:109]
	v_mfma_f32_16x16x32_bf16 v[98:101], v[208:211], v[166:169], v[98:101]
	v_mfma_f32_16x16x32_bf16 v[90:93], v[200:203], v[184:187], v[90:93]
	v_mfma_f32_16x16x32_bf16 v[82:85], v[208:211], v[184:187], v[82:85]
	v_mfma_f32_16x16x32_bf16 v[74:77], v[200:203], v[192:195], v[74:77]
	v_mfma_f32_16x16x32_bf16 v[66:69], v[208:211], v[192:195], v[66:69]
	v_mfma_f32_16x16x32_bf16 v[122:125], v[204:207], v[162:165], v[122:125]
	v_mfma_f32_16x16x32_bf16 v[114:117], v[212:215], v[162:165], v[114:117]
	v_mfma_f32_16x16x32_bf16 v[106:109], v[204:207], v[170:173], v[106:109]
	v_mfma_f32_16x16x32_bf16 v[98:101], v[212:215], v[170:173], v[98:101]
	v_mfma_f32_16x16x32_bf16 v[90:93], v[204:207], v[188:191], v[90:93]
	v_mfma_f32_16x16x32_bf16 v[82:85], v[212:215], v[188:191], v[82:85]
	v_mfma_f32_16x16x32_bf16 v[74:77], v[204:207], v[196:199], v[74:77]
	v_mfma_f32_16x16x32_bf16 v[66:69], v[212:215], v[196:199], v[66:69]
	s_mov_b32 m0, s47
	v_lshl_add_u64 v[218:219], s[8:9], 0, v[226:227]
	s_barrier
	ds_read_b128 v[158:161], v176 offset:16384
	ds_read_b128 v[162:165], v176 offset:17408
	ds_read_b128 v[166:169], v176 offset:18432
	ds_read_b128 v[170:173], v176 offset:19456
	ds_read_b128 v[184:187], v176 offset:20480
	ds_read_b128 v[188:191], v176 offset:21504
	ds_read_b128 v[192:195], v176 offset:22528
	ds_read_b128 v[196:199], v176 offset:23552
	global_load_lds_dwordx4 v[218:219], off
	v_lshl_add_u64 v[220:221], s[8:9], 0, v[228:229]
	s_mov_b32 m0, s49
	s_nop 0
	global_load_lds_dwordx4 v[220:221], off
	s_barrier
	s_waitcnt lgkmcnt(0)
	s_waitcnt lgkmcnt(0)
	v_mfma_f32_16x16x32_bf16 v[62:65], v[130:133], v[158:161], v[62:65]
	v_mfma_f32_16x16x32_bf16 v[54:57], v[150:153], v[158:161], v[54:57]
	v_mfma_f32_16x16x32_bf16 v[46:49], v[130:133], v[166:169], v[46:49]
	v_mfma_f32_16x16x32_bf16 v[38:41], v[150:153], v[166:169], v[38:41]
	v_mfma_f32_16x16x32_bf16 v[30:33], v[130:133], v[184:187], v[30:33]
	v_mfma_f32_16x16x32_bf16 v[22:25], v[150:153], v[184:187], v[22:25]
	v_mfma_f32_16x16x32_bf16 v[14:17], v[130:133], v[192:195], v[14:17]
	v_mfma_f32_16x16x32_bf16 v[6:9], v[150:153], v[192:195], v[6:9]
	v_mfma_f32_16x16x32_bf16 v[62:65], v[134:137], v[162:165], v[62:65]
	v_mfma_f32_16x16x32_bf16 v[54:57], v[154:157], v[162:165], v[54:57]
	v_mfma_f32_16x16x32_bf16 v[46:49], v[134:137], v[170:173], v[46:49]
	v_mfma_f32_16x16x32_bf16 v[38:41], v[154:157], v[170:173], v[38:41]
	v_mfma_f32_16x16x32_bf16 v[30:33], v[134:137], v[188:191], v[30:33]
	v_mfma_f32_16x16x32_bf16 v[22:25], v[154:157], v[188:191], v[22:25]
	v_mfma_f32_16x16x32_bf16 v[14:17], v[134:137], v[196:199], v[14:17]
	v_mfma_f32_16x16x32_bf16 v[6:9], v[154:157], v[196:199], v[6:9]
	s_barrier
	s_add_u32 s82, s6, 0x40000
	s_addc_u32 s83, s7, 0
	s_add_i32 s33, s61, s48
	v_lshl_add_u64 v[130:131], s[82:83], 0, v[226:227]
	s_mov_b32 m0, s33
	s_nop 0
	global_load_lds_dwordx4 v[130:131], off
	v_lshl_add_u64 v[130:131], s[82:83], 0, v[228:229]
	s_add_i32 m0, s33, 0x2000
	s_nop 0
	global_load_lds_dwordx4 v[130:131], off
	s_waitcnt vmcnt(6)
	s_barrier
	v_mfma_f32_16x16x32_bf16 v[58:61], v[200:203], v[158:161], v[58:61]
	v_mfma_f32_16x16x32_bf16 v[50:53], v[208:211], v[158:161], v[50:53]
	v_mfma_f32_16x16x32_bf16 v[42:45], v[200:203], v[166:169], v[42:45]
	v_mfma_f32_16x16x32_bf16 v[34:37], v[208:211], v[166:169], v[34:37]
	v_mfma_f32_16x16x32_bf16 v[26:29], v[200:203], v[184:187], v[26:29]
	v_mfma_f32_16x16x32_bf16 v[18:21], v[208:211], v[184:187], v[18:21]
	v_mfma_f32_16x16x32_bf16 v[10:13], v[200:203], v[192:195], v[10:13]
	v_mfma_f32_16x16x32_bf16 v[2:5], v[208:211], v[192:195], v[2:5]
	v_mfma_f32_16x16x32_bf16 v[58:61], v[204:207], v[162:165], v[58:61]
	v_mfma_f32_16x16x32_bf16 v[50:53], v[212:215], v[162:165], v[50:53]
	v_mfma_f32_16x16x32_bf16 v[42:45], v[204:207], v[170:173], v[42:45]
	v_mfma_f32_16x16x32_bf16 v[34:37], v[212:215], v[170:173], v[34:37]
	v_mfma_f32_16x16x32_bf16 v[26:29], v[204:207], v[188:191], v[26:29]
	v_mfma_f32_16x16x32_bf16 v[18:21], v[212:215], v[188:191], v[18:21]
	v_mfma_f32_16x16x32_bf16 v[10:13], v[204:207], v[196:199], v[10:13]
	v_mfma_f32_16x16x32_bf16 v[2:5], v[212:215], v[196:199], v[2:5]
	s_add_i32 s33, 0, 0x18000
	v_add_u32_e32 v140, s33, v1
	s_barrier
	ds_read_b128 v[130:133], v140
	ds_read_b128 v[134:137], v140 offset:1024
	ds_read_b128 v[150:153], v140 offset:2048
	ds_read_b128 v[154:157], v140 offset:3072
	s_add_u32 s8, s8, 0x40000
	s_addc_u32 s9, s9, 0
	s_mov_b32 m0, s50
	v_lshl_add_u64 v[200:201], s[8:9], 0, v[226:227]
	ds_read_b128 v[158:161], v176 offset:32768
	ds_read_b128 v[162:165], v176 offset:33792
	ds_read_b128 v[166:169], v176 offset:34816
	ds_read_b128 v[170:173], v176 offset:35840
	ds_read_b128 v[184:187], v176 offset:36864
	ds_read_b128 v[188:191], v176 offset:37888
	ds_read_b128 v[192:195], v176 offset:38912
	ds_read_b128 v[196:199], v176 offset:39936
	global_load_lds_dwordx4 v[200:201], off
	v_lshl_add_u64 v[200:201], s[8:9], 0, v[228:229]
	s_mov_b32 m0, s51
	s_nop 0
	global_load_lds_dwordx4 v[200:201], off
	s_waitcnt lgkmcnt(8)
	s_barrier
	s_waitcnt lgkmcnt(0)
	s_waitcnt lgkmcnt(0)
	v_mfma_f32_16x16x32_bf16 v[126:129], v[130:133], v[158:161], v[126:129]
	v_mfma_f32_16x16x32_bf16 v[118:121], v[150:153], v[158:161], v[118:121]
	v_mfma_f32_16x16x32_bf16 v[110:113], v[130:133], v[166:169], v[110:113]
	v_mfma_f32_16x16x32_bf16 v[102:105], v[150:153], v[166:169], v[102:105]
	v_mfma_f32_16x16x32_bf16 v[94:97], v[130:133], v[184:187], v[94:97]
	v_mfma_f32_16x16x32_bf16 v[86:89], v[150:153], v[184:187], v[86:89]
	v_mfma_f32_16x16x32_bf16 v[78:81], v[130:133], v[192:195], v[78:81]
	v_mfma_f32_16x16x32_bf16 v[70:73], v[150:153], v[192:195], v[70:73]
	v_mfma_f32_16x16x32_bf16 v[126:129], v[134:137], v[162:165], v[126:129]
	v_mfma_f32_16x16x32_bf16 v[118:121], v[154:157], v[162:165], v[118:121]
	v_mfma_f32_16x16x32_bf16 v[110:113], v[134:137], v[170:173], v[110:113]
	v_mfma_f32_16x16x32_bf16 v[102:105], v[154:157], v[170:173], v[102:105]
	v_mfma_f32_16x16x32_bf16 v[94:97], v[134:137], v[188:191], v[94:97]
	v_mfma_f32_16x16x32_bf16 v[86:89], v[154:157], v[188:191], v[86:89]
	v_mfma_f32_16x16x32_bf16 v[78:81], v[134:137], v[196:199], v[78:81]
	v_mfma_f32_16x16x32_bf16 v[70:73], v[154:157], v[196:199], v[70:73]
	s_barrier
	s_add_i32 s8, 0, 0x1c000
	s_add_i32 s9, s33, s48
	v_add_u32_e32 v140, s8, v1
	v_lshl_add_u64 v[174:175], v[174:175], 0, s[24:25]
	s_mov_b32 m0, s9
	ds_read_b128 v[200:203], v140
	ds_read_b128 v[204:207], v140 offset:1024
	ds_read_b128 v[208:211], v140 offset:2048
	ds_read_b128 v[212:215], v140 offset:3072
	global_load_lds_dwordx4 v[174:175], off
	v_lshl_add_u64 v[174:175], v[216:217], 0, s[24:25]
	s_add_i32 m0, s9, 0x2000
	s_nop 0
	global_load_lds_dwordx4 v[174:175], off
	s_barrier
	s_waitcnt lgkmcnt(0)
	s_waitcnt lgkmcnt(0)
	v_mfma_f32_16x16x32_bf16 v[122:125], v[200:203], v[158:161], v[122:125]
	v_mfma_f32_16x16x32_bf16 v[114:117], v[208:211], v[158:161], v[114:117]
	v_mfma_f32_16x16x32_bf16 v[106:109], v[200:203], v[166:169], v[106:109]
	v_mfma_f32_16x16x32_bf16 v[98:101], v[208:211], v[166:169], v[98:101]
	v_mfma_f32_16x16x32_bf16 v[90:93], v[200:203], v[184:187], v[90:93]
	v_mfma_f32_16x16x32_bf16 v[82:85], v[208:211], v[184:187], v[82:85]
	v_mfma_f32_16x16x32_bf16 v[74:77], v[200:203], v[192:195], v[74:77]
	v_mfma_f32_16x16x32_bf16 v[66:69], v[208:211], v[192:195], v[66:69]
	v_mfma_f32_16x16x32_bf16 v[122:125], v[204:207], v[162:165], v[122:125]
	v_mfma_f32_16x16x32_bf16 v[114:117], v[212:215], v[162:165], v[114:117]
	v_mfma_f32_16x16x32_bf16 v[106:109], v[204:207], v[170:173], v[106:109]
	v_mfma_f32_16x16x32_bf16 v[98:101], v[212:215], v[170:173], v[98:101]
	v_mfma_f32_16x16x32_bf16 v[90:93], v[204:207], v[188:191], v[90:93]
	v_mfma_f32_16x16x32_bf16 v[82:85], v[212:215], v[188:191], v[82:85]
	v_mfma_f32_16x16x32_bf16 v[74:77], v[204:207], v[196:199], v[74:77]
	v_mfma_f32_16x16x32_bf16 v[66:69], v[212:215], v[196:199], v[66:69]
	s_mov_b32 m0, s56
	v_lshl_add_u64 v[174:175], v[218:219], 0, s[24:25]
	s_barrier
	ds_read_b128 v[158:161], v176 offset:49152
	ds_read_b128 v[162:165], v176 offset:50176
	ds_read_b128 v[166:169], v176 offset:51200
	ds_read_b128 v[170:173], v176 offset:52224
	ds_read_b128 v[184:187], v176 offset:53248
	ds_read_b128 v[188:191], v176 offset:54272
	ds_read_b128 v[192:195], v176 offset:55296
	ds_read_b128 v[196:199], v176 offset:56320
	global_load_lds_dwordx4 v[174:175], off
	v_lshl_add_u64 v[174:175], v[220:221], 0, s[24:25]
	s_mov_b32 m0, s57
	s_nop 0
	global_load_lds_dwordx4 v[174:175], off
	s_barrier
	s_waitcnt lgkmcnt(0)
	s_waitcnt lgkmcnt(0)
	v_mfma_f32_16x16x32_bf16 v[62:65], v[130:133], v[158:161], v[62:65]
	v_mfma_f32_16x16x32_bf16 v[54:57], v[150:153], v[158:161], v[54:57]
	v_mfma_f32_16x16x32_bf16 v[46:49], v[130:133], v[166:169], v[46:49]
	v_mfma_f32_16x16x32_bf16 v[38:41], v[150:153], v[166:169], v[38:41]
	v_mfma_f32_16x16x32_bf16 v[30:33], v[130:133], v[184:187], v[30:33]
	v_mfma_f32_16x16x32_bf16 v[22:25], v[150:153], v[184:187], v[22:25]
	v_mfma_f32_16x16x32_bf16 v[14:17], v[130:133], v[192:195], v[14:17]
	v_mfma_f32_16x16x32_bf16 v[6:9], v[150:153], v[192:195], v[6:9]
	v_mfma_f32_16x16x32_bf16 v[62:65], v[134:137], v[162:165], v[62:65]
	v_mfma_f32_16x16x32_bf16 v[54:57], v[154:157], v[162:165], v[54:57]
	v_mfma_f32_16x16x32_bf16 v[46:49], v[134:137], v[170:173], v[46:49]
	v_mfma_f32_16x16x32_bf16 v[38:41], v[154:157], v[170:173], v[38:41]
	v_mfma_f32_16x16x32_bf16 v[30:33], v[134:137], v[188:191], v[30:33]
	v_mfma_f32_16x16x32_bf16 v[22:25], v[154:157], v[188:191], v[22:25]
	v_mfma_f32_16x16x32_bf16 v[14:17], v[134:137], v[196:199], v[14:17]
	v_mfma_f32_16x16x32_bf16 v[6:9], v[154:157], v[196:199], v[6:9]
	s_barrier
	s_add_u32 s6, s6, 0x40080
	s_addc_u32 s7, s7, 0
	s_add_i32 s8, s8, s48
	v_lshl_add_u64 v[130:131], s[6:7], 0, v[226:227]
	s_mov_b32 m0, s8
	s_nop 0
	global_load_lds_dwordx4 v[130:131], off
	v_lshl_add_u64 v[130:131], s[6:7], 0, v[228:229]
	s_add_i32 m0, s8, 0x2000
	s_nop 0
	global_load_lds_dwordx4 v[130:131], off
	s_waitcnt vmcnt(6)
	s_barrier
	v_mfma_f32_16x16x32_bf16 v[58:61], v[200:203], v[158:161], v[58:61]
	v_mfma_f32_16x16x32_bf16 v[50:53], v[208:211], v[158:161], v[50:53]
	v_mfma_f32_16x16x32_bf16 v[42:45], v[200:203], v[166:169], v[42:45]
	v_mfma_f32_16x16x32_bf16 v[34:37], v[208:211], v[166:169], v[34:37]
	v_mfma_f32_16x16x32_bf16 v[26:29], v[200:203], v[184:187], v[26:29]
	v_mfma_f32_16x16x32_bf16 v[18:21], v[208:211], v[184:187], v[18:21]
	v_mfma_f32_16x16x32_bf16 v[10:13], v[200:203], v[192:195], v[10:13]
	v_mfma_f32_16x16x32_bf16 v[2:5], v[208:211], v[192:195], v[2:5]
	v_mfma_f32_16x16x32_bf16 v[58:61], v[204:207], v[162:165], v[58:61]
	v_mfma_f32_16x16x32_bf16 v[50:53], v[212:215], v[162:165], v[50:53]
	v_mfma_f32_16x16x32_bf16 v[42:45], v[204:207], v[170:173], v[42:45]
	v_mfma_f32_16x16x32_bf16 v[34:37], v[212:215], v[170:173], v[34:37]
	v_mfma_f32_16x16x32_bf16 v[26:29], v[204:207], v[188:191], v[26:29]
	v_mfma_f32_16x16x32_bf16 v[18:21], v[212:215], v[188:191], v[18:21]
	v_mfma_f32_16x16x32_bf16 v[10:13], v[204:207], v[196:199], v[10:13]
	v_mfma_f32_16x16x32_bf16 v[2:5], v[212:215], v[196:199], v[2:5]
	s_add_i32 s15, s15, 2
	s_add_u32 s2, s2, 0x100
	s_addc_u32 s3, s3, 0
	s_add_u32 s13, s13, 0x100
	s_addc_u32 s14, s14, 0
	s_cmp_gt_u32 s15, 13
	s_barrier
	s_cbranch_scc0 .LBB0_154
	v_mov_b32_e32 v183, v238
	v_mov_b32_e32 v130, v239
	s_lshl_b32 s0, s0, 8
	s_add_i32 s0, s0, s54
	v_lshlrev_b32_e32 v154, 2, v130
	v_add_u32_e32 v150, s0, v183
	v_add_u32_e32 v152, s55, v154
	s_cmp_gt_i32 s46, 7
	s_mov_b64 s[0:1], -1
	s_cbranch_scc0 .LBB0_502
	s_cmp_gt_u32 s46, 23
	s_cbranch_scc0 .LBB0_435
	s_cmp_gt_u32 s46, 28
	s_cbranch_scc0 .LBB0_337
	s_cmp_lg_u32 s46, 29
	s_cbranch_scc0 .LBB0_238
	s_cmp_gt_u32 s46, 31
	s_cbranch_scc0 .LBB0_235
	s_cmp_gt_u32 s46, 39
	s_cbranch_scc0 .LBB0_232
	s_and_b64 vcc, exec, s[84:85]
	s_cbranch_vccz .LBB0_165
	v_cmp_gt_i32_e32 vcc, 2, v130
	s_and_b64 s[2:3], s[86:87], vcc
	s_and_saveexec_b64 s[0:1], s[2:3]
	s_cbranch_execz .LBB0_164
	v_ashrrev_i32_e32 v151, 31, v150
	v_readlane_b32 s68, v251, 35
	v_lshlrev_b64 v[134:135], 5, v[150:151]
	v_readlane_b32 s74, v251, 41
	v_readlane_b32 s75, v251, 42
	v_ashrrev_i32_e32 v155, 31, v154
	v_pk_mul_f32 v[132:133], v[128:129], s[34:35] op_sel_hi:[1,0]
	v_lshl_add_u64 v[134:135], s[74:75], 0, v[134:135]
	v_pk_mul_f32 v[130:131], v[126:127], s[34:35] op_sel_hi:[1,0]
	v_lshl_add_u64 v[134:135], v[154:155], 2, v[134:135]
	global_store_dwordx4 v[134:135], v[130:133], off
	s_movk_i32 s2, 0x1000
	v_readlane_b32 s69, v251, 36
	v_pk_mul_f32 v[132:133], v[112:113], s[34:35] op_sel_hi:[1,0]
	v_pk_mul_f32 v[130:131], v[110:111], s[34:35] op_sel_hi:[1,0]
	global_store_dwordx4 v[134:135], v[130:133], off offset:512
	v_readlane_b32 s70, v251, 37
	v_readlane_b32 s71, v251, 38
	v_pk_mul_f32 v[132:133], v[96:97], s[34:35] op_sel_hi:[1,0]
	v_pk_mul_f32 v[130:131], v[94:95], s[34:35] op_sel_hi:[1,0]
	global_store_dwordx4 v[134:135], v[130:133], off offset:1024
	v_readlane_b32 s72, v251, 39
	v_readlane_b32 s73, v251, 40
	v_pk_mul_f32 v[132:133], v[80:81], s[34:35] op_sel_hi:[1,0]
	v_pk_mul_f32 v[130:131], v[78:79], s[34:35] op_sel_hi:[1,0]
	global_store_dwordx4 v[134:135], v[130:133], off offset:1536
	v_add_co_u32_e32 v134, vcc, s2, v134
	s_nop 0
	v_pk_mul_f32 v[132:133], v[64:65], s[34:35] op_sel_hi:[1,0]
	v_pk_mul_f32 v[130:131], v[62:63], s[34:35] op_sel_hi:[1,0]
	v_addc_co_u32_e32 v135, vcc, 0, v135, vcc
	global_store_dwordx4 v[134:135], v[130:133], off
	v_readlane_b32 s76, v251, 43
	v_readlane_b32 s77, v251, 44
	v_pk_mul_f32 v[132:133], v[48:49], s[34:35] op_sel_hi:[1,0]
	v_pk_mul_f32 v[130:131], v[46:47], s[34:35] op_sel_hi:[1,0]
	global_store_dwordx4 v[134:135], v[130:133], off offset:512
	v_readlane_b32 s78, v251, 45
	v_readlane_b32 s79, v251, 46
	v_pk_mul_f32 v[132:133], v[32:33], s[34:35] op_sel_hi:[1,0]
	v_pk_mul_f32 v[130:131], v[30:31], s[34:35] op_sel_hi:[1,0]
	global_store_dwordx4 v[134:135], v[130:133], off offset:1024
	v_readlane_b32 s80, v251, 47
	v_readlane_b32 s81, v251, 48
	v_pk_mul_f32 v[132:133], v[16:17], s[34:35] op_sel_hi:[1,0]
	v_pk_mul_f32 v[130:131], v[14:15], s[34:35] op_sel_hi:[1,0]
	v_readlane_b32 s82, v251, 49
	v_readlane_b32 s83, v251, 50
	global_store_dwordx4 v[134:135], v[130:133], off offset:1536

.LBB0_3150:
	ds_read_b128 v[142:145], v176
	ds_read_b128 v[146:149], v176 offset:1024
	ds_read_b128 v[150:153], v176 offset:2048
	ds_read_b128 v[154:157], v176 offset:3072
	s_add_u32 s18, s16, 0xfff80080
	s_addc_u32 s19, s17, -1
	s_cmp_eq_u32 s43, 28
	s_cselect_b32 s21, s5, s19
	s_cselect_b32 s20, s39, s18
	s_cselect_b32 s19, s3, s42
	s_cselect_b32 s18, s40, s41
	v_lshl_add_u64 v[174:175], s[16:17], 0, v[134:135]
	s_add_i32 m0, s15, 0xc000
	ds_read_b128 v[158:161], v177
	ds_read_b128 v[162:165], v177 offset:1024
	ds_read_b128 v[166:169], v177 offset:2048
	ds_read_b128 v[170:173], v177 offset:3072
	ds_read_b128 v[184:187], v177 offset:4096
	ds_read_b128 v[188:191], v177 offset:5120
	ds_read_b128 v[192:195], v177 offset:6144
	ds_read_b128 v[196:199], v177 offset:7168
	global_load_lds_dwordx4 v[174:175], off
	v_lshl_add_u64 v[174:175], s[16:17], 0, v[136:137]
	s_add_i32 m0, s15, 0xe000
	s_nop 0
	global_load_lds_dwordx4 v[174:175], off
	s_waitcnt lgkmcnt(8)
	s_barrier
	s_waitcnt lgkmcnt(0)
	s_waitcnt lgkmcnt(0)
	v_mfma_f32_16x16x32_bf16 v[126:129], v[142:145], v[158:161], v[126:129]
	v_mfma_f32_16x16x32_bf16 v[122:125], v[150:153], v[158:161], v[122:125]
	v_mfma_f32_16x16x32_bf16 v[110:113], v[142:145], v[166:169], v[110:113]
	v_mfma_f32_16x16x32_bf16 v[106:109], v[150:153], v[166:169], v[106:109]
	v_mfma_f32_16x16x32_bf16 v[98:101], v[142:145], v[184:187], v[98:101]
	v_mfma_f32_16x16x32_bf16 v[90:93], v[150:153], v[184:187], v[90:93]
	v_mfma_f32_16x16x32_bf16 v[82:85], v[142:145], v[192:195], v[82:85]
	v_mfma_f32_16x16x32_bf16 v[74:77], v[150:153], v[192:195], v[74:77]
	v_mfma_f32_16x16x32_bf16 v[126:129], v[146:149], v[162:165], v[126:129]
	v_mfma_f32_16x16x32_bf16 v[122:125], v[154:157], v[162:165], v[122:125]
	v_mfma_f32_16x16x32_bf16 v[110:113], v[146:149], v[170:173], v[110:113]
	v_mfma_f32_16x16x32_bf16 v[106:109], v[154:157], v[170:173], v[106:109]
	v_mfma_f32_16x16x32_bf16 v[98:101], v[146:149], v[188:191], v[98:101]
	v_mfma_f32_16x16x32_bf16 v[90:93], v[154:157], v[188:191], v[90:93]
	v_mfma_f32_16x16x32_bf16 v[82:85], v[146:149], v[196:199], v[82:85]
	v_mfma_f32_16x16x32_bf16 v[74:77], v[154:157], v[196:199], v[74:77]
	s_barrier
	s_add_i32 s44, s36, s24
	v_lshl_add_u64 v[174:175], s[18:19], 0, v[130:131]
	s_mov_b32 m0, s44
	ds_read_b128 v[200:203], v178
	ds_read_b128 v[204:207], v178 offset:1024
	ds_read_b128 v[208:211], v178 offset:2048
	ds_read_b128 v[212:215], v178 offset:3072
	global_load_lds_dwordx4 v[174:175], off
	v_lshl_add_u64 v[180:181], s[18:19], 0, v[132:133]
	s_add_i32 m0, s44, 0x2000
	s_nop 0
	global_load_lds_dwordx4 v[180:181], off
	s_barrier
	s_waitcnt lgkmcnt(0)
	s_waitcnt lgkmcnt(0)
	v_mfma_f32_16x16x32_bf16 v[118:121], v[200:203], v[158:161], v[118:121]
	v_mfma_f32_16x16x32_bf16 v[114:117], v[208:211], v[158:161], v[114:117]
	v_mfma_f32_16x16x32_bf16 v[102:105], v[200:203], v[166:169], v[102:105]
	v_mfma_f32_16x16x32_bf16 v[94:97], v[208:211], v[166:169], v[94:97]
	v_mfma_f32_16x16x32_bf16 v[86:89], v[200:203], v[184:187], v[86:89]
	v_mfma_f32_16x16x32_bf16 v[78:81], v[208:211], v[184:187], v[78:81]
	v_mfma_f32_16x16x32_bf16 v[70:73], v[200:203], v[192:195], v[70:73]
	v_mfma_f32_16x16x32_bf16 v[66:69], v[208:211], v[192:195], v[66:69]
	v_mfma_f32_16x16x32_bf16 v[118:121], v[204:207], v[162:165], v[118:121]
	v_mfma_f32_16x16x32_bf16 v[114:117], v[212:215], v[162:165], v[114:117]
	v_mfma_f32_16x16x32_bf16 v[102:105], v[204:207], v[170:173], v[102:105]
	v_mfma_f32_16x16x32_bf16 v[94:97], v[212:215], v[170:173], v[94:97]
	v_mfma_f32_16x16x32_bf16 v[86:89], v[204:207], v[188:191], v[86:89]
	v_mfma_f32_16x16x32_bf16 v[78:81], v[212:215], v[188:191], v[78:81]
	v_mfma_f32_16x16x32_bf16 v[70:73], v[204:207], v[196:199], v[70:73]
	v_mfma_f32_16x16x32_bf16 v[66:69], v[212:215], v[196:199], v[66:69]
	s_mov_b32 m0, s15
	v_lshl_add_u64 v[216:217], s[20:21], 0, v[130:131]
	s_barrier
	ds_read_b128 v[158:161], v177 offset:16384
	ds_read_b128 v[162:165], v177 offset:17408
	ds_read_b128 v[166:169], v177 offset:18432
	ds_read_b128 v[170:173], v177 offset:19456
	ds_read_b128 v[184:187], v177 offset:20480
	ds_read_b128 v[188:191], v177 offset:21504
	ds_read_b128 v[192:195], v177 offset:22528
	ds_read_b128 v[196:199], v177 offset:23552
	global_load_lds_dwordx4 v[216:217], off
	v_lshl_add_u64 v[218:219], s[20:21], 0, v[132:133]
	s_mov_b32 m0, s25
	s_nop 0
	global_load_lds_dwordx4 v[218:219], off
	s_barrier
	s_waitcnt lgkmcnt(0)
	s_waitcnt lgkmcnt(0)
	v_mfma_f32_16x16x32_bf16 v[62:65], v[142:145], v[158:161], v[62:65]
	v_mfma_f32_16x16x32_bf16 v[58:61], v[150:153], v[158:161], v[58:61]
	v_mfma_f32_16x16x32_bf16 v[50:53], v[142:145], v[166:169], v[50:53]
	v_mfma_f32_16x16x32_bf16 v[42:45], v[150:153], v[166:169], v[42:45]
	v_mfma_f32_16x16x32_bf16 v[34:37], v[142:145], v[184:187], v[34:37]
	v_mfma_f32_16x16x32_bf16 v[26:29], v[150:153], v[184:187], v[26:29]
	v_mfma_f32_16x16x32_bf16 v[18:21], v[142:145], v[192:195], v[18:21]
	v_mfma_f32_16x16x32_bf16 v[10:13], v[150:153], v[192:195], v[10:13]
	v_mfma_f32_16x16x32_bf16 v[62:65], v[146:149], v[162:165], v[62:65]
	v_mfma_f32_16x16x32_bf16 v[58:61], v[154:157], v[162:165], v[58:61]
	v_mfma_f32_16x16x32_bf16 v[50:53], v[146:149], v[170:173], v[50:53]
	v_mfma_f32_16x16x32_bf16 v[42:45], v[154:157], v[170:173], v[42:45]
	v_mfma_f32_16x16x32_bf16 v[34:37], v[146:149], v[188:191], v[34:37]
	v_mfma_f32_16x16x32_bf16 v[26:29], v[154:157], v[188:191], v[26:29]
	v_mfma_f32_16x16x32_bf16 v[18:21], v[146:149], v[196:199], v[18:21]
	v_mfma_f32_16x16x32_bf16 v[10:13], v[154:157], v[196:199], v[10:13]
	s_barrier
	s_add_u32 s44, s18, 0x80000
	s_addc_u32 s45, s19, 0
	s_add_i32 s46, s37, s24
	v_lshl_add_u64 v[142:143], s[44:45], 0, v[130:131]
	s_mov_b32 m0, s46
	s_nop 0
	global_load_lds_dwordx4 v[142:143], off
	v_lshl_add_u64 v[142:143], s[44:45], 0, v[132:133]
	s_add_i32 m0, s46, 0x2000
	s_nop 0
	global_load_lds_dwordx4 v[142:143], off
	s_waitcnt vmcnt(6)
	s_barrier
	v_mfma_f32_16x16x32_bf16 v[54:57], v[200:203], v[158:161], v[54:57]
	v_mfma_f32_16x16x32_bf16 v[46:49], v[208:211], v[158:161], v[46:49]
	v_mfma_f32_16x16x32_bf16 v[38:41], v[200:203], v[166:169], v[38:41]
	v_mfma_f32_16x16x32_bf16 v[30:33], v[208:211], v[166:169], v[30:33]
	v_mfma_f32_16x16x32_bf16 v[22:25], v[200:203], v[184:187], v[22:25]
	v_mfma_f32_16x16x32_bf16 v[14:17], v[208:211], v[184:187], v[14:17]
	v_mfma_f32_16x16x32_bf16 v[6:9], v[200:203], v[192:195], v[6:9]
	v_mfma_f32_16x16x32_bf16 v[2:5], v[208:211], v[192:195], v[2:5]
	v_mfma_f32_16x16x32_bf16 v[54:57], v[204:207], v[162:165], v[54:57]
	v_mfma_f32_16x16x32_bf16 v[46:49], v[212:215], v[162:165], v[46:49]
	v_mfma_f32_16x16x32_bf16 v[38:41], v[204:207], v[170:173], v[38:41]
	v_mfma_f32_16x16x32_bf16 v[30:33], v[212:215], v[170:173], v[30:33]
	v_mfma_f32_16x16x32_bf16 v[22:25], v[204:207], v[188:191], v[22:25]
	v_mfma_f32_16x16x32_bf16 v[14:17], v[212:215], v[188:191], v[14:17]
	v_mfma_f32_16x16x32_bf16 v[6:9], v[204:207], v[196:199], v[6:9]
	v_mfma_f32_16x16x32_bf16 v[2:5], v[212:215], v[196:199], v[2:5]
	s_add_i32 s44, 0, 0x18000
	v_add_u32_e32 v154, s44, v1
	s_barrier
	ds_read_b128 v[142:145], v154
	ds_read_b128 v[146:149], v154 offset:1024
	ds_read_b128 v[150:153], v154 offset:2048
	ds_read_b128 v[154:157], v154 offset:3072
	s_add_u32 s20, s20, 0x80000
	s_addc_u32 s21, s21, 0
	s_mov_b32 m0, s26
	v_lshl_add_u64 v[200:201], s[20:21], 0, v[130:131]
	ds_read_b128 v[158:161], v177 offset:32768
	ds_read_b128 v[162:165], v177 offset:33792
	ds_read_b128 v[166:169], v177 offset:34816
	ds_read_b128 v[170:173], v177 offset:35840
	ds_read_b128 v[184:187], v177 offset:36864
	ds_read_b128 v[188:191], v177 offset:37888
	ds_read_b128 v[192:195], v177 offset:38912
	ds_read_b128 v[196:199], v177 offset:39936
	global_load_lds_dwordx4 v[200:201], off
	v_lshl_add_u64 v[200:201], s[20:21], 0, v[132:133]
	s_mov_b32 m0, s27
	s_nop 0
	global_load_lds_dwordx4 v[200:201], off
	s_waitcnt lgkmcnt(8)
	s_barrier
	s_waitcnt lgkmcnt(0)
	s_waitcnt lgkmcnt(0)
	v_mfma_f32_16x16x32_bf16 v[126:129], v[142:145], v[158:161], v[126:129]
	v_mfma_f32_16x16x32_bf16 v[122:125], v[150:153], v[158:161], v[122:125]
	v_mfma_f32_16x16x32_bf16 v[110:113], v[142:145], v[166:169], v[110:113]
	v_mfma_f32_16x16x32_bf16 v[106:109], v[150:153], v[166:169], v[106:109]
	v_mfma_f32_16x16x32_bf16 v[98:101], v[142:145], v[184:187], v[98:101]
	v_mfma_f32_16x16x32_bf16 v[90:93], v[150:153], v[184:187], v[90:93]
	v_mfma_f32_16x16x32_bf16 v[82:85], v[142:145], v[192:195], v[82:85]
	v_mfma_f32_16x16x32_bf16 v[74:77], v[150:153], v[192:195], v[74:77]
	v_mfma_f32_16x16x32_bf16 v[126:129], v[146:149], v[162:165], v[126:129]
	v_mfma_f32_16x16x32_bf16 v[122:125], v[154:157], v[162:165], v[122:125]
	v_mfma_f32_16x16x32_bf16 v[110:113], v[146:149], v[170:173], v[110:113]
	v_mfma_f32_16x16x32_bf16 v[106:109], v[154:157], v[170:173], v[106:109]
	v_mfma_f32_16x16x32_bf16 v[98:101], v[146:149], v[188:191], v[98:101]
	v_mfma_f32_16x16x32_bf16 v[90:93], v[154:157], v[188:191], v[90:93]
	v_mfma_f32_16x16x32_bf16 v[82:85], v[146:149], v[196:199], v[82:85]
	v_mfma_f32_16x16x32_bf16 v[74:77], v[154:157], v[196:199], v[74:77]
	s_barrier
	s_add_i32 s20, 0, 0x1c000
	s_add_i32 s21, s44, s24
	v_add_u32_e32 v179, s20, v1
	v_lshl_add_u64 v[174:175], v[174:175], 0, s[0:1]
	s_mov_b32 m0, s21
	ds_read_b128 v[200:203], v179
	ds_read_b128 v[204:207], v179 offset:1024
	ds_read_b128 v[208:211], v179 offset:2048
	ds_read_b128 v[212:215], v179 offset:3072
	global_load_lds_dwordx4 v[174:175], off
	v_lshl_add_u64 v[174:175], v[180:181], 0, s[0:1]
	s_add_i32 m0, s21, 0x2000
	s_nop 0
	global_load_lds_dwordx4 v[174:175], off
	s_barrier
	s_waitcnt lgkmcnt(0)
	s_waitcnt lgkmcnt(0)
	v_mfma_f32_16x16x32_bf16 v[118:121], v[200:203], v[158:161], v[118:121]
	v_mfma_f32_16x16x32_bf16 v[114:117], v[208:211], v[158:161], v[114:117]
	v_mfma_f32_16x16x32_bf16 v[102:105], v[200:203], v[166:169], v[102:105]
	v_mfma_f32_16x16x32_bf16 v[94:97], v[208:211], v[166:169], v[94:97]
	v_mfma_f32_16x16x32_bf16 v[86:89], v[200:203], v[184:187], v[86:89]
	v_mfma_f32_16x16x32_bf16 v[78:81], v[208:211], v[184:187], v[78:81]
	v_mfma_f32_16x16x32_bf16 v[70:73], v[200:203], v[192:195], v[70:73]
	v_mfma_f32_16x16x32_bf16 v[66:69], v[208:211], v[192:195], v[66:69]
	v_mfma_f32_16x16x32_bf16 v[118:121], v[204:207], v[162:165], v[118:121]
	v_mfma_f32_16x16x32_bf16 v[114:117], v[212:215], v[162:165], v[114:117]
	v_mfma_f32_16x16x32_bf16 v[102:105], v[204:207], v[170:173], v[102:105]
	v_mfma_f32_16x16x32_bf16 v[94:97], v[212:215], v[170:173], v[94:97]
	v_mfma_f32_16x16x32_bf16 v[86:89], v[204:207], v[188:191], v[86:89]
	v_mfma_f32_16x16x32_bf16 v[78:81], v[212:215], v[188:191], v[78:81]
	v_mfma_f32_16x16x32_bf16 v[70:73], v[204:207], v[196:199], v[70:73]
	v_mfma_f32_16x16x32_bf16 v[66:69], v[212:215], v[196:199], v[66:69]
	s_mov_b32 m0, s33
	v_lshl_add_u64 v[174:175], v[216:217], 0, s[0:1]
	s_barrier
	ds_read_b128 v[158:161], v177 offset:49152
	ds_read_b128 v[162:165], v177 offset:50176
	ds_read_b128 v[166:169], v177 offset:51200
	ds_read_b128 v[170:173], v177 offset:52224
	ds_read_b128 v[184:187], v177 offset:53248
	ds_read_b128 v[188:191], v177 offset:54272
	ds_read_b128 v[192:195], v177 offset:55296
	ds_read_b128 v[196:199], v177 offset:56320
	global_load_lds_dwordx4 v[174:175], off
	v_lshl_add_u64 v[174:175], v[218:219], 0, s[0:1]
	s_mov_b32 m0, s34
	s_nop 0
	global_load_lds_dwordx4 v[174:175], off
	s_barrier
	s_waitcnt lgkmcnt(0)
	s_waitcnt lgkmcnt(0)
	v_mfma_f32_16x16x32_bf16 v[62:65], v[142:145], v[158:161], v[62:65]
	v_mfma_f32_16x16x32_bf16 v[58:61], v[150:153], v[158:161], v[58:61]
	v_mfma_f32_16x16x32_bf16 v[50:53], v[142:145], v[166:169], v[50:53]
	v_mfma_f32_16x16x32_bf16 v[42:45], v[150:153], v[166:169], v[42:45]
	v_mfma_f32_16x16x32_bf16 v[34:37], v[142:145], v[184:187], v[34:37]
	v_mfma_f32_16x16x32_bf16 v[26:29], v[150:153], v[184:187], v[26:29]
	v_mfma_f32_16x16x32_bf16 v[18:21], v[142:145], v[192:195], v[18:21]
	v_mfma_f32_16x16x32_bf16 v[10:13], v[150:153], v[192:195], v[10:13]
	v_mfma_f32_16x16x32_bf16 v[62:65], v[146:149], v[162:165], v[62:65]
	v_mfma_f32_16x16x32_bf16 v[58:61], v[154:157], v[162:165], v[58:61]
	v_mfma_f32_16x16x32_bf16 v[50:53], v[146:149], v[170:173], v[50:53]
	v_mfma_f32_16x16x32_bf16 v[42:45], v[154:157], v[170:173], v[42:45]
	v_mfma_f32_16x16x32_bf16 v[34:37], v[146:149], v[188:191], v[34:37]
	v_mfma_f32_16x16x32_bf16 v[26:29], v[154:157], v[188:191], v[26:29]
	v_mfma_f32_16x16x32_bf16 v[18:21], v[146:149], v[196:199], v[18:21]
	v_mfma_f32_16x16x32_bf16 v[10:13], v[154:157], v[196:199], v[10:13]
	s_barrier
	s_add_u32 s18, s18, 0x80080
	s_addc_u32 s19, s19, 0
	s_add_i32 s20, s20, s24
	v_lshl_add_u64 v[142:143], s[18:19], 0, v[130:131]
	s_mov_b32 m0, s20
	s_nop 0
	global_load_lds_dwordx4 v[142:143], off
	v_lshl_add_u64 v[142:143], s[18:19], 0, v[132:133]
	s_add_i32 m0, s20, 0x2000
	s_nop 0
	global_load_lds_dwordx4 v[142:143], off
	s_waitcnt vmcnt(6)
	s_barrier
	v_mfma_f32_16x16x32_bf16 v[54:57], v[200:203], v[158:161], v[54:57]
	v_mfma_f32_16x16x32_bf16 v[46:49], v[208:211], v[158:161], v[46:49]
	v_mfma_f32_16x16x32_bf16 v[38:41], v[200:203], v[166:169], v[38:41]
	v_mfma_f32_16x16x32_bf16 v[30:33], v[208:211], v[166:169], v[30:33]
	v_mfma_f32_16x16x32_bf16 v[22:25], v[200:203], v[184:187], v[22:25]
	v_mfma_f32_16x16x32_bf16 v[14:17], v[208:211], v[184:187], v[14:17]
	v_mfma_f32_16x16x32_bf16 v[6:9], v[200:203], v[192:195], v[6:9]
	v_mfma_f32_16x16x32_bf16 v[2:5], v[208:211], v[192:195], v[2:5]
	v_mfma_f32_16x16x32_bf16 v[54:57], v[204:207], v[162:165], v[54:57]
	v_mfma_f32_16x16x32_bf16 v[46:49], v[212:215], v[162:165], v[46:49]
	v_mfma_f32_16x16x32_bf16 v[38:41], v[204:207], v[170:173], v[38:41]
	v_mfma_f32_16x16x32_bf16 v[30:33], v[212:215], v[170:173], v[30:33]
	v_mfma_f32_16x16x32_bf16 v[22:25], v[204:207], v[188:191], v[22:25]
	v_mfma_f32_16x16x32_bf16 v[14:17], v[212:215], v[188:191], v[14:17]
	v_mfma_f32_16x16x32_bf16 v[6:9], v[204:207], v[196:199], v[6:9]
	v_mfma_f32_16x16x32_bf16 v[2:5], v[212:215], v[196:199], v[2:5]
	s_add_i32 s43, s43, 2
	s_add_u32 s16, s16, 0x100
	s_addc_u32 s17, s17, 0
	s_add_u32 s41, s41, 0x100
	s_addc_u32 s42, s42, 0
	s_cmp_gt_u32 s43, 29
	s_barrier
	s_cbranch_scc0 .LBB0_3150
	s_lshl_b32 s3, s14, 8
	v_mov_b32_e32 v142, v238
	v_mov_b32_e32 v143, v239
	s_add_i32 s3, s3, s29
	v_readlane_b32 s40, v251, 19
	v_add_u32_e32 v146, s3, v142
	s_lshl_b32 s3, s38, 8
	s_or_b32 s3, s3, s31
	v_lshl_add_u32 v142, v143, 2, s3
	v_ashrrev_i32_e32 v143, 31, v142
	v_lshlrev_b64 v[142:143], 1, v[142:143]
	v_readlane_b32 s54, v251, 33
	v_readlane_b32 s55, v251, 34
	v_ashrrev_i32_e32 v147, 31, v146
	v_lshlrev_b64 v[146:147], 11, v[146:147]
	v_lshl_add_u64 v[144:145], s[54:55], 0, v[142:143]
	v_lshl_add_u64 v[148:149], v[144:145], 0, v[146:147]
	global_load_dwordx2 v[180:181], v[148:149], off
	global_load_dwordx2 v[184:185], v[148:149], off offset:32
	global_load_dwordx2 v[186:187], v[148:149], off offset:256
	global_load_dwordx2 v[188:189], v[148:149], off offset:288
	s_mov_b64 s[16:17], 0x8000
	v_lshl_add_u64 v[174:175], v[146:147], 0, s[16:17]
	v_lshl_add_u64 v[148:149], v[144:145], 0, v[174:175]
	global_load_dwordx2 v[190:191], v[148:149], off
	global_load_dwordx2 v[172:173], v[148:149], off offset:32
	global_load_dwordx2 v[170:171], v[148:149], off offset:256
	global_load_dwordx2 v[168:169], v[148:149], off offset:288
	s_mov_b64 s[16:17], 0x10000
	v_lshl_add_u64 v[164:165], v[146:147], 0, s[16:17]
	v_lshl_add_u64 v[148:149], v[144:145], 0, v[164:165]
	global_load_dwordx2 v[166:167], v[148:149], off
	global_load_dwordx2 v[162:163], v[148:149], off offset:32
	global_load_dwordx2 v[160:161], v[148:149], off offset:256
	global_load_dwordx2 v[154:155], v[148:149], off offset:288
	s_mov_b64 s[16:17], 0x18000
	v_lshl_add_u64 v[156:157], v[146:147], 0, s[16:17]
	v_lshl_add_u64 v[148:149], v[144:145], 0, v[156:157]
	global_load_dwordx2 v[158:159], v[148:149], off
	global_load_dwordx2 v[152:153], v[148:149], off offset:32
	global_load_dwordx2 v[150:151], v[148:149], off offset:256
	s_nop 0
	global_load_dwordx2 v[148:149], v[148:149], off offset:288
	v_lshl_add_u64 v[194:195], s[92:93], 0, v[146:147]
	v_lshl_add_u64 v[194:195], v[194:195], 0, v[142:143]
	s_mov_b64 s[16:17], 0x40000
	s_and_b64 vcc, exec, s[10:11]
	s_mov_b32 s38, s2
	s_mov_b32 s14, s4
	s_mov_b64 s[18:19], s[12:13]
	v_readlane_b32 s41, v251, 20
	v_readlane_b32 s42, v251, 21
	v_readlane_b32 s43, v251, 22
	v_readlane_b32 s44, v251, 23
	v_readlane_b32 s45, v251, 24
	v_readlane_b32 s46, v251, 25
	v_readlane_b32 s47, v251, 26
	v_readlane_b32 s48, v251, 27
	v_readlane_b32 s49, v251, 28
	v_readlane_b32 s50, v251, 29
	v_readlane_b32 s51, v251, 30
	v_readlane_b32 s52, v251, 31
	v_readlane_b32 s53, v251, 32
	s_waitcnt vmcnt(0)
	v_lshlrev_b32_e32 v192, 16, v180
	v_and_b32_e32 v193, 0xffff0000, v180
	v_lshlrev_b32_e32 v180, 16, v181
	v_and_b32_e32 v181, 0xffff0000, v181
	v_pk_mul_f32 v[126:127], v[126:127], v[192:193]
	v_pk_mul_f32 v[128:129], v[128:129], v[180:181]
	v_cvt_pk_bf16_f32 v126, v126, v127
	s_nop 0
	v_cvt_pk_bf16_f32 v127, v128, v129
	global_store_dwordx2 v[194:195], v[126:127], off
	v_lshlrev_b32_e32 v126, 16, v184
	v_and_b32_e32 v127, 0xffff0000, v184
	v_lshlrev_b32_e32 v128, 16, v185
	v_and_b32_e32 v129, 0xffff0000, v185
	v_pk_mul_f32 v[122:123], v[122:123], v[126:127]
	v_pk_mul_f32 v[124:125], v[124:125], v[128:129]
	v_cvt_pk_bf16_f32 v122, v122, v123
	s_nop 0
	v_cvt_pk_bf16_f32 v123, v124, v125
	global_store_dwordx2 v[194:195], v[122:123], off offset:32
	v_lshlrev_b32_e32 v122, 16, v186
	v_and_b32_e32 v123, 0xffff0000, v186
	v_lshlrev_b32_e32 v124, 16, v187
	v_and_b32_e32 v125, 0xffff0000, v187
	v_pk_mul_f32 v[118:119], v[118:119], v[122:123]
	v_pk_mul_f32 v[120:121], v[120:121], v[124:125]
	v_cvt_pk_bf16_f32 v118, v118, v119
	s_nop 0
	v_cvt_pk_bf16_f32 v119, v120, v121
	global_store_dwordx2 v[194:195], v[118:119], off offset:256
	v_lshlrev_b32_e32 v118, 16, v188
	v_and_b32_e32 v119, 0xffff0000, v188
	v_lshlrev_b32_e32 v120, 16, v189
	v_and_b32_e32 v121, 0xffff0000, v189
	v_pk_mul_f32 v[116:117], v[116:117], v[120:121]
	v_pk_mul_f32 v[114:115], v[114:115], v[118:119]
	v_lshlrev_b32_e32 v118, 16, v191
	v_cvt_pk_bf16_f32 v114, v114, v115
	v_cvt_pk_bf16_f32 v115, v116, v117
	v_lshlrev_b32_e32 v116, 16, v190
	v_and_b32_e32 v117, 0xffff0000, v190
	global_store_dwordx2 v[194:195], v[114:115], off offset:288
	v_and_b32_e32 v119, 0xffff0000, v191
	v_lshl_add_u64 v[114:115], s[92:93], 0, v[174:175]
	v_pk_mul_f32 v[110:111], v[110:111], v[116:117]
	v_lshl_add_u64 v[114:115], v[114:115], 0, v[142:143]
	v_pk_mul_f32 v[112:113], v[112:113], v[118:119]
	v_cvt_pk_bf16_f32 v110, v110, v111
	s_nop 0
	v_cvt_pk_bf16_f32 v111, v112, v113
	global_store_dwordx2 v[114:115], v[110:111], off
	v_lshlrev_b32_e32 v110, 16, v172
	v_and_b32_e32 v111, 0xffff0000, v172
	v_lshlrev_b32_e32 v112, 16, v173
	v_and_b32_e32 v113, 0xffff0000, v173
	v_pk_mul_f32 v[106:107], v[106:107], v[110:111]
	v_pk_mul_f32 v[108:109], v[108:109], v[112:113]
	v_cvt_pk_bf16_f32 v106, v106, v107
	s_nop 0
	v_cvt_pk_bf16_f32 v107, v108, v109
	global_store_dwordx2 v[114:115], v[106:107], off offset:32
	v_lshlrev_b32_e32 v106, 16, v170
	v_and_b32_e32 v107, 0xffff0000, v170
	v_lshlrev_b32_e32 v108, 16, v171
	v_and_b32_e32 v109, 0xffff0000, v171
	v_pk_mul_f32 v[102:103], v[102:103], v[106:107]
	v_pk_mul_f32 v[104:105], v[104:105], v[108:109]
	v_cvt_pk_bf16_f32 v102, v102, v103
	s_nop 0
	v_cvt_pk_bf16_f32 v103, v104, v105
	global_store_dwordx2 v[114:115], v[102:103], off offset:256
	v_lshlrev_b32_e32 v102, 16, v168
	v_and_b32_e32 v103, 0xffff0000, v168
	v_lshlrev_b32_e32 v104, 16, v169
	v_and_b32_e32 v105, 0xffff0000, v169
	v_pk_mul_f32 v[94:95], v[94:95], v[102:103]
	v_pk_mul_f32 v[96:97], v[96:97], v[104:105]
	v_cvt_pk_bf16_f32 v94, v94, v95
	v_lshl_add_u64 v[102:103], s[92:93], 0, v[164:165]
	v_cvt_pk_bf16_f32 v95, v96, v97
	global_store_dwordx2 v[114:115], v[94:95], off offset:288
	v_lshlrev_b32_e32 v94, 16, v166
	v_and_b32_e32 v95, 0xffff0000, v166
	v_lshlrev_b32_e32 v96, 16, v167
	v_and_b32_e32 v97, 0xffff0000, v167
	v_pk_mul_f32 v[94:95], v[98:99], v[94:95]
	v_lshl_add_u64 v[102:103], v[102:103], 0, v[142:143]
	v_pk_mul_f32 v[96:97], v[100:101], v[96:97]
	v_cvt_pk_bf16_f32 v94, v94, v95
	s_nop 0
	v_cvt_pk_bf16_f32 v95, v96, v97
	global_store_dwordx2 v[102:103], v[94:95], off
	v_lshlrev_b32_e32 v94, 16, v162
	v_and_b32_e32 v95, 0xffff0000, v162
	v_lshlrev_b32_e32 v96, 16, v163
	v_and_b32_e32 v97, 0xffff0000, v163
	v_pk_mul_f32 v[90:91], v[90:91], v[94:95]
	v_pk_mul_f32 v[92:93], v[92:93], v[96:97]
	v_cvt_pk_bf16_f32 v90, v90, v91
	s_nop 0
	v_cvt_pk_bf16_f32 v91, v92, v93
	global_store_dwordx2 v[102:103], v[90:91], off offset:32
	v_lshlrev_b32_e32 v90, 16, v160
	v_and_b32_e32 v91, 0xffff0000, v160
	v_lshlrev_b32_e32 v92, 16, v161
	v_and_b32_e32 v93, 0xffff0000, v161
	v_pk_mul_f32 v[86:87], v[86:87], v[90:91]
	v_pk_mul_f32 v[88:89], v[88:89], v[92:93]
	v_cvt_pk_bf16_f32 v86, v86, v87
	s_nop 0
	v_cvt_pk_bf16_f32 v87, v88, v89
	global_store_dwordx2 v[102:103], v[86:87], off offset:256
	v_lshlrev_b32_e32 v86, 16, v154
	v_and_b32_e32 v87, 0xffff0000, v154
	v_lshlrev_b32_e32 v88, 16, v155
	v_and_b32_e32 v89, 0xffff0000, v155
	v_pk_mul_f32 v[78:79], v[78:79], v[86:87]
	v_pk_mul_f32 v[80:81], v[80:81], v[88:89]
	v_cvt_pk_bf16_f32 v78, v78, v79
	v_lshl_add_u64 v[86:87], s[92:93], 0, v[156:157]
	v_cvt_pk_bf16_f32 v79, v80, v81
	global_store_dwordx2 v[102:103], v[78:79], off offset:288
	v_lshlrev_b32_e32 v78, 16, v158
	v_and_b32_e32 v79, 0xffff0000, v158
	v_lshlrev_b32_e32 v80, 16, v159
	v_and_b32_e32 v81, 0xffff0000, v159
	v_pk_mul_f32 v[78:79], v[82:83], v[78:79]
	v_lshl_add_u64 v[86:87], v[86:87], 0, v[142:143]
	v_pk_mul_f32 v[80:81], v[84:85], v[80:81]
	v_cvt_pk_bf16_f32 v78, v78, v79
	s_nop 0
	v_cvt_pk_bf16_f32 v79, v80, v81
	global_store_dwordx2 v[86:87], v[78:79], off
	v_lshlrev_b32_e32 v78, 16, v152
	v_and_b32_e32 v79, 0xffff0000, v152
	v_lshlrev_b32_e32 v80, 16, v153
	v_and_b32_e32 v81, 0xffff0000, v153
	v_pk_mul_f32 v[74:75], v[74:75], v[78:79]
	v_pk_mul_f32 v[76:77], v[76:77], v[80:81]
	v_cvt_pk_bf16_f32 v74, v74, v75
	s_nop 0
	v_cvt_pk_bf16_f32 v75, v76, v77
	global_store_dwordx2 v[86:87], v[74:75], off offset:32
	v_lshlrev_b32_e32 v74, 16, v150
	v_and_b32_e32 v75, 0xffff0000, v150
	v_lshlrev_b32_e32 v76, 16, v151
	v_and_b32_e32 v77, 0xffff0000, v151
	v_pk_mul_f32 v[70:71], v[70:71], v[74:75]
	v_pk_mul_f32 v[72:73], v[72:73], v[76:77]
	v_cvt_pk_bf16_f32 v70, v70, v71
	v_lshl_add_u64 v[76:77], v[146:147], 0, s[16:17]
	v_cvt_pk_bf16_f32 v71, v72, v73
	global_store_dwordx2 v[86:87], v[70:71], off offset:256
	v_lshlrev_b32_e32 v70, 16, v148
	v_and_b32_e32 v71, 0xffff0000, v148
	v_lshlrev_b32_e32 v72, 16, v149
	v_and_b32_e32 v73, 0xffff0000, v149
	v_pk_mul_f32 v[66:67], v[66:67], v[70:71]
	v_pk_mul_f32 v[68:69], v[68:69], v[72:73]
	v_cvt_pk_bf16_f32 v66, v66, v67
	s_mov_b64 s[16:17], 0x48000
	v_cvt_pk_bf16_f32 v67, v68, v69
	global_store_dwordx2 v[86:87], v[66:67], off offset:288
	v_lshl_add_u64 v[66:67], v[144:145], 0, v[76:77]
	global_load_dwordx2 v[78:79], v[66:67], off
	global_load_dwordx2 v[80:81], v[66:67], off offset:32
	global_load_dwordx2 v[82:83], v[66:67], off offset:256
	global_load_dwordx2 v[84:85], v[66:67], off offset:288
	v_lshl_add_u64 v[86:87], v[146:147], 0, s[16:17]
	v_lshl_add_u64 v[66:67], v[144:145], 0, v[86:87]
	global_load_dwordx2 v[88:89], v[66:67], off
	global_load_dwordx2 v[90:91], v[66:67], off offset:32
	global_load_dwordx2 v[92:93], v[66:67], off offset:256
	global_load_dwordx2 v[94:95], v[66:67], off offset:288
	s_mov_b64 s[16:17], 0x50000
	v_lshl_add_u64 v[96:97], v[146:147], 0, s[16:17]
	v_lshl_add_u64 v[66:67], v[144:145], 0, v[96:97]
	global_load_dwordx2 v[98:99], v[66:67], off
	global_load_dwordx2 v[100:101], v[66:67], off offset:32
	global_load_dwordx2 v[102:103], v[66:67], off offset:256
	global_load_dwordx2 v[104:105], v[66:67], off offset:288
	s_mov_b64 s[16:17], 0x58000
	v_lshl_add_u64 v[72:73], v[146:147], 0, s[16:17]
	v_lshl_add_u64 v[66:67], v[144:145], 0, v[72:73]
	global_load_dwordx2 v[74:75], v[66:67], off
	global_load_dwordx2 v[70:71], v[66:67], off offset:32
	global_load_dwordx2 v[68:69], v[66:67], off offset:256
	s_nop 0
	global_load_dwordx2 v[66:67], v[66:67], off offset:288
	v_lshl_add_u64 v[76:77], s[92:93], 0, v[76:77]
	v_lshl_add_u64 v[76:77], v[76:77], 0, v[142:143]
	s_mov_b64 s[16:17], s[6:7]
	s_waitcnt vmcnt(0)
	v_lshlrev_b32_e32 v106, 16, v78
	v_and_b32_e32 v107, 0xffff0000, v78
	v_lshlrev_b32_e32 v78, 16, v79
	v_and_b32_e32 v79, 0xffff0000, v79
	v_pk_mul_f32 v[62:63], v[62:63], v[106:107]
	v_pk_mul_f32 v[64:65], v[64:65], v[78:79]
	v_cvt_pk_bf16_f32 v62, v62, v63
	s_nop 0
	v_cvt_pk_bf16_f32 v63, v64, v65
	global_store_dwordx2 v[76:77], v[62:63], off
	v_lshlrev_b32_e32 v62, 16, v80
	v_and_b32_e32 v63, 0xffff0000, v80
	v_lshlrev_b32_e32 v64, 16, v81
	v_and_b32_e32 v65, 0xffff0000, v81
	v_pk_mul_f32 v[58:59], v[58:59], v[62:63]
	v_pk_mul_f32 v[60:61], v[60:61], v[64:65]
	v_cvt_pk_bf16_f32 v58, v58, v59
	s_nop 0
	v_cvt_pk_bf16_f32 v59, v60, v61
	global_store_dwordx2 v[76:77], v[58:59], off offset:32
	v_lshlrev_b32_e32 v58, 16, v82
	v_and_b32_e32 v59, 0xffff0000, v82
	v_lshlrev_b32_e32 v60, 16, v83
	v_and_b32_e32 v61, 0xffff0000, v83
	v_pk_mul_f32 v[54:55], v[54:55], v[58:59]
	v_pk_mul_f32 v[56:57], v[56:57], v[60:61]
	v_cvt_pk_bf16_f32 v54, v54, v55
	s_nop 0
	v_cvt_pk_bf16_f32 v55, v56, v57
	global_store_dwordx2 v[76:77], v[54:55], off offset:256
	v_lshlrev_b32_e32 v54, 16, v84
	v_and_b32_e32 v55, 0xffff0000, v84
	v_lshlrev_b32_e32 v56, 16, v85
	v_and_b32_e32 v57, 0xffff0000, v85
	v_pk_mul_f32 v[46:47], v[46:47], v[54:55]
	v_pk_mul_f32 v[48:49], v[48:49], v[56:57]
	v_cvt_pk_bf16_f32 v46, v46, v47
	v_lshl_add_u64 v[54:55], s[92:93], 0, v[86:87]
	v_cvt_pk_bf16_f32 v47, v48, v49
	global_store_dwordx2 v[76:77], v[46:47], off offset:288
	v_lshlrev_b32_e32 v46, 16, v88
	v_and_b32_e32 v47, 0xffff0000, v88
	v_lshlrev_b32_e32 v48, 16, v89
	v_and_b32_e32 v49, 0xffff0000, v89
	v_pk_mul_f32 v[46:47], v[50:51], v[46:47]
	v_lshl_add_u64 v[54:55], v[54:55], 0, v[142:143]
	v_pk_mul_f32 v[48:49], v[52:53], v[48:49]
	v_cvt_pk_bf16_f32 v46, v46, v47
	s_nop 0
	v_cvt_pk_bf16_f32 v47, v48, v49
	global_store_dwordx2 v[54:55], v[46:47], off
	v_lshlrev_b32_e32 v46, 16, v90
	v_and_b32_e32 v47, 0xffff0000, v90
	v_lshlrev_b32_e32 v48, 16, v91
	v_and_b32_e32 v49, 0xffff0000, v91
	v_pk_mul_f32 v[42:43], v[42:43], v[46:47]
	v_pk_mul_f32 v[44:45], v[44:45], v[48:49]
	v_cvt_pk_bf16_f32 v42, v42, v43
	s_nop 0
	v_cvt_pk_bf16_f32 v43, v44, v45
	global_store_dwordx2 v[54:55], v[42:43], off offset:32
	v_lshlrev_b32_e32 v42, 16, v92
	v_and_b32_e32 v43, 0xffff0000, v92
	v_lshlrev_b32_e32 v44, 16, v93
	v_and_b32_e32 v45, 0xffff0000, v93
	v_pk_mul_f32 v[38:39], v[38:39], v[42:43]
	v_pk_mul_f32 v[40:41], v[40:41], v[44:45]
	v_cvt_pk_bf16_f32 v38, v38, v39
	s_nop 0
	v_cvt_pk_bf16_f32 v39, v40, v41
	global_store_dwordx2 v[54:55], v[38:39], off offset:256
	v_lshlrev_b32_e32 v38, 16, v94
	v_and_b32_e32 v39, 0xffff0000, v94
	v_lshlrev_b32_e32 v40, 16, v95
	v_and_b32_e32 v41, 0xffff0000, v95
	v_pk_mul_f32 v[30:31], v[30:31], v[38:39]
	v_pk_mul_f32 v[32:33], v[32:33], v[40:41]
	v_cvt_pk_bf16_f32 v30, v30, v31
	v_lshl_add_u64 v[38:39], s[92:93], 0, v[96:97]
	v_cvt_pk_bf16_f32 v31, v32, v33
	global_store_dwordx2 v[54:55], v[30:31], off offset:288
	v_lshlrev_b32_e32 v30, 16, v98
	v_and_b32_e32 v31, 0xffff0000, v98
	v_lshlrev_b32_e32 v32, 16, v99
	v_and_b32_e32 v33, 0xffff0000, v99
	v_pk_mul_f32 v[30:31], v[34:35], v[30:31]
	v_lshl_add_u64 v[38:39], v[38:39], 0, v[142:143]
	v_pk_mul_f32 v[32:33], v[36:37], v[32:33]
	v_cvt_pk_bf16_f32 v30, v30, v31
	s_nop 0
	v_cvt_pk_bf16_f32 v31, v32, v33
	global_store_dwordx2 v[38:39], v[30:31], off
	v_lshlrev_b32_e32 v30, 16, v100
	v_and_b32_e32 v31, 0xffff0000, v100
	v_lshlrev_b32_e32 v32, 16, v101
	v_and_b32_e32 v33, 0xffff0000, v101
	v_pk_mul_f32 v[26:27], v[26:27], v[30:31]
	v_pk_mul_f32 v[28:29], v[28:29], v[32:33]
	v_cvt_pk_bf16_f32 v26, v26, v27
	s_nop 0
	v_cvt_pk_bf16_f32 v27, v28, v29
	global_store_dwordx2 v[38:39], v[26:27], off offset:32
	v_lshlrev_b32_e32 v26, 16, v102
	v_and_b32_e32 v27, 0xffff0000, v102
	v_lshlrev_b32_e32 v28, 16, v103
	v_and_b32_e32 v29, 0xffff0000, v103
	v_pk_mul_f32 v[22:23], v[22:23], v[26:27]
	v_pk_mul_f32 v[24:25], v[24:25], v[28:29]
	v_cvt_pk_bf16_f32 v22, v22, v23
	s_nop 0
	v_cvt_pk_bf16_f32 v23, v24, v25
	global_store_dwordx2 v[38:39], v[22:23], off offset:256
	v_lshlrev_b32_e32 v22, 16, v104
	v_and_b32_e32 v23, 0xffff0000, v104
	v_lshlrev_b32_e32 v24, 16, v105
	v_and_b32_e32 v25, 0xffff0000, v105
	v_pk_mul_f32 v[14:15], v[14:15], v[22:23]
	v_pk_mul_f32 v[16:17], v[16:17], v[24:25]
	v_cvt_pk_bf16_f32 v14, v14, v15
	v_lshl_add_u64 v[22:23], s[92:93], 0, v[72:73]
	v_cvt_pk_bf16_f32 v15, v16, v17
	global_store_dwordx2 v[38:39], v[14:15], off offset:288
	v_lshlrev_b32_e32 v14, 16, v74
	v_and_b32_e32 v15, 0xffff0000, v74
	v_lshlrev_b32_e32 v16, 16, v75
	v_and_b32_e32 v17, 0xffff0000, v75
	v_pk_mul_f32 v[14:15], v[18:19], v[14:15]
	v_lshl_add_u64 v[22:23], v[22:23], 0, v[142:143]
	v_pk_mul_f32 v[16:17], v[20:21], v[16:17]
	v_cvt_pk_bf16_f32 v14, v14, v15
	s_nop 0
	v_cvt_pk_bf16_f32 v15, v16, v17
	global_store_dwordx2 v[22:23], v[14:15], off
	v_lshlrev_b32_e32 v14, 16, v70
	v_and_b32_e32 v15, 0xffff0000, v70
	v_lshlrev_b32_e32 v16, 16, v71
	v_and_b32_e32 v17, 0xffff0000, v71
	v_pk_mul_f32 v[10:11], v[10:11], v[14:15]
	v_pk_mul_f32 v[12:13], v[12:13], v[16:17]
	v_cvt_pk_bf16_f32 v10, v10, v11
	s_nop 0
	v_cvt_pk_bf16_f32 v11, v12, v13
	global_store_dwordx2 v[22:23], v[10:11], off offset:32
	v_lshlrev_b32_e32 v10, 16, v68
	v_and_b32_e32 v11, 0xffff0000, v68
	v_lshlrev_b32_e32 v12, 16, v69
	v_and_b32_e32 v13, 0xffff0000, v69
	v_pk_mul_f32 v[6:7], v[6:7], v[10:11]
	v_pk_mul_f32 v[8:9], v[8:9], v[12:13]
	v_cvt_pk_bf16_f32 v6, v6, v7
	s_nop 0
	v_cvt_pk_bf16_f32 v7, v8, v9
	global_store_dwordx2 v[22:23], v[6:7], off offset:256
	v_lshlrev_b32_e32 v6, 16, v66
	v_and_b32_e32 v7, 0xffff0000, v66
	v_lshlrev_b32_e32 v8, 16, v67
	v_and_b32_e32 v9, 0xffff0000, v67
	v_pk_mul_f32 v[2:3], v[2:3], v[6:7]
	v_pk_mul_f32 v[4:5], v[4:5], v[8:9]
	v_cvt_pk_bf16_f32 v2, v2, v3
	s_nop 0
	v_cvt_pk_bf16_f32 v3, v4, v5
	global_store_dwordx2 v[22:23], v[2:3], off offset:288
	s_cbranch_vccz .LBB0_3143
	s_waitcnt vmcnt(0)
	s_cmpk_gt_u32 s22, 0xff
	s_cbranch_scc1 .LBB0_3154
	s_barrier

.LBB0_3170:
	ds_read_b128 v[138:141], v144
	ds_read_b128 v[148:151], v144 offset:1024
	ds_read_b128 v[152:155], v144 offset:2048
	ds_read_b128 v[156:159], v144 offset:3072
	s_add_u32 s18, s16, 0xfffc0080
	s_addc_u32 s19, s17, -1
	s_cmp_eq_u32 s43, 12
	s_cselect_b32 s21, s5, s19
	s_cselect_b32 s20, s39, s18
	s_cselect_b32 s19, s3, s42
	s_cselect_b32 s18, s40, s41
	v_lshl_add_u64 v[142:143], s[16:17], 0, v[130:131]
	s_add_i32 m0, s15, 0xc000
	ds_read_b128 v[160:163], v145
	ds_read_b128 v[164:167], v145 offset:1024
	ds_read_b128 v[168:171], v145 offset:2048
	ds_read_b128 v[172:175], v145 offset:3072
	ds_read_b128 v[176:179], v145 offset:4096
	ds_read_b128 v[184:187], v145 offset:5120
	ds_read_b128 v[188:191], v145 offset:6144
	ds_read_b128 v[192:195], v145 offset:7168
	global_load_lds_dwordx4 v[142:143], off
	v_lshl_add_u64 v[142:143], s[16:17], 0, v[132:133]
	s_add_i32 m0, s15, 0xe000
	s_nop 0
	global_load_lds_dwordx4 v[142:143], off
	s_waitcnt lgkmcnt(8)
	s_barrier
	s_waitcnt lgkmcnt(0)
	s_waitcnt lgkmcnt(0)
	v_mfma_f32_16x16x32_bf16 v[126:129], v[138:141], v[160:163], v[126:129]
	v_mfma_f32_16x16x32_bf16 v[122:125], v[152:155], v[160:163], v[122:125]
	v_mfma_f32_16x16x32_bf16 v[110:113], v[138:141], v[168:171], v[110:113]
	v_mfma_f32_16x16x32_bf16 v[106:109], v[152:155], v[168:171], v[106:109]
	v_mfma_f32_16x16x32_bf16 v[94:97], v[138:141], v[176:179], v[94:97]
	v_mfma_f32_16x16x32_bf16 v[90:93], v[152:155], v[176:179], v[90:93]
	v_mfma_f32_16x16x32_bf16 v[78:81], v[138:141], v[188:191], v[78:81]
	v_mfma_f32_16x16x32_bf16 v[74:77], v[152:155], v[188:191], v[74:77]
	v_mfma_f32_16x16x32_bf16 v[126:129], v[148:151], v[164:167], v[126:129]
	v_mfma_f32_16x16x32_bf16 v[122:125], v[156:159], v[164:167], v[122:125]
	v_mfma_f32_16x16x32_bf16 v[110:113], v[148:151], v[172:175], v[110:113]
	v_mfma_f32_16x16x32_bf16 v[106:109], v[156:159], v[172:175], v[106:109]
	v_mfma_f32_16x16x32_bf16 v[94:97], v[148:151], v[184:187], v[94:97]
	v_mfma_f32_16x16x32_bf16 v[90:93], v[156:159], v[184:187], v[90:93]
	v_mfma_f32_16x16x32_bf16 v[78:81], v[148:151], v[192:195], v[78:81]
	v_mfma_f32_16x16x32_bf16 v[74:77], v[156:159], v[192:195], v[74:77]
	s_barrier
	s_add_i32 s44, s36, s24
	v_lshl_add_u64 v[142:143], s[18:19], 0, v[226:227]
	s_mov_b32 m0, s44
	ds_read_b128 v[196:199], v146
	ds_read_b128 v[200:203], v146 offset:1024
	ds_read_b128 v[204:207], v146 offset:2048
	ds_read_b128 v[208:211], v146 offset:3072
	global_load_lds_dwordx4 v[142:143], off
	v_lshl_add_u64 v[180:181], s[18:19], 0, v[228:229]
	s_add_i32 m0, s44, 0x2000
	s_nop 0
	global_load_lds_dwordx4 v[180:181], off
	s_barrier
	s_waitcnt lgkmcnt(0)
	s_waitcnt lgkmcnt(0)
	v_mfma_f32_16x16x32_bf16 v[118:121], v[196:199], v[160:163], v[118:121]
	v_mfma_f32_16x16x32_bf16 v[114:117], v[204:207], v[160:163], v[114:117]
	v_mfma_f32_16x16x32_bf16 v[102:105], v[196:199], v[168:171], v[102:105]
	v_mfma_f32_16x16x32_bf16 v[98:101], v[204:207], v[168:171], v[98:101]
	v_mfma_f32_16x16x32_bf16 v[86:89], v[196:199], v[176:179], v[86:89]
	v_mfma_f32_16x16x32_bf16 v[82:85], v[204:207], v[176:179], v[82:85]
	v_mfma_f32_16x16x32_bf16 v[70:73], v[196:199], v[188:191], v[70:73]
	v_mfma_f32_16x16x32_bf16 v[66:69], v[204:207], v[188:191], v[66:69]
	v_mfma_f32_16x16x32_bf16 v[118:121], v[200:203], v[164:167], v[118:121]
	v_mfma_f32_16x16x32_bf16 v[114:117], v[208:211], v[164:167], v[114:117]
	v_mfma_f32_16x16x32_bf16 v[102:105], v[200:203], v[172:175], v[102:105]
	v_mfma_f32_16x16x32_bf16 v[98:101], v[208:211], v[172:175], v[98:101]
	v_mfma_f32_16x16x32_bf16 v[86:89], v[200:203], v[184:187], v[86:89]
	v_mfma_f32_16x16x32_bf16 v[82:85], v[208:211], v[184:187], v[82:85]
	v_mfma_f32_16x16x32_bf16 v[70:73], v[200:203], v[192:195], v[70:73]
	v_mfma_f32_16x16x32_bf16 v[66:69], v[208:211], v[192:195], v[66:69]
	s_mov_b32 m0, s15
	v_lshl_add_u64 v[212:213], s[20:21], 0, v[226:227]
	s_barrier
	ds_read_b128 v[160:163], v145 offset:16384
	ds_read_b128 v[164:167], v145 offset:17408
	ds_read_b128 v[168:171], v145 offset:18432
	ds_read_b128 v[172:175], v145 offset:19456
	ds_read_b128 v[176:179], v145 offset:20480
	ds_read_b128 v[184:187], v145 offset:21504
	ds_read_b128 v[188:191], v145 offset:22528
	ds_read_b128 v[192:195], v145 offset:23552
	global_load_lds_dwordx4 v[212:213], off
	v_lshl_add_u64 v[214:215], s[20:21], 0, v[228:229]
	s_mov_b32 m0, s25
	s_nop 0
	global_load_lds_dwordx4 v[214:215], off
	s_barrier
	s_waitcnt lgkmcnt(0)
	s_waitcnt lgkmcnt(0)
	v_mfma_f32_16x16x32_bf16 v[62:65], v[138:141], v[160:163], v[62:65]
	v_mfma_f32_16x16x32_bf16 v[58:61], v[152:155], v[160:163], v[58:61]
	v_mfma_f32_16x16x32_bf16 v[50:53], v[138:141], v[168:171], v[50:53]
	v_mfma_f32_16x16x32_bf16 v[42:45], v[152:155], v[168:171], v[42:45]
	v_mfma_f32_16x16x32_bf16 v[30:33], v[138:141], v[176:179], v[30:33]
	v_mfma_f32_16x16x32_bf16 v[26:29], v[152:155], v[176:179], v[26:29]
	v_mfma_f32_16x16x32_bf16 v[18:21], v[138:141], v[188:191], v[18:21]
	v_mfma_f32_16x16x32_bf16 v[10:13], v[152:155], v[188:191], v[10:13]
	v_mfma_f32_16x16x32_bf16 v[62:65], v[148:151], v[164:167], v[62:65]
	v_mfma_f32_16x16x32_bf16 v[58:61], v[156:159], v[164:167], v[58:61]
	v_mfma_f32_16x16x32_bf16 v[50:53], v[148:151], v[172:175], v[50:53]
	v_mfma_f32_16x16x32_bf16 v[42:45], v[156:159], v[172:175], v[42:45]
	v_mfma_f32_16x16x32_bf16 v[30:33], v[148:151], v[184:187], v[30:33]
	v_mfma_f32_16x16x32_bf16 v[26:29], v[156:159], v[184:187], v[26:29]
	v_mfma_f32_16x16x32_bf16 v[18:21], v[148:151], v[192:195], v[18:21]
	v_mfma_f32_16x16x32_bf16 v[10:13], v[156:159], v[192:195], v[10:13]
	s_barrier
	s_add_u32 s44, s18, 0x40000
	s_addc_u32 s45, s19, 0
	s_add_i32 s46, s37, s24
	v_lshl_add_u64 v[138:139], s[44:45], 0, v[226:227]
	s_mov_b32 m0, s46
	s_nop 0
	global_load_lds_dwordx4 v[138:139], off
	v_lshl_add_u64 v[138:139], s[44:45], 0, v[228:229]
	s_add_i32 m0, s46, 0x2000
	s_nop 0
	global_load_lds_dwordx4 v[138:139], off
	s_waitcnt vmcnt(6)
	s_barrier
	v_mfma_f32_16x16x32_bf16 v[54:57], v[196:199], v[160:163], v[54:57]
	v_mfma_f32_16x16x32_bf16 v[46:49], v[204:207], v[160:163], v[46:49]
	v_mfma_f32_16x16x32_bf16 v[38:41], v[196:199], v[168:171], v[38:41]
	v_mfma_f32_16x16x32_bf16 v[34:37], v[204:207], v[168:171], v[34:37]
	v_mfma_f32_16x16x32_bf16 v[22:25], v[196:199], v[176:179], v[22:25]
	v_mfma_f32_16x16x32_bf16 v[14:17], v[204:207], v[176:179], v[14:17]
	v_mfma_f32_16x16x32_bf16 v[6:9], v[196:199], v[188:191], v[6:9]
	v_mfma_f32_16x16x32_bf16 v[2:5], v[204:207], v[188:191], v[2:5]
	v_mfma_f32_16x16x32_bf16 v[54:57], v[200:203], v[164:167], v[54:57]
	v_mfma_f32_16x16x32_bf16 v[46:49], v[208:211], v[164:167], v[46:49]
	v_mfma_f32_16x16x32_bf16 v[38:41], v[200:203], v[172:175], v[38:41]
	v_mfma_f32_16x16x32_bf16 v[34:37], v[208:211], v[172:175], v[34:37]
	v_mfma_f32_16x16x32_bf16 v[22:25], v[200:203], v[184:187], v[22:25]
	v_mfma_f32_16x16x32_bf16 v[14:17], v[208:211], v[184:187], v[14:17]
	v_mfma_f32_16x16x32_bf16 v[6:9], v[200:203], v[192:195], v[6:9]
	v_mfma_f32_16x16x32_bf16 v[2:5], v[208:211], v[192:195], v[2:5]
	s_add_i32 s44, 0, 0x18000
	v_add_u32_e32 v147, s44, v1
	s_barrier
	ds_read_b128 v[138:141], v147
	ds_read_b128 v[148:151], v147 offset:1024
	ds_read_b128 v[152:155], v147 offset:2048
	ds_read_b128 v[156:159], v147 offset:3072
	s_add_u32 s20, s20, 0x40000
	s_addc_u32 s21, s21, 0
	s_mov_b32 m0, s26
	v_lshl_add_u64 v[196:197], s[20:21], 0, v[226:227]
	ds_read_b128 v[160:163], v145 offset:32768
	ds_read_b128 v[164:167], v145 offset:33792
	ds_read_b128 v[168:171], v145 offset:34816
	ds_read_b128 v[172:175], v145 offset:35840
	ds_read_b128 v[176:179], v145 offset:36864
	ds_read_b128 v[184:187], v145 offset:37888
	ds_read_b128 v[188:191], v145 offset:38912
	ds_read_b128 v[192:195], v145 offset:39936
	global_load_lds_dwordx4 v[196:197], off
	v_lshl_add_u64 v[196:197], s[20:21], 0, v[228:229]
	s_mov_b32 m0, s27
	s_nop 0
	global_load_lds_dwordx4 v[196:197], off
	s_waitcnt lgkmcnt(8)
	s_barrier
	s_waitcnt lgkmcnt(0)
	s_waitcnt lgkmcnt(0)
	v_mfma_f32_16x16x32_bf16 v[126:129], v[138:141], v[160:163], v[126:129]
	v_mfma_f32_16x16x32_bf16 v[122:125], v[152:155], v[160:163], v[122:125]
	v_mfma_f32_16x16x32_bf16 v[110:113], v[138:141], v[168:171], v[110:113]
	v_mfma_f32_16x16x32_bf16 v[106:109], v[152:155], v[168:171], v[106:109]
	v_mfma_f32_16x16x32_bf16 v[94:97], v[138:141], v[176:179], v[94:97]
	v_mfma_f32_16x16x32_bf16 v[90:93], v[152:155], v[176:179], v[90:93]
	v_mfma_f32_16x16x32_bf16 v[78:81], v[138:141], v[188:191], v[78:81]
	v_mfma_f32_16x16x32_bf16 v[74:77], v[152:155], v[188:191], v[74:77]
	v_mfma_f32_16x16x32_bf16 v[126:129], v[148:151], v[164:167], v[126:129]
	v_mfma_f32_16x16x32_bf16 v[122:125], v[156:159], v[164:167], v[122:125]
	v_mfma_f32_16x16x32_bf16 v[110:113], v[148:151], v[172:175], v[110:113]
	v_mfma_f32_16x16x32_bf16 v[106:109], v[156:159], v[172:175], v[106:109]
	v_mfma_f32_16x16x32_bf16 v[94:97], v[148:151], v[184:187], v[94:97]
	v_mfma_f32_16x16x32_bf16 v[90:93], v[156:159], v[184:187], v[90:93]
	v_mfma_f32_16x16x32_bf16 v[78:81], v[148:151], v[192:195], v[78:81]
	v_mfma_f32_16x16x32_bf16 v[74:77], v[156:159], v[192:195], v[74:77]
	s_barrier
	s_add_i32 s20, 0, 0x1c000
	s_add_i32 s21, s44, s24
	v_add_u32_e32 v147, s20, v1
	v_lshl_add_u64 v[142:143], v[142:143], 0, s[0:1]
	s_mov_b32 m0, s21
	ds_read_b128 v[196:199], v147
	ds_read_b128 v[200:203], v147 offset:1024
	ds_read_b128 v[204:207], v147 offset:2048
	ds_read_b128 v[208:211], v147 offset:3072
	global_load_lds_dwordx4 v[142:143], off
	v_lshl_add_u64 v[142:143], v[180:181], 0, s[0:1]
	s_add_i32 m0, s21, 0x2000
	s_nop 0
	global_load_lds_dwordx4 v[142:143], off
	s_barrier
	s_waitcnt lgkmcnt(0)
	s_waitcnt lgkmcnt(0)
	v_mfma_f32_16x16x32_bf16 v[118:121], v[196:199], v[160:163], v[118:121]
	v_mfma_f32_16x16x32_bf16 v[114:117], v[204:207], v[160:163], v[114:117]
	v_mfma_f32_16x16x32_bf16 v[102:105], v[196:199], v[168:171], v[102:105]
	v_mfma_f32_16x16x32_bf16 v[98:101], v[204:207], v[168:171], v[98:101]
	v_mfma_f32_16x16x32_bf16 v[86:89], v[196:199], v[176:179], v[86:89]
	v_mfma_f32_16x16x32_bf16 v[82:85], v[204:207], v[176:179], v[82:85]
	v_mfma_f32_16x16x32_bf16 v[70:73], v[196:199], v[188:191], v[70:73]
	v_mfma_f32_16x16x32_bf16 v[66:69], v[204:207], v[188:191], v[66:69]
	v_mfma_f32_16x16x32_bf16 v[118:121], v[200:203], v[164:167], v[118:121]
	v_mfma_f32_16x16x32_bf16 v[114:117], v[208:211], v[164:167], v[114:117]
	v_mfma_f32_16x16x32_bf16 v[102:105], v[200:203], v[172:175], v[102:105]
	v_mfma_f32_16x16x32_bf16 v[98:101], v[208:211], v[172:175], v[98:101]
	v_mfma_f32_16x16x32_bf16 v[86:89], v[200:203], v[184:187], v[86:89]
	v_mfma_f32_16x16x32_bf16 v[82:85], v[208:211], v[184:187], v[82:85]
	v_mfma_f32_16x16x32_bf16 v[70:73], v[200:203], v[192:195], v[70:73]
	v_mfma_f32_16x16x32_bf16 v[66:69], v[208:211], v[192:195], v[66:69]
	s_mov_b32 m0, s33
	v_lshl_add_u64 v[142:143], v[212:213], 0, s[0:1]
	s_barrier
	ds_read_b128 v[160:163], v145 offset:49152
	ds_read_b128 v[164:167], v145 offset:50176
	ds_read_b128 v[168:171], v145 offset:51200
	ds_read_b128 v[172:175], v145 offset:52224
	ds_read_b128 v[176:179], v145 offset:53248
	ds_read_b128 v[184:187], v145 offset:54272
	ds_read_b128 v[188:191], v145 offset:55296
	ds_read_b128 v[192:195], v145 offset:56320
	global_load_lds_dwordx4 v[142:143], off
	v_lshl_add_u64 v[142:143], v[214:215], 0, s[0:1]
	s_mov_b32 m0, s34
	s_nop 0
	global_load_lds_dwordx4 v[142:143], off
	s_barrier
	s_waitcnt lgkmcnt(0)
	s_waitcnt lgkmcnt(0)
	v_mfma_f32_16x16x32_bf16 v[62:65], v[138:141], v[160:163], v[62:65]
	v_mfma_f32_16x16x32_bf16 v[58:61], v[152:155], v[160:163], v[58:61]
	v_mfma_f32_16x16x32_bf16 v[50:53], v[138:141], v[168:171], v[50:53]
	v_mfma_f32_16x16x32_bf16 v[42:45], v[152:155], v[168:171], v[42:45]
	v_mfma_f32_16x16x32_bf16 v[30:33], v[138:141], v[176:179], v[30:33]
	v_mfma_f32_16x16x32_bf16 v[26:29], v[152:155], v[176:179], v[26:29]
	v_mfma_f32_16x16x32_bf16 v[18:21], v[138:141], v[188:191], v[18:21]
	v_mfma_f32_16x16x32_bf16 v[10:13], v[152:155], v[188:191], v[10:13]
	v_mfma_f32_16x16x32_bf16 v[62:65], v[148:151], v[164:167], v[62:65]
	v_mfma_f32_16x16x32_bf16 v[58:61], v[156:159], v[164:167], v[58:61]
	v_mfma_f32_16x16x32_bf16 v[50:53], v[148:151], v[172:175], v[50:53]
	v_mfma_f32_16x16x32_bf16 v[42:45], v[156:159], v[172:175], v[42:45]
	v_mfma_f32_16x16x32_bf16 v[30:33], v[148:151], v[184:187], v[30:33]
	v_mfma_f32_16x16x32_bf16 v[26:29], v[156:159], v[184:187], v[26:29]
	v_mfma_f32_16x16x32_bf16 v[18:21], v[148:151], v[192:195], v[18:21]
	v_mfma_f32_16x16x32_bf16 v[10:13], v[156:159], v[192:195], v[10:13]
	s_barrier
	s_add_u32 s18, s18, 0x40080
	s_addc_u32 s19, s19, 0
	s_add_i32 s20, s20, s24
	v_lshl_add_u64 v[138:139], s[18:19], 0, v[226:227]
	s_mov_b32 m0, s20
	s_nop 0
	global_load_lds_dwordx4 v[138:139], off
	v_lshl_add_u64 v[138:139], s[18:19], 0, v[228:229]
	s_add_i32 m0, s20, 0x2000
	s_nop 0
	global_load_lds_dwordx4 v[138:139], off
	s_waitcnt vmcnt(6)
	s_barrier
	v_mfma_f32_16x16x32_bf16 v[54:57], v[196:199], v[160:163], v[54:57]
	v_mfma_f32_16x16x32_bf16 v[46:49], v[204:207], v[160:163], v[46:49]
	v_mfma_f32_16x16x32_bf16 v[38:41], v[196:199], v[168:171], v[38:41]
	v_mfma_f32_16x16x32_bf16 v[34:37], v[204:207], v[168:171], v[34:37]
	v_mfma_f32_16x16x32_bf16 v[22:25], v[196:199], v[176:179], v[22:25]
	v_mfma_f32_16x16x32_bf16 v[14:17], v[204:207], v[176:179], v[14:17]
	v_mfma_f32_16x16x32_bf16 v[6:9], v[196:199], v[188:191], v[6:9]
	v_mfma_f32_16x16x32_bf16 v[2:5], v[204:207], v[188:191], v[2:5]
	v_mfma_f32_16x16x32_bf16 v[54:57], v[200:203], v[164:167], v[54:57]
	v_mfma_f32_16x16x32_bf16 v[46:49], v[208:211], v[164:167], v[46:49]
	v_mfma_f32_16x16x32_bf16 v[38:41], v[200:203], v[172:175], v[38:41]
	v_mfma_f32_16x16x32_bf16 v[34:37], v[208:211], v[172:175], v[34:37]
	v_mfma_f32_16x16x32_bf16 v[22:25], v[200:203], v[184:187], v[22:25]
	v_mfma_f32_16x16x32_bf16 v[14:17], v[208:211], v[184:187], v[14:17]
	v_mfma_f32_16x16x32_bf16 v[6:9], v[200:203], v[192:195], v[6:9]
	v_mfma_f32_16x16x32_bf16 v[2:5], v[208:211], v[192:195], v[2:5]
	s_add_i32 s43, s43, 2
	s_add_u32 s16, s16, 0x100
	s_addc_u32 s17, s17, 0
	s_add_u32 s41, s41, 0x100
	s_addc_u32 s42, s42, 0
	s_cmp_gt_u32 s43, 13
	s_barrier
	s_cbranch_scc0 .LBB0_3170
	s_lshl_b32 s3, s14, 8
	v_mov_b32_e32 v138, v238
	v_mov_b32_e32 v139, v239
	s_add_i32 s3, s3, s29
	v_readlane_b32 s40, v251, 35
	v_add_u32_e32 v142, s3, v138
	s_lshl_b32 s3, s38, 8
	s_or_b32 s3, s3, s31
	v_lshl_add_u32 v140, v139, 2, s3
	v_ashrrev_i32_e32 v143, 31, v142
	v_ashrrev_i32_e32 v141, 31, v140
	v_lshlrev_b64 v[138:139], 10, v[142:143]
	v_lshl_add_u64 v[138:139], v[138:139], 0, v[140:141]
	v_lshlrev_b64 v[138:139], 1, v[138:139]
	v_readlane_b32 s41, v251, 36
	v_add_u32_e32 v158, 16, v142
	v_lshl_add_u64 v[148:149], s[92:93], 0, v[138:139]
	v_lshl_add_u64 v[138:139], s[40:41], 0, v[138:139]
	v_ashrrev_i32_e32 v159, 31, v158
	global_load_dwordx2 v[150:151], v[148:149], off
	global_load_dwordx2 v[152:153], v[148:149], off offset:32
	global_load_dwordx2 v[154:155], v[148:149], off offset:256
	s_nop 0
	global_load_dwordx2 v[148:149], v[148:149], off offset:288
	v_lshlrev_b64 v[160:161], 10, v[158:159]
	global_load_dwordx2 v[156:157], v[138:139], off
	global_load_dwordx2 v[162:163], v[138:139], off offset:32
	v_lshl_add_u64 v[160:161], v[160:161], 0, v[140:141]
	v_lshlrev_b64 v[160:161], 1, v[160:161]
	v_lshl_add_u64 v[164:165], s[92:93], 0, v[160:161]
	global_load_dwordx2 v[166:167], v[164:165], off
	global_load_dwordx2 v[168:169], v[164:165], off offset:32
	global_load_dwordx2 v[170:171], v[164:165], off offset:256
	s_nop 0
	global_load_dwordx2 v[164:165], v[164:165], off offset:288
	s_nop 0
	global_load_dwordx2 v[172:173], v[138:139], off offset:256
	global_load_dwordx2 v[174:175], v[138:139], off offset:288
	v_lshl_add_u64 v[160:161], s[40:41], 0, v[160:161]
	global_load_dwordx2 v[176:177], v[160:161], off
	global_load_dwordx2 v[180:181], v[160:161], off offset:32
	global_load_dwordx2 v[184:185], v[160:161], off offset:256
	s_nop 0
	global_load_dwordx2 v[160:161], v[160:161], off offset:288
	v_lshlrev_b64 v[178:179], 11, v[142:143]
	v_lshlrev_b64 v[138:139], 1, v[140:141]
	v_lshl_add_u64 v[178:179], s[94:95], 0, v[178:179]
	v_lshl_add_u64 v[178:179], v[178:179], 0, v[138:139]
	s_and_b64 vcc, exec, s[10:11]
	s_mov_b32 s38, s2
	s_mov_b32 s14, s4
	s_mov_b64 s[18:19], s[12:13]
	s_mov_b64 s[16:17], s[6:7]
	v_readlane_b32 s42, v251, 37
	v_readlane_b32 s43, v251, 38
	v_readlane_b32 s44, v251, 39
	v_readlane_b32 s45, v251, 40
	v_readlane_b32 s46, v251, 41
	v_readlane_b32 s47, v251, 42
	v_readlane_b32 s48, v251, 43
	v_readlane_b32 s49, v251, 44
	v_readlane_b32 s50, v251, 45
	v_readlane_b32 s51, v251, 46
	v_readlane_b32 s52, v251, 47
	v_readlane_b32 s53, v251, 48
	v_readlane_b32 s54, v251, 49
	v_readlane_b32 s55, v251, 50
	s_waitcnt vmcnt(0)
	v_lshlrev_b32_e32 v186, 16, v150
	v_and_b32_e32 v187, 0xffff0000, v150
	v_lshlrev_b32_e32 v188, 16, v152
	v_and_b32_e32 v189, 0xffff0000, v152
	v_lshlrev_b32_e32 v150, 16, v151
	v_lshlrev_b32_e32 v194, 16, v156
	v_and_b32_e32 v195, 0xffff0000, v156
	v_lshlrev_b32_e32 v196, 16, v162
	v_and_b32_e32 v197, 0xffff0000, v162
	v_and_b32_e32 v151, 0xffff0000, v151
	v_lshlrev_b32_e32 v152, 16, v153
	v_and_b32_e32 v153, 0xffff0000, v153
	v_lshlrev_b32_e32 v156, 16, v157
	v_and_b32_e32 v157, 0xffff0000, v157
	v_lshlrev_b32_e32 v162, 16, v163
	v_and_b32_e32 v163, 0xffff0000, v163
	v_pk_fma_f32 v[126:127], v[126:127], v[194:195], v[186:187]
	v_pk_fma_f32 v[122:123], v[122:123], v[196:197], v[188:189]
	v_pk_fma_f32 v[128:129], v[128:129], v[156:157], v[150:151]
	v_pk_fma_f32 v[124:125], v[124:125], v[162:163], v[152:153]
	v_cvt_pk_bf16_f32 v126, v126, v127
	v_cvt_pk_bf16_f32 v127, v128, v129
	global_store_dwordx2 v[178:179], v[126:127], off
	v_cvt_pk_bf16_f32 v122, v122, v123
	v_cvt_pk_bf16_f32 v123, v124, v125
	v_lshlrev_b32_e32 v190, 16, v154
	v_and_b32_e32 v191, 0xffff0000, v154
	global_store_dwordx2 v[178:179], v[122:123], off offset:32
	v_lshlrev_b32_e32 v122, 16, v172
	v_and_b32_e32 v123, 0xffff0000, v172
	v_lshlrev_b32_e32 v154, 16, v155
	v_and_b32_e32 v155, 0xffff0000, v155
	v_lshlrev_b32_e32 v124, 16, v173
	v_and_b32_e32 v125, 0xffff0000, v173
	v_pk_fma_f32 v[118:119], v[118:119], v[122:123], v[190:191]
	v_pk_fma_f32 v[120:121], v[120:121], v[124:125], v[154:155]
	v_cvt_pk_bf16_f32 v118, v118, v119
	v_lshlrev_b32_e32 v192, 16, v148
	v_cvt_pk_bf16_f32 v119, v120, v121
	v_and_b32_e32 v193, 0xffff0000, v148
	global_store_dwordx2 v[178:179], v[118:119], off offset:256
	v_lshlrev_b32_e32 v118, 16, v174
	v_and_b32_e32 v119, 0xffff0000, v174
	v_lshlrev_b32_e32 v148, 16, v149
	v_and_b32_e32 v149, 0xffff0000, v149
	v_lshlrev_b32_e32 v120, 16, v175
	v_and_b32_e32 v121, 0xffff0000, v175
	v_pk_fma_f32 v[114:115], v[114:115], v[118:119], v[192:193]
	v_pk_fma_f32 v[116:117], v[116:117], v[120:121], v[148:149]
	v_cvt_pk_bf16_f32 v114, v114, v115
	v_lshlrev_b32_e32 v198, 16, v166
	v_cvt_pk_bf16_f32 v115, v116, v117
	v_and_b32_e32 v199, 0xffff0000, v166
	global_store_dwordx2 v[178:179], v[114:115], off offset:288
	v_lshlrev_b64 v[114:115], 11, v[158:159]
	v_lshlrev_b32_e32 v116, 16, v176
	v_and_b32_e32 v117, 0xffff0000, v176
	v_lshlrev_b32_e32 v166, 16, v167
	v_and_b32_e32 v167, 0xffff0000, v167
	v_lshlrev_b32_e32 v118, 16, v177
	v_and_b32_e32 v119, 0xffff0000, v177
	v_lshl_add_u64 v[114:115], s[94:95], 0, v[114:115]
	v_pk_fma_f32 v[110:111], v[110:111], v[116:117], v[198:199]
	v_lshl_add_u64 v[114:115], v[114:115], 0, v[138:139]
	v_pk_fma_f32 v[112:113], v[112:113], v[118:119], v[166:167]
	v_cvt_pk_bf16_f32 v110, v110, v111
	v_lshlrev_b32_e32 v200, 16, v168
	v_cvt_pk_bf16_f32 v111, v112, v113
	v_and_b32_e32 v201, 0xffff0000, v168
	global_store_dwordx2 v[114:115], v[110:111], off
	v_lshlrev_b32_e32 v110, 16, v180
	v_and_b32_e32 v111, 0xffff0000, v180
	v_lshlrev_b32_e32 v168, 16, v169
	v_and_b32_e32 v169, 0xffff0000, v169
	v_lshlrev_b32_e32 v112, 16, v181
	v_and_b32_e32 v113, 0xffff0000, v181
	v_pk_fma_f32 v[106:107], v[106:107], v[110:111], v[200:201]
	v_pk_fma_f32 v[108:109], v[108:109], v[112:113], v[168:169]
	v_cvt_pk_bf16_f32 v106, v106, v107
	v_lshlrev_b32_e32 v202, 16, v170
	v_cvt_pk_bf16_f32 v107, v108, v109
	v_and_b32_e32 v203, 0xffff0000, v170
	global_store_dwordx2 v[114:115], v[106:107], off offset:32
	v_lshlrev_b32_e32 v106, 16, v184
	v_and_b32_e32 v107, 0xffff0000, v184
	v_lshlrev_b32_e32 v170, 16, v171
	v_and_b32_e32 v171, 0xffff0000, v171
	v_lshlrev_b32_e32 v108, 16, v185
	v_and_b32_e32 v109, 0xffff0000, v185
	v_pk_fma_f32 v[102:103], v[102:103], v[106:107], v[202:203]
	v_pk_fma_f32 v[104:105], v[104:105], v[108:109], v[170:171]
	v_cvt_pk_bf16_f32 v102, v102, v103
	v_lshlrev_b32_e32 v204, 16, v164
	v_cvt_pk_bf16_f32 v103, v104, v105
	v_and_b32_e32 v205, 0xffff0000, v164
	global_store_dwordx2 v[114:115], v[102:103], off offset:256
	v_lshlrev_b32_e32 v102, 16, v160
	v_and_b32_e32 v103, 0xffff0000, v160
	v_pk_fma_f32 v[98:99], v[98:99], v[102:103], v[204:205]
	v_lshlrev_b32_e32 v164, 16, v165
	v_and_b32_e32 v165, 0xffff0000, v165
	v_lshlrev_b32_e32 v104, 16, v161
	v_and_b32_e32 v105, 0xffff0000, v161
	v_cvt_pk_bf16_f32 v98, v98, v99
	v_pk_fma_f32 v[100:101], v[100:101], v[104:105], v[164:165]
	v_add_u32_e32 v110, 48, v142
	v_cvt_pk_bf16_f32 v99, v100, v101
	global_store_dwordx2 v[114:115], v[98:99], off offset:288
	v_add_u32_e32 v98, 32, v142
	v_ashrrev_i32_e32 v99, 31, v98
	v_ashrrev_i32_e32 v111, 31, v110
	v_lshlrev_b64 v[100:101], 10, v[98:99]
	v_lshlrev_b64 v[112:113], 10, v[110:111]
	v_lshl_add_u64 v[100:101], v[100:101], 0, v[140:141]
	v_lshl_add_u64 v[112:113], v[112:113], 0, v[140:141]
	v_lshlrev_b64 v[100:101], 1, v[100:101]
	v_lshlrev_b64 v[112:113], 1, v[112:113]
	v_lshl_add_u64 v[102:103], s[92:93], 0, v[100:101]
	v_lshl_add_u64 v[114:115], s[92:93], 0, v[112:113]
	v_lshl_add_u64 v[100:101], s[40:41], 0, v[100:101]
	global_load_dwordx2 v[104:105], v[102:103], off
	global_load_dwordx2 v[106:107], v[102:103], off offset:32
	global_load_dwordx2 v[108:109], v[102:103], off offset:256
	s_nop 0
	global_load_dwordx2 v[102:103], v[102:103], off offset:288
	s_nop 0
	global_load_dwordx2 v[116:117], v[114:115], off
	global_load_dwordx2 v[118:119], v[114:115], off offset:32
	global_load_dwordx2 v[120:121], v[114:115], off offset:256
	s_nop 0
	global_load_dwordx2 v[114:115], v[114:115], off offset:288
	s_nop 0
	global_load_dwordx2 v[122:123], v[100:101], off
	global_load_dwordx2 v[124:125], v[100:101], off offset:32
	global_load_dwordx2 v[126:127], v[100:101], off offset:256
	s_nop 0
	global_load_dwordx2 v[100:101], v[100:101], off offset:288
	v_lshl_add_u64 v[112:113], s[40:41], 0, v[112:113]
	global_load_dwordx2 v[128:129], v[112:113], off
	global_load_dwordx2 v[152:153], v[112:113], off offset:32
	global_load_dwordx2 v[158:159], v[112:113], off offset:256
	v_lshlrev_b64 v[98:99], 11, v[98:99]
	global_load_dwordx2 v[112:113], v[112:113], off offset:288
	v_lshl_add_u64 v[98:99], s[94:95], 0, v[98:99]
	v_lshl_add_u64 v[98:99], v[98:99], 0, v[138:139]
	s_waitcnt vmcnt(0)
	v_lshlrev_b32_e32 v148, 16, v104
	v_and_b32_e32 v149, 0xffff0000, v104
	v_lshlrev_b32_e32 v168, 16, v122
	v_and_b32_e32 v169, 0xffff0000, v122
	v_lshlrev_b32_e32 v104, 16, v105
	v_and_b32_e32 v105, 0xffff0000, v105
	v_lshlrev_b32_e32 v122, 16, v123
	v_and_b32_e32 v123, 0xffff0000, v123
	v_pk_fma_f32 v[94:95], v[94:95], v[168:169], v[148:149]
	v_pk_fma_f32 v[96:97], v[96:97], v[122:123], v[104:105]
	v_cvt_pk_bf16_f32 v94, v94, v95
	v_lshlrev_b32_e32 v150, 16, v106
	v_cvt_pk_bf16_f32 v95, v96, v97
	v_and_b32_e32 v151, 0xffff0000, v106
	global_store_dwordx2 v[98:99], v[94:95], off
	v_lshlrev_b32_e32 v94, 16, v124
	v_and_b32_e32 v95, 0xffff0000, v124
	v_lshlrev_b32_e32 v106, 16, v107
	v_and_b32_e32 v107, 0xffff0000, v107
	v_lshlrev_b32_e32 v96, 16, v125
	v_and_b32_e32 v97, 0xffff0000, v125
	v_pk_fma_f32 v[90:91], v[90:91], v[94:95], v[150:151]
	v_pk_fma_f32 v[92:93], v[92:93], v[96:97], v[106:107]
	v_cvt_pk_bf16_f32 v90, v90, v91
	v_lshlrev_b32_e32 v154, 16, v108
	v_cvt_pk_bf16_f32 v91, v92, v93
	v_and_b32_e32 v155, 0xffff0000, v108
	global_store_dwordx2 v[98:99], v[90:91], off offset:32
	v_lshlrev_b32_e32 v90, 16, v126
	v_and_b32_e32 v91, 0xffff0000, v126
	v_lshlrev_b32_e32 v108, 16, v109
	v_and_b32_e32 v109, 0xffff0000, v109
	v_lshlrev_b32_e32 v92, 16, v127
	v_and_b32_e32 v93, 0xffff0000, v127
	v_pk_fma_f32 v[86:87], v[86:87], v[90:91], v[154:155]
	v_pk_fma_f32 v[88:89], v[88:89], v[92:93], v[108:109]
	v_cvt_pk_bf16_f32 v86, v86, v87
	v_lshlrev_b32_e32 v156, 16, v102
	v_cvt_pk_bf16_f32 v87, v88, v89
	v_and_b32_e32 v157, 0xffff0000, v102
	global_store_dwordx2 v[98:99], v[86:87], off offset:256
	v_lshlrev_b32_e32 v86, 16, v100
	v_and_b32_e32 v87, 0xffff0000, v100
	v_lshlrev_b32_e32 v102, 16, v103
	v_and_b32_e32 v103, 0xffff0000, v103
	v_lshlrev_b32_e32 v88, 16, v101
	v_and_b32_e32 v89, 0xffff0000, v101
	v_pk_fma_f32 v[82:83], v[82:83], v[86:87], v[156:157]
	v_pk_fma_f32 v[84:85], v[84:85], v[88:89], v[102:103]
	v_cvt_pk_bf16_f32 v82, v82, v83
	v_lshlrev_b32_e32 v160, 16, v116
	v_cvt_pk_bf16_f32 v83, v84, v85
	v_and_b32_e32 v161, 0xffff0000, v116
	global_store_dwordx2 v[98:99], v[82:83], off offset:288
	v_lshlrev_b64 v[82:83], 11, v[110:111]
	v_lshlrev_b32_e32 v84, 16, v128
	v_and_b32_e32 v85, 0xffff0000, v128
	v_lshlrev_b32_e32 v116, 16, v117
	v_and_b32_e32 v117, 0xffff0000, v117
	v_lshlrev_b32_e32 v86, 16, v129
	v_and_b32_e32 v87, 0xffff0000, v129
	v_lshl_add_u64 v[82:83], s[94:95], 0, v[82:83]
	v_pk_fma_f32 v[78:79], v[78:79], v[84:85], v[160:161]
	v_lshl_add_u64 v[82:83], v[82:83], 0, v[138:139]
	v_pk_fma_f32 v[80:81], v[80:81], v[86:87], v[116:117]
	v_cvt_pk_bf16_f32 v78, v78, v79
	v_lshlrev_b32_e32 v162, 16, v118
	v_cvt_pk_bf16_f32 v79, v80, v81
	v_and_b32_e32 v163, 0xffff0000, v118
	global_store_dwordx2 v[82:83], v[78:79], off
	v_lshlrev_b32_e32 v78, 16, v152
	v_and_b32_e32 v79, 0xffff0000, v152
	v_lshlrev_b32_e32 v118, 16, v119
	v_and_b32_e32 v119, 0xffff0000, v119
	v_lshlrev_b32_e32 v80, 16, v153
	v_and_b32_e32 v81, 0xffff0000, v153
	v_pk_fma_f32 v[74:75], v[74:75], v[78:79], v[162:163]
	v_pk_fma_f32 v[76:77], v[76:77], v[80:81], v[118:119]
	v_cvt_pk_bf16_f32 v74, v74, v75
	v_lshlrev_b32_e32 v164, 16, v120
	v_cvt_pk_bf16_f32 v75, v76, v77
	v_and_b32_e32 v165, 0xffff0000, v120
	global_store_dwordx2 v[82:83], v[74:75], off offset:32
	v_lshlrev_b32_e32 v74, 16, v158
	v_and_b32_e32 v75, 0xffff0000, v158
	v_lshlrev_b32_e32 v120, 16, v121
	v_and_b32_e32 v121, 0xffff0000, v121
	v_lshlrev_b32_e32 v76, 16, v159
	v_and_b32_e32 v77, 0xffff0000, v159
	v_pk_fma_f32 v[70:71], v[70:71], v[74:75], v[164:165]
	v_pk_fma_f32 v[72:73], v[72:73], v[76:77], v[120:121]
	v_cvt_pk_bf16_f32 v70, v70, v71
	v_lshlrev_b32_e32 v166, 16, v114
	v_cvt_pk_bf16_f32 v71, v72, v73
	v_and_b32_e32 v167, 0xffff0000, v114
	global_store_dwordx2 v[82:83], v[70:71], off offset:256
	v_lshlrev_b32_e32 v70, 16, v112
	v_and_b32_e32 v71, 0xffff0000, v112
	v_pk_fma_f32 v[66:67], v[66:67], v[70:71], v[166:167]
	v_lshlrev_b32_e32 v114, 16, v115
	v_and_b32_e32 v115, 0xffff0000, v115
	v_lshlrev_b32_e32 v72, 16, v113
	v_and_b32_e32 v73, 0xffff0000, v113
	v_cvt_pk_bf16_f32 v66, v66, v67
	v_pk_fma_f32 v[68:69], v[68:69], v[72:73], v[114:115]
	v_add_u32_e32 v78, 0x90, v142
	v_cvt_pk_bf16_f32 v67, v68, v69
	global_store_dwordx2 v[82:83], v[66:67], off offset:288
	v_add_u32_e32 v66, 0x80, v142
	v_ashrrev_i32_e32 v67, 31, v66
	v_ashrrev_i32_e32 v79, 31, v78
	v_lshlrev_b64 v[68:69], 10, v[66:67]
	v_lshlrev_b64 v[80:81], 10, v[78:79]
	v_lshl_add_u64 v[68:69], v[68:69], 0, v[140:141]
	v_lshl_add_u64 v[80:81], v[80:81], 0, v[140:141]
	v_lshlrev_b64 v[68:69], 1, v[68:69]
	v_lshlrev_b64 v[80:81], 1, v[80:81]
	v_lshl_add_u64 v[70:71], s[92:93], 0, v[68:69]
	v_lshl_add_u64 v[82:83], s[92:93], 0, v[80:81]
	v_lshl_add_u64 v[68:69], s[40:41], 0, v[68:69]
	global_load_dwordx2 v[72:73], v[70:71], off
	global_load_dwordx2 v[74:75], v[70:71], off offset:32
	global_load_dwordx2 v[76:77], v[70:71], off offset:256
	s_nop 0
	global_load_dwordx2 v[70:71], v[70:71], off offset:288
	s_nop 0
	global_load_dwordx2 v[84:85], v[82:83], off
	global_load_dwordx2 v[86:87], v[82:83], off offset:32
	global_load_dwordx2 v[88:89], v[82:83], off offset:256
	s_nop 0
	global_load_dwordx2 v[82:83], v[82:83], off offset:288
	s_nop 0
	global_load_dwordx2 v[90:91], v[68:69], off
	global_load_dwordx2 v[92:93], v[68:69], off offset:32
	global_load_dwordx2 v[94:95], v[68:69], off offset:256
	s_nop 0
	global_load_dwordx2 v[68:69], v[68:69], off offset:288
	v_lshl_add_u64 v[80:81], s[40:41], 0, v[80:81]
	global_load_dwordx2 v[96:97], v[80:81], off
	global_load_dwordx2 v[102:103], v[80:81], off offset:32
	global_load_dwordx2 v[108:109], v[80:81], off offset:256
	v_lshlrev_b64 v[66:67], 11, v[66:67]
	global_load_dwordx2 v[80:81], v[80:81], off offset:288
	v_lshl_add_u64 v[66:67], s[94:95], 0, v[66:67]
	v_lshl_add_u64 v[66:67], v[66:67], 0, v[138:139]
	s_waitcnt vmcnt(0)
	v_lshlrev_b32_e32 v98, 16, v72
	v_and_b32_e32 v99, 0xffff0000, v72
	v_lshlrev_b32_e32 v118, 16, v90
	v_and_b32_e32 v119, 0xffff0000, v90
	v_lshlrev_b32_e32 v72, 16, v73
	v_and_b32_e32 v73, 0xffff0000, v73
	v_lshlrev_b32_e32 v90, 16, v91
	v_and_b32_e32 v91, 0xffff0000, v91
	v_pk_fma_f32 v[62:63], v[62:63], v[118:119], v[98:99]
	v_pk_fma_f32 v[64:65], v[64:65], v[90:91], v[72:73]
	v_cvt_pk_bf16_f32 v62, v62, v63
	v_lshlrev_b32_e32 v100, 16, v74
	v_cvt_pk_bf16_f32 v63, v64, v65
	v_and_b32_e32 v101, 0xffff0000, v74
	global_store_dwordx2 v[66:67], v[62:63], off
	v_lshlrev_b32_e32 v62, 16, v92
	v_and_b32_e32 v63, 0xffff0000, v92
	v_lshlrev_b32_e32 v74, 16, v75
	v_and_b32_e32 v75, 0xffff0000, v75
	v_lshlrev_b32_e32 v64, 16, v93
	v_and_b32_e32 v65, 0xffff0000, v93
	v_pk_fma_f32 v[58:59], v[58:59], v[62:63], v[100:101]
	v_pk_fma_f32 v[60:61], v[60:61], v[64:65], v[74:75]
	v_cvt_pk_bf16_f32 v58, v58, v59
	v_lshlrev_b32_e32 v104, 16, v76
	v_cvt_pk_bf16_f32 v59, v60, v61
	v_and_b32_e32 v105, 0xffff0000, v76
	global_store_dwordx2 v[66:67], v[58:59], off offset:32
	v_lshlrev_b32_e32 v58, 16, v94
	v_and_b32_e32 v59, 0xffff0000, v94
	v_lshlrev_b32_e32 v76, 16, v77
	v_and_b32_e32 v77, 0xffff0000, v77
	v_lshlrev_b32_e32 v60, 16, v95
	v_and_b32_e32 v61, 0xffff0000, v95
	v_pk_fma_f32 v[54:55], v[54:55], v[58:59], v[104:105]
	v_pk_fma_f32 v[56:57], v[56:57], v[60:61], v[76:77]
	v_cvt_pk_bf16_f32 v54, v54, v55
	v_lshlrev_b32_e32 v106, 16, v70
	v_cvt_pk_bf16_f32 v55, v56, v57
	v_and_b32_e32 v107, 0xffff0000, v70
	global_store_dwordx2 v[66:67], v[54:55], off offset:256
	v_lshlrev_b32_e32 v54, 16, v68
	v_and_b32_e32 v55, 0xffff0000, v68
	v_lshlrev_b32_e32 v70, 16, v71
	v_and_b32_e32 v71, 0xffff0000, v71
	v_lshlrev_b32_e32 v56, 16, v69
	v_and_b32_e32 v57, 0xffff0000, v69
	v_pk_fma_f32 v[46:47], v[46:47], v[54:55], v[106:107]
	v_pk_fma_f32 v[48:49], v[48:49], v[56:57], v[70:71]
	v_cvt_pk_bf16_f32 v46, v46, v47
	v_lshlrev_b32_e32 v110, 16, v84
	v_cvt_pk_bf16_f32 v47, v48, v49
	v_and_b32_e32 v111, 0xffff0000, v84
	global_store_dwordx2 v[66:67], v[46:47], off offset:288
	v_lshlrev_b64 v[46:47], 11, v[78:79]
	v_lshlrev_b32_e32 v48, 16, v96
	v_and_b32_e32 v49, 0xffff0000, v96
	v_lshlrev_b32_e32 v84, 16, v85
	v_and_b32_e32 v85, 0xffff0000, v85
	v_lshlrev_b32_e32 v54, 16, v97
	v_and_b32_e32 v55, 0xffff0000, v97
	v_lshl_add_u64 v[46:47], s[94:95], 0, v[46:47]
	v_pk_fma_f32 v[48:49], v[50:51], v[48:49], v[110:111]
	v_lshl_add_u64 v[46:47], v[46:47], 0, v[138:139]
	v_pk_fma_f32 v[52:53], v[52:53], v[54:55], v[84:85]
	v_cvt_pk_bf16_f32 v48, v48, v49
	v_lshlrev_b32_e32 v112, 16, v86
	v_cvt_pk_bf16_f32 v49, v52, v53
	v_and_b32_e32 v113, 0xffff0000, v86
	global_store_dwordx2 v[46:47], v[48:49], off
	v_lshlrev_b32_e32 v48, 16, v102
	v_and_b32_e32 v49, 0xffff0000, v102
	v_lshlrev_b32_e32 v86, 16, v87
	v_and_b32_e32 v87, 0xffff0000, v87
	v_lshlrev_b32_e32 v50, 16, v103
	v_and_b32_e32 v51, 0xffff0000, v103
	v_pk_fma_f32 v[42:43], v[42:43], v[48:49], v[112:113]
	v_pk_fma_f32 v[44:45], v[44:45], v[50:51], v[86:87]
	v_cvt_pk_bf16_f32 v42, v42, v43
	v_lshlrev_b32_e32 v114, 16, v88
	v_cvt_pk_bf16_f32 v43, v44, v45
	v_and_b32_e32 v115, 0xffff0000, v88
	global_store_dwordx2 v[46:47], v[42:43], off offset:32
	v_lshlrev_b32_e32 v42, 16, v108
	v_and_b32_e32 v43, 0xffff0000, v108
	v_lshlrev_b32_e32 v88, 16, v89
	v_and_b32_e32 v89, 0xffff0000, v89
	v_lshlrev_b32_e32 v44, 16, v109
	v_and_b32_e32 v45, 0xffff0000, v109
	v_pk_fma_f32 v[38:39], v[38:39], v[42:43], v[114:115]
	v_pk_fma_f32 v[40:41], v[40:41], v[44:45], v[88:89]
	v_cvt_pk_bf16_f32 v38, v38, v39
	v_lshlrev_b32_e32 v116, 16, v82
	v_cvt_pk_bf16_f32 v39, v40, v41
	v_and_b32_e32 v117, 0xffff0000, v82
	global_store_dwordx2 v[46:47], v[38:39], off offset:256
	v_lshlrev_b32_e32 v38, 16, v80
	v_and_b32_e32 v39, 0xffff0000, v80
	v_pk_fma_f32 v[34:35], v[34:35], v[38:39], v[116:117]
	v_lshlrev_b32_e32 v82, 16, v83
	v_and_b32_e32 v83, 0xffff0000, v83
	v_lshlrev_b32_e32 v40, 16, v81
	v_and_b32_e32 v41, 0xffff0000, v81
	v_cvt_pk_bf16_f32 v34, v34, v35
	v_pk_fma_f32 v[36:37], v[36:37], v[40:41], v[82:83]
	s_nop 0
	v_cvt_pk_bf16_f32 v35, v36, v37
	global_store_dwordx2 v[46:47], v[34:35], off offset:288
	v_add_u32_e32 v34, 0xa0, v142
	v_add_u32_e32 v46, 0xb0, v142
	v_ashrrev_i32_e32 v35, 31, v34
	v_ashrrev_i32_e32 v47, 31, v46
	v_lshlrev_b64 v[36:37], 10, v[34:35]
	v_lshlrev_b64 v[48:49], 10, v[46:47]
	v_lshl_add_u64 v[36:37], v[36:37], 0, v[140:141]
	v_lshl_add_u64 v[48:49], v[48:49], 0, v[140:141]
	v_lshlrev_b64 v[36:37], 1, v[36:37]
	v_lshlrev_b64 v[48:49], 1, v[48:49]
	v_lshl_add_u64 v[38:39], s[92:93], 0, v[36:37]
	v_lshl_add_u64 v[50:51], s[92:93], 0, v[48:49]
	v_lshl_add_u64 v[36:37], s[40:41], 0, v[36:37]
	global_load_dwordx2 v[40:41], v[38:39], off
	global_load_dwordx2 v[42:43], v[38:39], off offset:32
	global_load_dwordx2 v[44:45], v[38:39], off offset:256
	s_nop 0
	global_load_dwordx2 v[38:39], v[38:39], off offset:288
	s_nop 0
	global_load_dwordx2 v[52:53], v[50:51], off
	global_load_dwordx2 v[54:55], v[50:51], off offset:32
	global_load_dwordx2 v[56:57], v[50:51], off offset:256
	s_nop 0
	global_load_dwordx2 v[50:51], v[50:51], off offset:288
	s_nop 0
	global_load_dwordx2 v[58:59], v[36:37], off
	global_load_dwordx2 v[60:61], v[36:37], off offset:32
	global_load_dwordx2 v[62:63], v[36:37], off offset:256
	s_nop 0
	global_load_dwordx2 v[36:37], v[36:37], off offset:288
	v_lshl_add_u64 v[48:49], s[40:41], 0, v[48:49]
	global_load_dwordx2 v[64:65], v[48:49], off
	global_load_dwordx2 v[70:71], v[48:49], off offset:32
	global_load_dwordx2 v[76:77], v[48:49], off offset:256
	v_lshlrev_b64 v[34:35], 11, v[34:35]
	global_load_dwordx2 v[48:49], v[48:49], off offset:288
	v_lshl_add_u64 v[34:35], s[94:95], 0, v[34:35]
	v_lshl_add_u64 v[34:35], v[34:35], 0, v[138:139]
	s_waitcnt vmcnt(0)
	v_lshlrev_b32_e32 v66, 16, v40
	v_and_b32_e32 v67, 0xffff0000, v40
	v_lshlrev_b32_e32 v86, 16, v58
	v_and_b32_e32 v87, 0xffff0000, v58
	v_lshlrev_b32_e32 v40, 16, v41
	v_and_b32_e32 v41, 0xffff0000, v41
	v_lshlrev_b32_e32 v58, 16, v59
	v_and_b32_e32 v59, 0xffff0000, v59
	v_pk_fma_f32 v[30:31], v[30:31], v[86:87], v[66:67]
	v_pk_fma_f32 v[32:33], v[32:33], v[58:59], v[40:41]
	v_cvt_pk_bf16_f32 v30, v30, v31
	v_lshlrev_b32_e32 v68, 16, v42
	v_cvt_pk_bf16_f32 v31, v32, v33
	v_and_b32_e32 v69, 0xffff0000, v42
	global_store_dwordx2 v[34:35], v[30:31], off
	v_lshlrev_b32_e32 v30, 16, v60
	v_and_b32_e32 v31, 0xffff0000, v60
	v_lshlrev_b32_e32 v42, 16, v43
	v_and_b32_e32 v43, 0xffff0000, v43
	v_lshlrev_b32_e32 v32, 16, v61
	v_and_b32_e32 v33, 0xffff0000, v61
	v_pk_fma_f32 v[26:27], v[26:27], v[30:31], v[68:69]
	v_pk_fma_f32 v[28:29], v[28:29], v[32:33], v[42:43]
	v_cvt_pk_bf16_f32 v26, v26, v27
	v_lshlrev_b32_e32 v72, 16, v44
	v_cvt_pk_bf16_f32 v27, v28, v29
	v_and_b32_e32 v73, 0xffff0000, v44
	global_store_dwordx2 v[34:35], v[26:27], off offset:32
	v_lshlrev_b32_e32 v26, 16, v62
	v_and_b32_e32 v27, 0xffff0000, v62
	v_lshlrev_b32_e32 v44, 16, v45
	v_and_b32_e32 v45, 0xffff0000, v45
	v_lshlrev_b32_e32 v28, 16, v63
	v_and_b32_e32 v29, 0xffff0000, v63
	v_pk_fma_f32 v[22:23], v[22:23], v[26:27], v[72:73]
	v_pk_fma_f32 v[24:25], v[24:25], v[28:29], v[44:45]
	v_cvt_pk_bf16_f32 v22, v22, v23
	v_lshlrev_b32_e32 v74, 16, v38
	v_cvt_pk_bf16_f32 v23, v24, v25
	v_and_b32_e32 v75, 0xffff0000, v38
	global_store_dwordx2 v[34:35], v[22:23], off offset:256
	v_lshlrev_b32_e32 v22, 16, v36
	v_and_b32_e32 v23, 0xffff0000, v36
	v_lshlrev_b32_e32 v38, 16, v39
	v_and_b32_e32 v39, 0xffff0000, v39
	v_lshlrev_b32_e32 v24, 16, v37
	v_and_b32_e32 v25, 0xffff0000, v37
	v_pk_fma_f32 v[14:15], v[14:15], v[22:23], v[74:75]
	v_pk_fma_f32 v[16:17], v[16:17], v[24:25], v[38:39]
	v_cvt_pk_bf16_f32 v14, v14, v15
	v_lshlrev_b32_e32 v78, 16, v52
	v_cvt_pk_bf16_f32 v15, v16, v17
	v_and_b32_e32 v79, 0xffff0000, v52
	global_store_dwordx2 v[34:35], v[14:15], off offset:288
	v_lshlrev_b64 v[14:15], 11, v[46:47]
	v_lshlrev_b32_e32 v16, 16, v64
	v_and_b32_e32 v17, 0xffff0000, v64
	v_lshlrev_b32_e32 v52, 16, v53
	v_and_b32_e32 v53, 0xffff0000, v53
	v_lshlrev_b32_e32 v22, 16, v65
	v_and_b32_e32 v23, 0xffff0000, v65
	v_lshl_add_u64 v[14:15], s[94:95], 0, v[14:15]
	v_pk_fma_f32 v[16:17], v[18:19], v[16:17], v[78:79]
	v_lshl_add_u64 v[14:15], v[14:15], 0, v[138:139]
	v_pk_fma_f32 v[20:21], v[20:21], v[22:23], v[52:53]
	v_cvt_pk_bf16_f32 v16, v16, v17
	v_lshlrev_b32_e32 v80, 16, v54
	v_cvt_pk_bf16_f32 v17, v20, v21
	v_and_b32_e32 v81, 0xffff0000, v54
	global_store_dwordx2 v[14:15], v[16:17], off
	v_lshlrev_b32_e32 v16, 16, v70
	v_and_b32_e32 v17, 0xffff0000, v70
	v_lshlrev_b32_e32 v54, 16, v55
	v_and_b32_e32 v55, 0xffff0000, v55
	v_lshlrev_b32_e32 v18, 16, v71
	v_and_b32_e32 v19, 0xffff0000, v71
	v_pk_fma_f32 v[10:11], v[10:11], v[16:17], v[80:81]
	v_pk_fma_f32 v[12:13], v[12:13], v[18:19], v[54:55]
	v_cvt_pk_bf16_f32 v10, v10, v11
	v_lshlrev_b32_e32 v82, 16, v56
	v_cvt_pk_bf16_f32 v11, v12, v13
	v_and_b32_e32 v83, 0xffff0000, v56
	global_store_dwordx2 v[14:15], v[10:11], off offset:32
	v_lshlrev_b32_e32 v10, 16, v76
	v_and_b32_e32 v11, 0xffff0000, v76
	v_lshlrev_b32_e32 v56, 16, v57
	v_and_b32_e32 v57, 0xffff0000, v57
	v_lshlrev_b32_e32 v12, 16, v77
	v_and_b32_e32 v13, 0xffff0000, v77
	v_pk_fma_f32 v[6:7], v[6:7], v[10:11], v[82:83]
	v_pk_fma_f32 v[8:9], v[8:9], v[12:13], v[56:57]
	v_cvt_pk_bf16_f32 v6, v6, v7
	v_lshlrev_b32_e32 v84, 16, v50
	v_cvt_pk_bf16_f32 v7, v8, v9
	v_and_b32_e32 v85, 0xffff0000, v50
	global_store_dwordx2 v[14:15], v[6:7], off offset:256
	v_lshlrev_b32_e32 v6, 16, v48
	v_and_b32_e32 v7, 0xffff0000, v48
	v_lshlrev_b32_e32 v50, 16, v51
	v_and_b32_e32 v51, 0xffff0000, v51
	v_lshlrev_b32_e32 v8, 16, v49
	v_and_b32_e32 v9, 0xffff0000, v49
	v_pk_fma_f32 v[2:3], v[2:3], v[6:7], v[84:85]
	v_pk_fma_f32 v[4:5], v[4:5], v[8:9], v[50:51]
	v_cvt_pk_bf16_f32 v2, v2, v3
	s_nop 0
	v_cvt_pk_bf16_f32 v3, v4, v5
	global_store_dwordx2 v[14:15], v[2:3], off offset:288
	s_cbranch_vccz .LBB0_3163
	s_waitcnt vmcnt(0)
	s_cmpk_gt_u32 s22, 0xff
	s_cbranch_scc1 .LBB0_3174
	s_barrier

.LBB0_3184:
	v_readlane_b32 s48, v253, 0
	s_ashr_i32 s17, s16, 31
	v_readlane_b32 s54, v253, 6
	v_readlane_b32 s55, v253, 7
	v_readlane_b32 s62, v253, 14
	v_readlane_b32 s63, v253, 15
	s_lshl_b64 s[18:19], s[16:17], 17
	s_mov_b64 s[54:55], s[62:63]
	s_add_u32 s18, s54, s18
	v_cmp_lt_i64_e32 vcc, s[12:13], v[6:7]
	s_addc_u32 s19, s55, s19
	ds_read_b128 v[14:17], v10
	ds_read_b128 v[18:21], v10 offset:1024
	ds_read_b128 v[22:25], v10 offset:2048
	ds_read_b128 v[26:29], v10 offset:3072
	v_readlane_b32 s49, v253, 1
	v_readlane_b32 s50, v253, 2
	v_readlane_b32 s51, v253, 3
	s_and_b64 s[20:21], vcc, exec
	s_cselect_b32 s29, s19, s23
	s_cselect_b32 s28, s18, s22
	s_ashr_i32 s15, s14, 31
	v_readlane_b32 s48, v253, 26
	s_lshl_b64 s[20:21], s[14:15], 17
	v_readlane_b32 s50, v253, 28
	v_readlane_b32 s51, v253, 29
	s_add_u32 s20, s50, s20
	s_addc_u32 s21, s51, s21
	s_and_b64 s[26:27], vcc, exec
	v_readlane_b32 s52, v253, 4
	v_readlane_b32 s53, v253, 5
	v_readlane_b32 s56, v253, 8
	v_readlane_b32 s57, v253, 9
	v_readlane_b32 s58, v253, 10
	v_readlane_b32 s59, v253, 11
	v_readlane_b32 s60, v253, 12
	v_readlane_b32 s61, v253, 13
	v_readlane_b32 s49, v253, 27
	s_cselect_b32 s27, s21, s25
	s_cselect_b32 s26, s20, s24
	s_add_u32 s48, s22, 0x10080
	s_addc_u32 s49, s23, 0
	s_mov_b32 m0, s44
	v_lshl_add_u64 v[62:63], s[48:49], 0, v[2:3]
	ds_read_b128 v[30:33], v11
	ds_read_b128 v[34:37], v11 offset:1024
	ds_read_b128 v[38:41], v11 offset:2048
	ds_read_b128 v[42:45], v11 offset:3072
	ds_read_b128 v[46:49], v11 offset:4096
	ds_read_b128 v[50:53], v11 offset:5120
	ds_read_b128 v[54:57], v11 offset:6144
	ds_read_b128 v[58:61], v11 offset:7168
	global_load_lds_dwordx4 v[62:63], off
	v_lshl_add_u64 v[62:63], s[48:49], 0, v[4:5]
	s_mov_b32 m0, s45
	s_nop 0
	global_load_lds_dwordx4 v[62:63], off
	s_waitcnt lgkmcnt(8)
	s_barrier
	s_waitcnt lgkmcnt(0)
	s_waitcnt lgkmcnt(0)
	v_mfma_f32_16x16x32_bf16 v[62:65], v[14:17], v[30:33], 0
	v_mfma_f32_16x16x32_bf16 v[66:69], v[22:25], v[30:33], 0
	v_mfma_f32_16x16x32_bf16 v[70:73], v[14:17], v[38:41], 0
	v_mfma_f32_16x16x32_bf16 v[74:77], v[22:25], v[38:41], 0
	v_mfma_f32_16x16x32_bf16 v[78:81], v[14:17], v[46:49], 0
	v_mfma_f32_16x16x32_bf16 v[82:85], v[22:25], v[46:49], 0
	v_mfma_f32_16x16x32_bf16 v[86:89], v[14:17], v[54:57], 0
	v_mfma_f32_16x16x32_bf16 v[90:93], v[22:25], v[54:57], 0
	v_mfma_f32_16x16x32_bf16 v[62:65], v[18:21], v[34:37], v[62:65]
	v_mfma_f32_16x16x32_bf16 v[66:69], v[26:29], v[34:37], v[66:69]
	v_mfma_f32_16x16x32_bf16 v[70:73], v[18:21], v[42:45], v[70:73]
	v_mfma_f32_16x16x32_bf16 v[74:77], v[26:29], v[42:45], v[74:77]
	v_mfma_f32_16x16x32_bf16 v[78:81], v[18:21], v[50:53], v[78:81]
	v_mfma_f32_16x16x32_bf16 v[82:85], v[26:29], v[50:53], v[82:85]
	v_mfma_f32_16x16x32_bf16 v[86:89], v[18:21], v[58:61], v[86:89]
	v_mfma_f32_16x16x32_bf16 v[90:93], v[26:29], v[58:61], v[90:93]
	s_barrier
	v_lshl_add_u64 v[208:209], s[24:25], 0, v[2:3]
	s_add_i32 s48, s43, s33
	v_lshl_add_u64 v[110:111], v[208:209], 0, s[6:7]
	s_mov_b32 m0, s48
	v_lshl_add_u64 v[210:211], s[24:25], 0, v[4:5]
	s_add_i32 s15, s48, 0x2000
	ds_read_b128 v[94:97], v12
	ds_read_b128 v[98:101], v12 offset:1024
	ds_read_b128 v[102:105], v12 offset:2048
	ds_read_b128 v[106:109], v12 offset:3072
	global_load_lds_dwordx4 v[110:111], off
	v_lshl_add_u64 v[110:111], v[210:211], 0, s[6:7]
	s_mov_b32 m0, s15
	s_nop 0
	global_load_lds_dwordx4 v[110:111], off
	s_barrier
	s_waitcnt lgkmcnt(0)
	s_waitcnt lgkmcnt(0)
	v_mfma_f32_16x16x32_bf16 v[110:113], v[94:97], v[30:33], 0
	v_mfma_f32_16x16x32_bf16 v[30:33], v[102:105], v[30:33], 0
	v_mfma_f32_16x16x32_bf16 v[110:113], v[98:101], v[34:37], v[110:113]
	v_mfma_f32_16x16x32_bf16 v[30:33], v[106:109], v[34:37], v[30:33]
	v_mfma_f32_16x16x32_bf16 v[34:37], v[94:97], v[38:41], 0
	v_mfma_f32_16x16x32_bf16 v[38:41], v[102:105], v[38:41], 0
	v_mfma_f32_16x16x32_bf16 v[34:37], v[98:101], v[42:45], v[34:37]
	v_mfma_f32_16x16x32_bf16 v[38:41], v[106:109], v[42:45], v[38:41]
	v_mfma_f32_16x16x32_bf16 v[42:45], v[94:97], v[46:49], 0
	v_mfma_f32_16x16x32_bf16 v[46:49], v[102:105], v[46:49], 0
	v_mfma_f32_16x16x32_bf16 v[42:45], v[98:101], v[50:53], v[42:45]
	v_mfma_f32_16x16x32_bf16 v[46:49], v[106:109], v[50:53], v[46:49]
	v_mfma_f32_16x16x32_bf16 v[50:53], v[94:97], v[54:57], 0
	v_mfma_f32_16x16x32_bf16 v[54:57], v[102:105], v[54:57], 0
	v_mfma_f32_16x16x32_bf16 v[50:53], v[98:101], v[58:61], v[50:53]
	v_mfma_f32_16x16x32_bf16 v[54:57], v[106:109], v[58:61], v[54:57]
	v_lshl_add_u64 v[212:213], s[22:23], 0, v[2:3]
	s_mov_b32 m0, s5
	v_lshl_add_u64 v[142:143], v[212:213], 0, s[6:7]
	v_lshl_add_u64 v[214:215], s[22:23], 0, v[4:5]
	s_barrier
	ds_read_b128 v[58:61], v11 offset:16384
	ds_read_b128 v[114:117], v11 offset:17408
	ds_read_b128 v[118:121], v11 offset:18432
	ds_read_b128 v[122:125], v11 offset:19456
	ds_read_b128 v[126:129], v11 offset:20480
	ds_read_b128 v[130:133], v11 offset:21504
	ds_read_b128 v[134:137], v11 offset:22528
	ds_read_b128 v[138:141], v11 offset:23552
	global_load_lds_dwordx4 v[142:143], off
	v_lshl_add_u64 v[142:143], v[214:215], 0, s[6:7]
	s_mov_b32 m0, s34
	s_nop 0
	global_load_lds_dwordx4 v[142:143], off
	s_barrier
	s_waitcnt lgkmcnt(0)
	s_waitcnt lgkmcnt(0)
	v_mfma_f32_16x16x32_bf16 v[142:145], v[14:17], v[58:61], 0
	v_mfma_f32_16x16x32_bf16 v[150:153], v[14:17], v[118:121], 0
	v_mfma_f32_16x16x32_bf16 v[158:161], v[14:17], v[126:129], 0
	v_mfma_f32_16x16x32_bf16 v[14:17], v[14:17], v[134:137], 0
	v_mfma_f32_16x16x32_bf16 v[142:145], v[18:21], v[114:117], v[142:145]
	v_mfma_f32_16x16x32_bf16 v[146:149], v[22:25], v[58:61], 0
	v_mfma_f32_16x16x32_bf16 v[150:153], v[18:21], v[122:125], v[150:153]
	v_mfma_f32_16x16x32_bf16 v[154:157], v[22:25], v[118:121], 0
	v_mfma_f32_16x16x32_bf16 v[158:161], v[18:21], v[130:133], v[158:161]
	v_mfma_f32_16x16x32_bf16 v[162:165], v[22:25], v[126:129], 0
	v_mfma_f32_16x16x32_bf16 v[14:17], v[18:21], v[138:141], v[14:17]
	v_mfma_f32_16x16x32_bf16 v[18:21], v[22:25], v[134:137], 0
	v_mfma_f32_16x16x32_bf16 v[146:149], v[26:29], v[114:117], v[146:149]
	v_mfma_f32_16x16x32_bf16 v[154:157], v[26:29], v[122:125], v[154:157]
	v_mfma_f32_16x16x32_bf16 v[162:165], v[26:29], v[130:133], v[162:165]
	v_mfma_f32_16x16x32_bf16 v[18:21], v[26:29], v[138:141], v[18:21]
	s_barrier
	s_add_u32 s50, s24, 0x10100
	s_addc_u32 s51, s25, 0
	s_add_i32 s49, s46, s33
	v_lshl_add_u64 v[22:23], s[50:51], 0, v[2:3]
	s_mov_b32 m0, s49
	s_add_i32 s17, s49, 0x2000
	global_load_lds_dwordx4 v[22:23], off
	v_lshl_add_u64 v[22:23], s[50:51], 0, v[4:5]
	s_mov_b32 m0, s17
	s_nop 0
	global_load_lds_dwordx4 v[22:23], off
	s_waitcnt vmcnt(6)
	s_barrier
	v_mfma_f32_16x16x32_bf16 v[22:25], v[94:97], v[58:61], 0
	v_mfma_f32_16x16x32_bf16 v[26:29], v[102:105], v[58:61], 0
	v_mfma_f32_16x16x32_bf16 v[22:25], v[98:101], v[114:117], v[22:25]
	v_mfma_f32_16x16x32_bf16 v[26:29], v[106:109], v[114:117], v[26:29]
	v_mfma_f32_16x16x32_bf16 v[58:61], v[94:97], v[118:121], 0
	v_mfma_f32_16x16x32_bf16 v[114:117], v[102:105], v[118:121], 0
	v_mfma_f32_16x16x32_bf16 v[118:121], v[94:97], v[126:129], 0
	v_mfma_f32_16x16x32_bf16 v[94:97], v[94:97], v[134:137], 0
	v_mfma_f32_16x16x32_bf16 v[58:61], v[98:101], v[122:125], v[58:61]
	v_mfma_f32_16x16x32_bf16 v[114:117], v[106:109], v[122:125], v[114:117]
	v_mfma_f32_16x16x32_bf16 v[118:121], v[98:101], v[130:133], v[118:121]
	v_mfma_f32_16x16x32_bf16 v[122:125], v[102:105], v[126:129], 0
	v_mfma_f32_16x16x32_bf16 v[94:97], v[98:101], v[138:141], v[94:97]
	v_mfma_f32_16x16x32_bf16 v[98:101], v[102:105], v[134:137], 0
	v_mfma_f32_16x16x32_bf16 v[122:125], v[106:109], v[130:133], v[122:125]
	v_mfma_f32_16x16x32_bf16 v[98:101], v[106:109], v[138:141], v[98:101]
	s_add_i32 s52, 0, 0x18000
	v_add_u32_e32 v13, s52, v1
	s_barrier
	ds_read_b128 v[102:105], v13
	ds_read_b128 v[106:109], v13 offset:1024
	ds_read_b128 v[126:129], v13 offset:2048
	ds_read_b128 v[130:133], v13 offset:3072
	s_add_u32 s50, s22, 0x10100
	s_addc_u32 s51, s23, 0
	s_mov_b32 m0, s35
	v_lshl_add_u64 v[192:193], s[50:51], 0, v[2:3]
	ds_read_b128 v[134:137], v11 offset:32768
	ds_read_b128 v[138:141], v11 offset:33792
	ds_read_b128 v[166:169], v11 offset:34816
	ds_read_b128 v[170:173], v11 offset:35840
	ds_read_b128 v[174:177], v11 offset:36864
	ds_read_b128 v[178:181], v11 offset:37888
	ds_read_b128 v[184:187], v11 offset:38912
	ds_read_b128 v[188:191], v11 offset:39936
	global_load_lds_dwordx4 v[192:193], off
	v_lshl_add_u64 v[192:193], s[50:51], 0, v[4:5]
	s_mov_b32 m0, s36
	s_nop 0
	global_load_lds_dwordx4 v[192:193], off
	s_waitcnt lgkmcnt(8)
	s_barrier
	s_waitcnt lgkmcnt(0)
	s_waitcnt lgkmcnt(0)
	v_mfma_f32_16x16x32_bf16 v[62:65], v[102:105], v[134:137], v[62:65]
	v_mfma_f32_16x16x32_bf16 v[66:69], v[126:129], v[134:137], v[66:69]
	v_mfma_f32_16x16x32_bf16 v[70:73], v[102:105], v[166:169], v[70:73]
	v_mfma_f32_16x16x32_bf16 v[74:77], v[126:129], v[166:169], v[74:77]
	v_mfma_f32_16x16x32_bf16 v[78:81], v[102:105], v[174:177], v[78:81]
	v_mfma_f32_16x16x32_bf16 v[82:85], v[126:129], v[174:177], v[82:85]
	v_mfma_f32_16x16x32_bf16 v[86:89], v[102:105], v[184:187], v[86:89]
	v_mfma_f32_16x16x32_bf16 v[90:93], v[126:129], v[184:187], v[90:93]
	v_mfma_f32_16x16x32_bf16 v[62:65], v[106:109], v[138:141], v[62:65]
	v_mfma_f32_16x16x32_bf16 v[66:69], v[130:133], v[138:141], v[66:69]
	v_mfma_f32_16x16x32_bf16 v[70:73], v[106:109], v[170:173], v[70:73]
	v_mfma_f32_16x16x32_bf16 v[74:77], v[130:133], v[170:173], v[74:77]
	v_mfma_f32_16x16x32_bf16 v[78:81], v[106:109], v[178:181], v[78:81]
	v_mfma_f32_16x16x32_bf16 v[82:85], v[130:133], v[178:181], v[82:85]
	v_mfma_f32_16x16x32_bf16 v[86:89], v[106:109], v[188:191], v[86:89]
	v_mfma_f32_16x16x32_bf16 v[90:93], v[130:133], v[188:191], v[90:93]
	s_barrier
	s_add_i32 s54, 0, 0x1c000
	s_add_i32 s51, s52, s33
	v_add_u32_e32 v183, s54, v1
	v_lshl_add_u64 v[208:209], v[208:209], 0, s[10:11]
	s_mov_b32 m0, s51
	s_add_i32 s50, s51, 0x2000
	ds_read_b128 v[192:195], v183
	ds_read_b128 v[196:199], v183 offset:1024
	ds_read_b128 v[200:203], v183 offset:2048
	ds_read_b128 v[204:207], v183 offset:3072
	global_load_lds_dwordx4 v[208:209], off
	v_lshl_add_u64 v[208:209], v[210:211], 0, s[10:11]
	s_mov_b32 m0, s50
	s_nop 0
	global_load_lds_dwordx4 v[208:209], off
	s_barrier
	s_waitcnt lgkmcnt(0)
	s_waitcnt lgkmcnt(0)
	v_mfma_f32_16x16x32_bf16 v[110:113], v[192:195], v[134:137], v[110:113]
	v_mfma_f32_16x16x32_bf16 v[30:33], v[200:203], v[134:137], v[30:33]
	v_mfma_f32_16x16x32_bf16 v[34:37], v[192:195], v[166:169], v[34:37]
	v_mfma_f32_16x16x32_bf16 v[38:41], v[200:203], v[166:169], v[38:41]
	v_mfma_f32_16x16x32_bf16 v[42:45], v[192:195], v[174:177], v[42:45]
	v_mfma_f32_16x16x32_bf16 v[46:49], v[200:203], v[174:177], v[46:49]
	v_mfma_f32_16x16x32_bf16 v[50:53], v[192:195], v[184:187], v[50:53]
	v_mfma_f32_16x16x32_bf16 v[54:57], v[200:203], v[184:187], v[54:57]
	v_mfma_f32_16x16x32_bf16 v[110:113], v[196:199], v[138:141], v[110:113]
	v_mfma_f32_16x16x32_bf16 v[30:33], v[204:207], v[138:141], v[30:33]
	v_mfma_f32_16x16x32_bf16 v[34:37], v[196:199], v[170:173], v[34:37]
	v_mfma_f32_16x16x32_bf16 v[38:41], v[204:207], v[170:173], v[38:41]
	v_mfma_f32_16x16x32_bf16 v[42:45], v[196:199], v[178:181], v[42:45]
	v_mfma_f32_16x16x32_bf16 v[46:49], v[204:207], v[178:181], v[46:49]
	v_mfma_f32_16x16x32_bf16 v[50:53], v[196:199], v[188:191], v[50:53]
	v_mfma_f32_16x16x32_bf16 v[54:57], v[204:207], v[188:191], v[54:57]
	s_mov_b32 m0, s39
	v_lshl_add_u64 v[208:209], v[212:213], 0, s[10:11]
	s_barrier
	ds_read_b128 v[134:137], v11 offset:49152
	ds_read_b128 v[138:141], v11 offset:50176
	ds_read_b128 v[166:169], v11 offset:51200
	ds_read_b128 v[170:173], v11 offset:52224
	ds_read_b128 v[174:177], v11 offset:53248
	ds_read_b128 v[178:181], v11 offset:54272
	ds_read_b128 v[184:187], v11 offset:55296
	ds_read_b128 v[188:191], v11 offset:56320
	global_load_lds_dwordx4 v[208:209], off
	v_lshl_add_u64 v[208:209], v[214:215], 0, s[10:11]
	s_mov_b32 m0, s40
	s_nop 0
	global_load_lds_dwordx4 v[208:209], off
	s_barrier
	s_waitcnt lgkmcnt(0)
	s_waitcnt lgkmcnt(0)
	v_mfma_f32_16x16x32_bf16 v[142:145], v[102:105], v[134:137], v[142:145]
	v_mfma_f32_16x16x32_bf16 v[146:149], v[126:129], v[134:137], v[146:149]
	v_mfma_f32_16x16x32_bf16 v[150:153], v[102:105], v[166:169], v[150:153]
	v_mfma_f32_16x16x32_bf16 v[154:157], v[126:129], v[166:169], v[154:157]
	v_mfma_f32_16x16x32_bf16 v[158:161], v[102:105], v[174:177], v[158:161]
	v_mfma_f32_16x16x32_bf16 v[162:165], v[126:129], v[174:177], v[162:165]
	v_mfma_f32_16x16x32_bf16 v[14:17], v[102:105], v[184:187], v[14:17]
	v_mfma_f32_16x16x32_bf16 v[18:21], v[126:129], v[184:187], v[18:21]
	v_mfma_f32_16x16x32_bf16 v[142:145], v[106:109], v[138:141], v[142:145]
	v_mfma_f32_16x16x32_bf16 v[146:149], v[130:133], v[138:141], v[146:149]
	v_mfma_f32_16x16x32_bf16 v[150:153], v[106:109], v[170:173], v[150:153]
	v_mfma_f32_16x16x32_bf16 v[154:157], v[130:133], v[170:173], v[154:157]
	v_mfma_f32_16x16x32_bf16 v[158:161], v[106:109], v[178:181], v[158:161]
	v_mfma_f32_16x16x32_bf16 v[162:165], v[130:133], v[178:181], v[162:165]
	v_mfma_f32_16x16x32_bf16 v[14:17], v[106:109], v[188:191], v[14:17]
	v_mfma_f32_16x16x32_bf16 v[18:21], v[130:133], v[188:191], v[18:21]
	s_barrier
	s_add_u32 s52, s24, 0x10180
	s_addc_u32 s53, s25, 0
	s_add_i32 s25, s54, s33
	v_lshl_add_u64 v[102:103], s[52:53], 0, v[2:3]
	s_mov_b32 m0, s25
	s_add_i32 s24, s25, 0x2000
	global_load_lds_dwordx4 v[102:103], off
	v_lshl_add_u64 v[102:103], s[52:53], 0, v[4:5]
	s_mov_b32 m0, s24
	s_nop 0
	global_load_lds_dwordx4 v[102:103], off
	s_waitcnt vmcnt(6)
	s_barrier
	v_mfma_f32_16x16x32_bf16 v[22:25], v[192:195], v[134:137], v[22:25]
	v_mfma_f32_16x16x32_bf16 v[26:29], v[200:203], v[134:137], v[26:29]
	v_mfma_f32_16x16x32_bf16 v[58:61], v[192:195], v[166:169], v[58:61]
	v_mfma_f32_16x16x32_bf16 v[102:105], v[200:203], v[166:169], v[114:117]
	v_mfma_f32_16x16x32_bf16 v[106:109], v[192:195], v[174:177], v[118:121]
	v_mfma_f32_16x16x32_bf16 v[114:117], v[200:203], v[174:177], v[122:125]
	v_mfma_f32_16x16x32_bf16 v[94:97], v[192:195], v[184:187], v[94:97]
	v_mfma_f32_16x16x32_bf16 v[98:101], v[200:203], v[184:187], v[98:101]
	v_mfma_f32_16x16x32_bf16 v[22:25], v[196:199], v[138:141], v[22:25]
	v_mfma_f32_16x16x32_bf16 v[26:29], v[204:207], v[138:141], v[26:29]
	v_mfma_f32_16x16x32_bf16 v[58:61], v[196:199], v[170:173], v[58:61]
	v_mfma_f32_16x16x32_bf16 v[102:105], v[204:207], v[170:173], v[102:105]
	v_mfma_f32_16x16x32_bf16 v[106:109], v[196:199], v[178:181], v[106:109]
	v_mfma_f32_16x16x32_bf16 v[114:117], v[204:207], v[178:181], v[114:117]
	v_mfma_f32_16x16x32_bf16 v[94:97], v[196:199], v[188:191], v[94:97]
	v_mfma_f32_16x16x32_bf16 v[98:101], v[204:207], v[188:191], v[98:101]
	s_barrier
	ds_read_b128 v[118:121], v10
	ds_read_b128 v[122:125], v10 offset:1024
	ds_read_b128 v[126:129], v10 offset:2048
	ds_read_b128 v[130:133], v10 offset:3072
	s_add_u32 s22, s22, 0x10180
	s_addc_u32 s23, s23, 0
	s_mov_b32 m0, s44
	v_lshl_add_u64 v[192:193], s[22:23], 0, v[2:3]
	ds_read_b128 v[134:137], v11
	ds_read_b128 v[138:141], v11 offset:1024
	ds_read_b128 v[166:169], v11 offset:2048
	ds_read_b128 v[170:173], v11 offset:3072
	ds_read_b128 v[174:177], v11 offset:4096
	ds_read_b128 v[178:181], v11 offset:5120
	ds_read_b128 v[184:187], v11 offset:6144
	ds_read_b128 v[188:191], v11 offset:7168
	global_load_lds_dwordx4 v[192:193], off
	v_lshl_add_u64 v[192:193], s[22:23], 0, v[4:5]
	s_mov_b32 m0, s45
	s_nop 0
	global_load_lds_dwordx4 v[192:193], off
	s_waitcnt lgkmcnt(8)
	s_barrier
	s_waitcnt lgkmcnt(0)
	s_waitcnt lgkmcnt(0)
	v_mfma_f32_16x16x32_bf16 v[62:65], v[118:121], v[134:137], v[62:65]
	v_mfma_f32_16x16x32_bf16 v[66:69], v[126:129], v[134:137], v[66:69]
	v_mfma_f32_16x16x32_bf16 v[70:73], v[118:121], v[166:169], v[70:73]
	v_mfma_f32_16x16x32_bf16 v[74:77], v[126:129], v[166:169], v[74:77]
	v_mfma_f32_16x16x32_bf16 v[78:81], v[118:121], v[174:177], v[78:81]
	v_mfma_f32_16x16x32_bf16 v[82:85], v[126:129], v[174:177], v[82:85]
	v_mfma_f32_16x16x32_bf16 v[86:89], v[118:121], v[184:187], v[86:89]
	v_mfma_f32_16x16x32_bf16 v[90:93], v[126:129], v[184:187], v[90:93]
	v_mfma_f32_16x16x32_bf16 v[62:65], v[122:125], v[138:141], v[62:65]
	v_mfma_f32_16x16x32_bf16 v[66:69], v[130:133], v[138:141], v[66:69]
	v_mfma_f32_16x16x32_bf16 v[70:73], v[122:125], v[170:173], v[70:73]
	v_mfma_f32_16x16x32_bf16 v[74:77], v[130:133], v[170:173], v[74:77]
	v_mfma_f32_16x16x32_bf16 v[78:81], v[122:125], v[178:181], v[78:81]
	v_mfma_f32_16x16x32_bf16 v[82:85], v[130:133], v[178:181], v[82:85]
	v_mfma_f32_16x16x32_bf16 v[86:89], v[122:125], v[188:191], v[86:89]
	v_mfma_f32_16x16x32_bf16 v[90:93], v[130:133], v[188:191], v[90:93]
	s_barrier
	s_mov_b32 m0, s48
	v_lshl_add_u64 v[208:209], s[26:27], 0, v[2:3]
	ds_read_b128 v[192:195], v12
	ds_read_b128 v[196:199], v12 offset:1024
	ds_read_b128 v[200:203], v12 offset:2048
	ds_read_b128 v[204:207], v12 offset:3072
	global_load_lds_dwordx4 v[208:209], off
	v_lshl_add_u64 v[210:211], s[26:27], 0, v[4:5]
	s_mov_b32 m0, s15
	s_nop 0
	global_load_lds_dwordx4 v[210:211], off
	s_barrier
	s_waitcnt lgkmcnt(0)
	s_waitcnt lgkmcnt(0)
	v_mfma_f32_16x16x32_bf16 v[110:113], v[192:195], v[134:137], v[110:113]
	v_mfma_f32_16x16x32_bf16 v[30:33], v[200:203], v[134:137], v[30:33]
	v_mfma_f32_16x16x32_bf16 v[34:37], v[192:195], v[166:169], v[34:37]
	v_mfma_f32_16x16x32_bf16 v[38:41], v[200:203], v[166:169], v[38:41]
	v_mfma_f32_16x16x32_bf16 v[42:45], v[192:195], v[174:177], v[42:45]
	v_mfma_f32_16x16x32_bf16 v[46:49], v[200:203], v[174:177], v[46:49]
	v_mfma_f32_16x16x32_bf16 v[50:53], v[192:195], v[184:187], v[50:53]
	v_mfma_f32_16x16x32_bf16 v[54:57], v[200:203], v[184:187], v[54:57]
	v_mfma_f32_16x16x32_bf16 v[110:113], v[196:199], v[138:141], v[110:113]
	v_mfma_f32_16x16x32_bf16 v[30:33], v[204:207], v[138:141], v[30:33]
	v_mfma_f32_16x16x32_bf16 v[34:37], v[196:199], v[170:173], v[34:37]
	v_mfma_f32_16x16x32_bf16 v[38:41], v[204:207], v[170:173], v[38:41]
	v_mfma_f32_16x16x32_bf16 v[42:45], v[196:199], v[178:181], v[42:45]
	v_mfma_f32_16x16x32_bf16 v[46:49], v[204:207], v[178:181], v[46:49]
	v_mfma_f32_16x16x32_bf16 v[50:53], v[196:199], v[188:191], v[50:53]
	v_mfma_f32_16x16x32_bf16 v[54:57], v[204:207], v[188:191], v[54:57]
	s_mov_b32 m0, s5
	v_lshl_add_u64 v[212:213], s[28:29], 0, v[2:3]
	s_barrier
	ds_read_b128 v[134:137], v11 offset:16384
	ds_read_b128 v[138:141], v11 offset:17408
	ds_read_b128 v[166:169], v11 offset:18432
	ds_read_b128 v[170:173], v11 offset:19456
	ds_read_b128 v[174:177], v11 offset:20480
	ds_read_b128 v[178:181], v11 offset:21504
	ds_read_b128 v[184:187], v11 offset:22528
	ds_read_b128 v[188:191], v11 offset:23552
	global_load_lds_dwordx4 v[212:213], off
	v_lshl_add_u64 v[214:215], s[28:29], 0, v[4:5]
	s_mov_b32 m0, s34
	s_nop 0
	global_load_lds_dwordx4 v[214:215], off
	s_barrier
	s_waitcnt lgkmcnt(0)
	s_waitcnt lgkmcnt(0)
	v_mfma_f32_16x16x32_bf16 v[142:145], v[118:121], v[134:137], v[142:145]
	v_mfma_f32_16x16x32_bf16 v[146:149], v[126:129], v[134:137], v[146:149]
	v_mfma_f32_16x16x32_bf16 v[150:153], v[118:121], v[166:169], v[150:153]
	v_mfma_f32_16x16x32_bf16 v[154:157], v[126:129], v[166:169], v[154:157]
	v_mfma_f32_16x16x32_bf16 v[158:161], v[118:121], v[174:177], v[158:161]
	v_mfma_f32_16x16x32_bf16 v[162:165], v[126:129], v[174:177], v[162:165]
	v_mfma_f32_16x16x32_bf16 v[14:17], v[118:121], v[184:187], v[14:17]
	v_mfma_f32_16x16x32_bf16 v[18:21], v[126:129], v[184:187], v[18:21]
	v_mfma_f32_16x16x32_bf16 v[142:145], v[122:125], v[138:141], v[142:145]
	v_mfma_f32_16x16x32_bf16 v[146:149], v[130:133], v[138:141], v[146:149]
	v_mfma_f32_16x16x32_bf16 v[150:153], v[122:125], v[170:173], v[150:153]
	v_mfma_f32_16x16x32_bf16 v[154:157], v[130:133], v[170:173], v[154:157]
	v_mfma_f32_16x16x32_bf16 v[158:161], v[122:125], v[178:181], v[158:161]
	v_mfma_f32_16x16x32_bf16 v[162:165], v[130:133], v[178:181], v[162:165]
	v_mfma_f32_16x16x32_bf16 v[14:17], v[122:125], v[188:191], v[14:17]
	v_mfma_f32_16x16x32_bf16 v[18:21], v[130:133], v[188:191], v[18:21]
	s_barrier
	s_add_u32 s22, s26, 0x10000
	s_addc_u32 s23, s27, 0
	s_mov_b32 m0, s49
	v_lshl_add_u64 v[118:119], s[22:23], 0, v[2:3]
	global_load_lds_dwordx4 v[118:119], off
	v_lshl_add_u64 v[118:119], s[22:23], 0, v[4:5]
	s_mov_b32 m0, s17
	s_nop 0
	global_load_lds_dwordx4 v[118:119], off
	s_waitcnt vmcnt(6)
	s_barrier
	v_mfma_f32_16x16x32_bf16 v[22:25], v[192:195], v[134:137], v[22:25]
	v_mfma_f32_16x16x32_bf16 v[26:29], v[200:203], v[134:137], v[26:29]
	v_mfma_f32_16x16x32_bf16 v[58:61], v[192:195], v[166:169], v[58:61]
	v_mfma_f32_16x16x32_bf16 v[102:105], v[200:203], v[166:169], v[102:105]
	v_mfma_f32_16x16x32_bf16 v[106:109], v[192:195], v[174:177], v[106:109]
	v_mfma_f32_16x16x32_bf16 v[114:117], v[200:203], v[174:177], v[114:117]
	v_mfma_f32_16x16x32_bf16 v[94:97], v[192:195], v[184:187], v[94:97]
	v_mfma_f32_16x16x32_bf16 v[98:101], v[200:203], v[184:187], v[98:101]
	v_mfma_f32_16x16x32_bf16 v[22:25], v[196:199], v[138:141], v[22:25]
	v_mfma_f32_16x16x32_bf16 v[26:29], v[204:207], v[138:141], v[26:29]
	v_mfma_f32_16x16x32_bf16 v[58:61], v[196:199], v[170:173], v[58:61]
	v_mfma_f32_16x16x32_bf16 v[102:105], v[204:207], v[170:173], v[102:105]
	v_mfma_f32_16x16x32_bf16 v[106:109], v[196:199], v[178:181], v[106:109]
	v_mfma_f32_16x16x32_bf16 v[114:117], v[204:207], v[178:181], v[114:117]
	v_mfma_f32_16x16x32_bf16 v[94:97], v[196:199], v[188:191], v[94:97]
	v_mfma_f32_16x16x32_bf16 v[98:101], v[204:207], v[188:191], v[98:101]
	s_barrier
	ds_read_b128 v[118:121], v13
	ds_read_b128 v[122:125], v13 offset:1024
	ds_read_b128 v[126:129], v13 offset:2048
	ds_read_b128 v[130:133], v13 offset:3072
	s_add_u32 s22, s28, 0x10000
	s_addc_u32 s23, s29, 0
	s_mov_b32 m0, s35
	v_lshl_add_u64 v[192:193], s[22:23], 0, v[2:3]
	ds_read_b128 v[134:137], v11 offset:32768
	ds_read_b128 v[138:141], v11 offset:33792
	ds_read_b128 v[166:169], v11 offset:34816
	ds_read_b128 v[170:173], v11 offset:35840
	ds_read_b128 v[174:177], v11 offset:36864
	ds_read_b128 v[178:181], v11 offset:37888
	ds_read_b128 v[184:187], v11 offset:38912
	ds_read_b128 v[188:191], v11 offset:39936
	global_load_lds_dwordx4 v[192:193], off
	v_lshl_add_u64 v[192:193], s[22:23], 0, v[4:5]
	s_mov_b32 m0, s36
	s_nop 0
	global_load_lds_dwordx4 v[192:193], off
	s_waitcnt lgkmcnt(8)
	s_barrier
	s_waitcnt lgkmcnt(0)
	s_waitcnt lgkmcnt(0)
	v_mfma_f32_16x16x32_bf16 v[62:65], v[118:121], v[134:137], v[62:65]
	v_mfma_f32_16x16x32_bf16 v[66:69], v[126:129], v[134:137], v[66:69]
	v_mfma_f32_16x16x32_bf16 v[70:73], v[118:121], v[166:169], v[70:73]
	v_mfma_f32_16x16x32_bf16 v[74:77], v[126:129], v[166:169], v[74:77]
	v_mfma_f32_16x16x32_bf16 v[78:81], v[118:121], v[174:177], v[78:81]
	v_mfma_f32_16x16x32_bf16 v[82:85], v[126:129], v[174:177], v[82:85]
	v_mfma_f32_16x16x32_bf16 v[86:89], v[118:121], v[184:187], v[86:89]
	v_mfma_f32_16x16x32_bf16 v[90:93], v[126:129], v[184:187], v[90:93]
	v_mfma_f32_16x16x32_bf16 v[62:65], v[122:125], v[138:141], v[62:65]
	v_mfma_f32_16x16x32_bf16 v[66:69], v[130:133], v[138:141], v[66:69]
	v_mfma_f32_16x16x32_bf16 v[70:73], v[122:125], v[170:173], v[70:73]
	v_mfma_f32_16x16x32_bf16 v[74:77], v[130:133], v[170:173], v[74:77]
	v_mfma_f32_16x16x32_bf16 v[78:81], v[122:125], v[178:181], v[78:81]
	v_mfma_f32_16x16x32_bf16 v[82:85], v[130:133], v[178:181], v[82:85]
	v_mfma_f32_16x16x32_bf16 v[86:89], v[122:125], v[188:191], v[86:89]
	v_mfma_f32_16x16x32_bf16 v[90:93], v[130:133], v[188:191], v[90:93]
	s_barrier
	s_mov_b32 m0, s51
	v_lshl_add_u64 v[208:209], v[208:209], 0, s[2:3]
	ds_read_b128 v[192:195], v183
	ds_read_b128 v[196:199], v183 offset:1024
	ds_read_b128 v[200:203], v183 offset:2048
	ds_read_b128 v[204:207], v183 offset:3072
	global_load_lds_dwordx4 v[208:209], off
	v_lshl_add_u64 v[208:209], v[210:211], 0, s[2:3]
	s_mov_b32 m0, s50
	s_nop 0
	global_load_lds_dwordx4 v[208:209], off
	s_barrier
	s_waitcnt lgkmcnt(0)
	s_waitcnt lgkmcnt(0)
	v_mfma_f32_16x16x32_bf16 v[110:113], v[192:195], v[134:137], v[110:113]
	v_mfma_f32_16x16x32_bf16 v[30:33], v[200:203], v[134:137], v[30:33]
	v_mfma_f32_16x16x32_bf16 v[34:37], v[192:195], v[166:169], v[34:37]
	v_mfma_f32_16x16x32_bf16 v[38:41], v[200:203], v[166:169], v[38:41]
	v_mfma_f32_16x16x32_bf16 v[42:45], v[192:195], v[174:177], v[42:45]
	v_mfma_f32_16x16x32_bf16 v[46:49], v[200:203], v[174:177], v[46:49]
	v_mfma_f32_16x16x32_bf16 v[50:53], v[192:195], v[184:187], v[50:53]
	v_mfma_f32_16x16x32_bf16 v[54:57], v[200:203], v[184:187], v[54:57]
	v_mfma_f32_16x16x32_bf16 v[110:113], v[196:199], v[138:141], v[110:113]
	v_mfma_f32_16x16x32_bf16 v[30:33], v[204:207], v[138:141], v[30:33]
	v_mfma_f32_16x16x32_bf16 v[34:37], v[196:199], v[170:173], v[34:37]
	v_mfma_f32_16x16x32_bf16 v[38:41], v[204:207], v[170:173], v[38:41]
	v_mfma_f32_16x16x32_bf16 v[42:45], v[196:199], v[178:181], v[42:45]
	v_mfma_f32_16x16x32_bf16 v[46:49], v[204:207], v[178:181], v[46:49]
	v_mfma_f32_16x16x32_bf16 v[50:53], v[196:199], v[188:191], v[50:53]
	v_mfma_f32_16x16x32_bf16 v[54:57], v[204:207], v[188:191], v[54:57]
	s_mov_b32 m0, s39
	v_lshl_add_u64 v[208:209], v[212:213], 0, s[2:3]
	s_barrier
	ds_read_b128 v[134:137], v11 offset:49152
	ds_read_b128 v[138:141], v11 offset:50176
	ds_read_b128 v[166:169], v11 offset:51200
	ds_read_b128 v[170:173], v11 offset:52224
	ds_read_b128 v[174:177], v11 offset:53248
	ds_read_b128 v[178:181], v11 offset:54272
	ds_read_b128 v[184:187], v11 offset:55296
	ds_read_b128 v[188:191], v11 offset:56320
	global_load_lds_dwordx4 v[208:209], off
	v_lshl_add_u64 v[208:209], v[214:215], 0, s[2:3]
	s_mov_b32 m0, s40
	s_nop 0
	global_load_lds_dwordx4 v[208:209], off
	s_barrier
	s_waitcnt lgkmcnt(0)
	s_waitcnt lgkmcnt(0)
	v_mfma_f32_16x16x32_bf16 v[142:145], v[118:121], v[134:137], v[142:145]
	v_mfma_f32_16x16x32_bf16 v[146:149], v[126:129], v[134:137], v[146:149]
	v_mfma_f32_16x16x32_bf16 v[150:153], v[118:121], v[166:169], v[150:153]
	v_mfma_f32_16x16x32_bf16 v[154:157], v[126:129], v[166:169], v[154:157]
	v_mfma_f32_16x16x32_bf16 v[158:161], v[118:121], v[174:177], v[158:161]
	v_mfma_f32_16x16x32_bf16 v[162:165], v[126:129], v[174:177], v[162:165]
	v_mfma_f32_16x16x32_bf16 v[14:17], v[118:121], v[184:187], v[14:17]
	v_mfma_f32_16x16x32_bf16 v[18:21], v[126:129], v[184:187], v[18:21]
	v_mfma_f32_16x16x32_bf16 v[142:145], v[122:125], v[138:141], v[142:145]
	v_mfma_f32_16x16x32_bf16 v[146:149], v[130:133], v[138:141], v[146:149]
	v_mfma_f32_16x16x32_bf16 v[150:153], v[122:125], v[170:173], v[150:153]
	v_mfma_f32_16x16x32_bf16 v[154:157], v[130:133], v[170:173], v[154:157]
	v_mfma_f32_16x16x32_bf16 v[158:161], v[122:125], v[178:181], v[158:161]
	v_mfma_f32_16x16x32_bf16 v[162:165], v[130:133], v[178:181], v[162:165]
	v_mfma_f32_16x16x32_bf16 v[14:17], v[122:125], v[188:191], v[14:17]
	v_mfma_f32_16x16x32_bf16 v[18:21], v[130:133], v[188:191], v[18:21]
	s_barrier
	s_add_u32 s22, s26, 0x10080
	s_addc_u32 s23, s27, 0
	s_mov_b32 m0, s25
	v_lshl_add_u64 v[118:119], s[22:23], 0, v[2:3]
	global_load_lds_dwordx4 v[118:119], off
	v_lshl_add_u64 v[118:119], s[22:23], 0, v[4:5]
	s_mov_b32 m0, s24
	s_nop 0
	global_load_lds_dwordx4 v[118:119], off
	s_waitcnt vmcnt(6)
	s_barrier
	v_mfma_f32_16x16x32_bf16 v[22:25], v[192:195], v[134:137], v[22:25]
	v_mfma_f32_16x16x32_bf16 v[26:29], v[200:203], v[134:137], v[26:29]
	v_mfma_f32_16x16x32_bf16 v[58:61], v[192:195], v[166:169], v[58:61]
	v_mfma_f32_16x16x32_bf16 v[102:105], v[200:203], v[166:169], v[102:105]
	v_mfma_f32_16x16x32_bf16 v[106:109], v[192:195], v[174:177], v[106:109]
	v_mfma_f32_16x16x32_bf16 v[114:117], v[200:203], v[174:177], v[114:117]
	v_mfma_f32_16x16x32_bf16 v[94:97], v[192:195], v[184:187], v[94:97]
	v_mfma_f32_16x16x32_bf16 v[98:101], v[200:203], v[184:187], v[98:101]
	v_mfma_f32_16x16x32_bf16 v[22:25], v[196:199], v[138:141], v[22:25]
	v_mfma_f32_16x16x32_bf16 v[26:29], v[204:207], v[138:141], v[26:29]
	v_mfma_f32_16x16x32_bf16 v[58:61], v[196:199], v[170:173], v[58:61]
	v_mfma_f32_16x16x32_bf16 v[102:105], v[204:207], v[170:173], v[102:105]
	v_mfma_f32_16x16x32_bf16 v[106:109], v[196:199], v[178:181], v[106:109]
	v_mfma_f32_16x16x32_bf16 v[114:117], v[204:207], v[178:181], v[114:117]
	v_mfma_f32_16x16x32_bf16 v[94:97], v[196:199], v[188:191], v[94:97]
	v_mfma_f32_16x16x32_bf16 v[98:101], v[204:207], v[188:191], v[98:101]
	s_lshl_b32 s4, s4, 8
	v_mov_b32_e32 v13, v238
	v_mov_b32_e32 v119, v239
	s_add_i32 s4, s4, s37
	s_barrier
	v_readlane_b32 s48, v251, 51
	v_add_u32_e32 v118, s4, v13
	s_lshl_b32 s4, s47, 8
	s_or_b32 s4, s4, s38
	v_lshl_add_u32 v120, v119, 2, s4
	v_ashrrev_i32_e32 v119, 31, v118
	v_lshlrev_b64 v[118:119], 12, v[118:119]
	v_readlane_b32 s52, v251, 55
	v_readlane_b32 s53, v251, 56
	v_ashrrev_i32_e32 v121, 31, v120
	s_mov_b32 s4, 0x10000
	v_lshl_add_u64 v[118:119], s[52:53], 0, v[118:119]
	v_lshl_add_u64 v[118:119], v[120:121], 2, v[118:119]
	global_store_dwordx4 v[118:119], v[62:65], off
	global_store_dwordx4 v[118:119], v[66:69], off offset:64
	global_store_dwordx4 v[118:119], v[110:113], off offset:512
	global_store_dwordx4 v[118:119], v[30:33], off offset:576
	s_mov_b64 s[22:23], 0x10000
	s_add_i32 s42, s42, s88
	v_add_co_u32_e32 v32, vcc, s4, v118
	s_mov_b32 s4, 0x20000
	s_nop 0
	v_addc_co_u32_e32 v33, vcc, 0, v119, vcc
	v_lshl_add_u64 v[30:31], v[118:119], 0, s[22:23]
	global_store_dwordx4 v[32:33], v[70:73], off
	global_store_dwordx4 v[30:31], v[74:77], off offset:64
	global_store_dwordx4 v[30:31], v[34:37], off offset:512
	global_store_dwordx4 v[30:31], v[38:41], off offset:576
	v_add_co_u32_e32 v32, vcc, s4, v118
	s_mov_b64 s[22:23], 0x20000
	s_nop 0
	v_addc_co_u32_e32 v33, vcc, 0, v119, vcc
	s_mov_b32 s4, 0x30000
	v_lshl_add_u64 v[30:31], v[118:119], 0, s[22:23]
	global_store_dwordx4 v[32:33], v[78:81], off
	global_store_dwordx4 v[30:31], v[82:85], off offset:64
	global_store_dwordx4 v[30:31], v[42:45], off offset:512
	global_store_dwordx4 v[30:31], v[46:49], off offset:576
	v_add_co_u32_e32 v32, vcc, s4, v118
	s_mov_b64 s[22:23], 0x30000
	s_nop 0
	v_addc_co_u32_e32 v33, vcc, 0, v119, vcc
	s_mov_b32 s4, 0x80000
	v_lshl_add_u64 v[30:31], v[118:119], 0, s[22:23]
	global_store_dwordx4 v[32:33], v[86:89], off
	global_store_dwordx4 v[30:31], v[90:93], off offset:64
	global_store_dwordx4 v[30:31], v[50:53], off offset:512
	global_store_dwordx4 v[30:31], v[54:57], off offset:576
	v_add_co_u32_e32 v32, vcc, s4, v118
	s_mov_b64 s[22:23], 0x80000
	s_nop 0
	v_addc_co_u32_e32 v33, vcc, 0, v119, vcc
	s_mov_b32 s4, 0x90000
	v_lshl_add_u64 v[30:31], v[118:119], 0, s[22:23]
	global_store_dwordx4 v[32:33], v[142:145], off
	global_store_dwordx4 v[30:31], v[146:149], off offset:64
	global_store_dwordx4 v[30:31], v[22:25], off offset:512
	global_store_dwordx4 v[30:31], v[26:29], off offset:576
	s_mov_b64 s[22:23], 0x90000
	v_add_co_u32_e32 v24, vcc, s4, v118
	s_mov_b32 s4, 0xa0000
	s_nop 0
	v_addc_co_u32_e32 v25, vcc, 0, v119, vcc
	v_lshl_add_u64 v[22:23], v[118:119], 0, s[22:23]
	global_store_dwordx4 v[24:25], v[150:153], off
	global_store_dwordx4 v[22:23], v[154:157], off offset:64
	global_store_dwordx4 v[22:23], v[58:61], off offset:512
	global_store_dwordx4 v[22:23], v[102:105], off offset:576
	v_add_co_u32_e32 v24, vcc, s4, v118
	s_mov_b64 s[22:23], 0xa0000
	s_nop 0
	v_addc_co_u32_e32 v25, vcc, 0, v119, vcc
	v_lshl_add_u64 v[22:23], v[118:119], 0, s[22:23]
	global_store_dwordx4 v[24:25], v[158:161], off
	global_store_dwordx4 v[22:23], v[162:165], off offset:64
	global_store_dwordx4 v[22:23], v[106:109], off offset:512
	global_store_dwordx4 v[22:23], v[114:117], off offset:576
	v_add_co_u32_e32 v24, vcc, 0xb0000, v118
	s_mov_b64 s[22:23], 0xb0000
	s_nop 0
	v_addc_co_u32_e32 v25, vcc, 0, v119, vcc
	v_lshl_add_u64 v[22:23], v[118:119], 0, s[22:23]
	s_andn2_b64 vcc, exec, s[0:1]
	s_mov_b32 s47, s14
	s_mov_b32 s4, s16
	s_mov_b64 s[24:25], s[20:21]
	s_mov_b64 s[22:23], s[18:19]
	v_readlane_b32 s49, v251, 52
	v_readlane_b32 s50, v251, 53
	v_readlane_b32 s51, v251, 54
	v_readlane_b32 s54, v251, 57
	v_readlane_b32 s55, v251, 58
	v_readlane_b32 s56, v251, 59
	v_readlane_b32 s57, v251, 60
	v_readlane_b32 s58, v251, 61
	v_readlane_b32 s59, v251, 62
	v_readlane_b32 s60, v251, 63
	v_readlane_b32 s61, v252, 0
	v_readlane_b32 s62, v252, 1
	v_readlane_b32 s63, v252, 2
	global_store_dwordx4 v[24:25], v[14:17], off
	global_store_dwordx4 v[22:23], v[18:21], off offset:64
	global_store_dwordx4 v[22:23], v[94:97], off offset:512
	global_store_dwordx4 v[22:23], v[98:101], off offset:576
	s_cbranch_vccz .LBB0_3190

.LBB0_3266:
	ds_read_b128 v[138:141], v180
	ds_read_b128 v[142:145], v180 offset:1024
	ds_read_b128 v[146:149], v180 offset:2048
	ds_read_b128 v[150:153], v180 offset:3072
	s_add_u32 s20, s18, 0xfffc0080
	s_addc_u32 s21, s19, -1
	s_cmp_eq_u32 s43, 12
	s_cselect_b32 s23, s9, s21
	s_cselect_b32 s22, s15, s20
	s_cselect_b32 s21, s7, s42
	s_cselect_b32 s20, s40, s41
	v_lshl_add_u64 v[178:179], s[18:19], 0, v[130:131]
	s_add_i32 m0, s17, 0xc000
	ds_read_b128 v[154:157], v181
	ds_read_b128 v[158:161], v181 offset:1024
	ds_read_b128 v[162:165], v181 offset:2048
	ds_read_b128 v[166:169], v181 offset:3072
	ds_read_b128 v[170:173], v181 offset:4096
	ds_read_b128 v[174:177], v181 offset:5120
	ds_read_b128 v[184:187], v181 offset:6144
	ds_read_b128 v[188:191], v181 offset:7168
	global_load_lds_dwordx4 v[178:179], off
	v_lshl_add_u64 v[178:179], s[18:19], 0, v[132:133]
	s_add_i32 m0, s17, 0xe000
	s_nop 0
	global_load_lds_dwordx4 v[178:179], off
	s_waitcnt lgkmcnt(8)
	s_barrier
	s_waitcnt lgkmcnt(0)
	s_waitcnt lgkmcnt(0)
	v_mfma_f32_16x16x32_bf16 v[126:129], v[138:141], v[154:157], v[126:129]
	v_mfma_f32_16x16x32_bf16 v[122:125], v[146:149], v[154:157], v[122:125]
	v_mfma_f32_16x16x32_bf16 v[114:117], v[138:141], v[162:165], v[114:117]
	v_mfma_f32_16x16x32_bf16 v[106:109], v[146:149], v[162:165], v[106:109]
	v_mfma_f32_16x16x32_bf16 v[94:97], v[138:141], v[170:173], v[94:97]
	v_mfma_f32_16x16x32_bf16 v[90:93], v[146:149], v[170:173], v[90:93]
	v_mfma_f32_16x16x32_bf16 v[82:85], v[138:141], v[184:187], v[82:85]
	v_mfma_f32_16x16x32_bf16 v[74:77], v[146:149], v[184:187], v[74:77]
	v_mfma_f32_16x16x32_bf16 v[126:129], v[142:145], v[158:161], v[126:129]
	v_mfma_f32_16x16x32_bf16 v[122:125], v[150:153], v[158:161], v[122:125]
	v_mfma_f32_16x16x32_bf16 v[114:117], v[142:145], v[166:169], v[114:117]
	v_mfma_f32_16x16x32_bf16 v[106:109], v[150:153], v[166:169], v[106:109]
	v_mfma_f32_16x16x32_bf16 v[94:97], v[142:145], v[174:177], v[94:97]
	v_mfma_f32_16x16x32_bf16 v[90:93], v[150:153], v[174:177], v[90:93]
	v_mfma_f32_16x16x32_bf16 v[82:85], v[142:145], v[188:191], v[82:85]
	v_mfma_f32_16x16x32_bf16 v[74:77], v[150:153], v[188:191], v[74:77]
	s_barrier
	s_add_i32 s44, s38, s24
	v_lshl_add_u64 v[178:179], s[20:21], 0, v[226:227]
	s_mov_b32 m0, s44
	ds_read_b128 v[192:195], v183
	ds_read_b128 v[196:199], v183 offset:1024
	ds_read_b128 v[200:203], v183 offset:2048
	ds_read_b128 v[204:207], v183 offset:3072
	global_load_lds_dwordx4 v[178:179], off
	v_lshl_add_u64 v[208:209], s[20:21], 0, v[228:229]
	s_add_i32 m0, s44, 0x2000
	s_nop 0
	global_load_lds_dwordx4 v[208:209], off
	s_barrier
	s_waitcnt lgkmcnt(0)
	s_waitcnt lgkmcnt(0)
	v_mfma_f32_16x16x32_bf16 v[118:121], v[192:195], v[154:157], v[118:121]
	v_mfma_f32_16x16x32_bf16 v[110:113], v[200:203], v[154:157], v[110:113]
	v_mfma_f32_16x16x32_bf16 v[102:105], v[192:195], v[162:165], v[102:105]
	v_mfma_f32_16x16x32_bf16 v[98:101], v[200:203], v[162:165], v[98:101]
	v_mfma_f32_16x16x32_bf16 v[86:89], v[192:195], v[170:173], v[86:89]
	v_mfma_f32_16x16x32_bf16 v[78:81], v[200:203], v[170:173], v[78:81]
	v_mfma_f32_16x16x32_bf16 v[70:73], v[192:195], v[184:187], v[70:73]
	v_mfma_f32_16x16x32_bf16 v[66:69], v[200:203], v[184:187], v[66:69]
	v_mfma_f32_16x16x32_bf16 v[118:121], v[196:199], v[158:161], v[118:121]
	v_mfma_f32_16x16x32_bf16 v[110:113], v[204:207], v[158:161], v[110:113]
	v_mfma_f32_16x16x32_bf16 v[102:105], v[196:199], v[166:169], v[102:105]
	v_mfma_f32_16x16x32_bf16 v[98:101], v[204:207], v[166:169], v[98:101]
	v_mfma_f32_16x16x32_bf16 v[86:89], v[196:199], v[174:177], v[86:89]
	v_mfma_f32_16x16x32_bf16 v[78:81], v[204:207], v[174:177], v[78:81]
	v_mfma_f32_16x16x32_bf16 v[70:73], v[196:199], v[188:191], v[70:73]
	v_mfma_f32_16x16x32_bf16 v[66:69], v[204:207], v[188:191], v[66:69]
	s_mov_b32 m0, s17
	v_lshl_add_u64 v[210:211], s[22:23], 0, v[226:227]
	s_barrier
	ds_read_b128 v[154:157], v181 offset:16384
	ds_read_b128 v[158:161], v181 offset:17408
	ds_read_b128 v[162:165], v181 offset:18432
	ds_read_b128 v[166:169], v181 offset:19456
	ds_read_b128 v[170:173], v181 offset:20480
	ds_read_b128 v[174:177], v181 offset:21504
	ds_read_b128 v[184:187], v181 offset:22528
	ds_read_b128 v[188:191], v181 offset:23552
	global_load_lds_dwordx4 v[210:211], off
	v_lshl_add_u64 v[212:213], s[22:23], 0, v[228:229]
	s_mov_b32 m0, s25
	s_nop 0
	global_load_lds_dwordx4 v[212:213], off
	s_barrier
	s_waitcnt lgkmcnt(0)
	s_waitcnt lgkmcnt(0)
	v_mfma_f32_16x16x32_bf16 v[62:65], v[138:141], v[154:157], v[62:65]
	v_mfma_f32_16x16x32_bf16 v[58:61], v[146:149], v[154:157], v[58:61]
	v_mfma_f32_16x16x32_bf16 v[50:53], v[138:141], v[162:165], v[50:53]
	v_mfma_f32_16x16x32_bf16 v[42:45], v[146:149], v[162:165], v[42:45]
	v_mfma_f32_16x16x32_bf16 v[30:33], v[138:141], v[170:173], v[30:33]
	v_mfma_f32_16x16x32_bf16 v[26:29], v[146:149], v[170:173], v[26:29]
	v_mfma_f32_16x16x32_bf16 v[18:21], v[138:141], v[184:187], v[18:21]
	v_mfma_f32_16x16x32_bf16 v[10:13], v[146:149], v[184:187], v[10:13]
	v_mfma_f32_16x16x32_bf16 v[62:65], v[142:145], v[158:161], v[62:65]
	v_mfma_f32_16x16x32_bf16 v[58:61], v[150:153], v[158:161], v[58:61]
	v_mfma_f32_16x16x32_bf16 v[50:53], v[142:145], v[166:169], v[50:53]
	v_mfma_f32_16x16x32_bf16 v[42:45], v[150:153], v[166:169], v[42:45]
	v_mfma_f32_16x16x32_bf16 v[30:33], v[142:145], v[174:177], v[30:33]
	v_mfma_f32_16x16x32_bf16 v[26:29], v[150:153], v[174:177], v[26:29]
	v_mfma_f32_16x16x32_bf16 v[18:21], v[142:145], v[188:191], v[18:21]
	v_mfma_f32_16x16x32_bf16 v[10:13], v[150:153], v[188:191], v[10:13]
	s_barrier
	s_add_u32 s44, s20, 0x40000
	s_addc_u32 s45, s21, 0
	s_add_i32 s46, s39, s24
	v_lshl_add_u64 v[138:139], s[44:45], 0, v[226:227]
	s_mov_b32 m0, s46
	s_nop 0
	global_load_lds_dwordx4 v[138:139], off
	v_lshl_add_u64 v[138:139], s[44:45], 0, v[228:229]
	s_add_i32 m0, s46, 0x2000
	s_nop 0
	global_load_lds_dwordx4 v[138:139], off
	s_waitcnt vmcnt(6)
	s_barrier
	v_mfma_f32_16x16x32_bf16 v[54:57], v[192:195], v[154:157], v[54:57]
	v_mfma_f32_16x16x32_bf16 v[46:49], v[200:203], v[154:157], v[46:49]
	v_mfma_f32_16x16x32_bf16 v[38:41], v[192:195], v[162:165], v[38:41]
	v_mfma_f32_16x16x32_bf16 v[34:37], v[200:203], v[162:165], v[34:37]
	v_mfma_f32_16x16x32_bf16 v[22:25], v[192:195], v[170:173], v[22:25]
	v_mfma_f32_16x16x32_bf16 v[14:17], v[200:203], v[170:173], v[14:17]
	v_mfma_f32_16x16x32_bf16 v[6:9], v[192:195], v[184:187], v[6:9]
	v_mfma_f32_16x16x32_bf16 v[2:5], v[200:203], v[184:187], v[2:5]
	v_mfma_f32_16x16x32_bf16 v[54:57], v[196:199], v[158:161], v[54:57]
	v_mfma_f32_16x16x32_bf16 v[46:49], v[204:207], v[158:161], v[46:49]
	v_mfma_f32_16x16x32_bf16 v[38:41], v[196:199], v[166:169], v[38:41]
	v_mfma_f32_16x16x32_bf16 v[34:37], v[204:207], v[166:169], v[34:37]
	v_mfma_f32_16x16x32_bf16 v[22:25], v[196:199], v[174:177], v[22:25]
	v_mfma_f32_16x16x32_bf16 v[14:17], v[204:207], v[174:177], v[14:17]
	v_mfma_f32_16x16x32_bf16 v[6:9], v[196:199], v[188:191], v[6:9]
	v_mfma_f32_16x16x32_bf16 v[2:5], v[204:207], v[188:191], v[2:5]
	s_add_i32 s44, 0, 0x18000
	v_add_u32_e32 v150, s44, v1
	s_barrier
	ds_read_b128 v[138:141], v150
	ds_read_b128 v[142:145], v150 offset:1024
	ds_read_b128 v[146:149], v150 offset:2048
	ds_read_b128 v[150:153], v150 offset:3072
	s_add_u32 s22, s22, 0x40000
	s_addc_u32 s23, s23, 0
	s_mov_b32 m0, s26
	v_lshl_add_u64 v[192:193], s[22:23], 0, v[226:227]
	ds_read_b128 v[154:157], v181 offset:32768
	ds_read_b128 v[158:161], v181 offset:33792
	ds_read_b128 v[162:165], v181 offset:34816
	ds_read_b128 v[166:169], v181 offset:35840
	ds_read_b128 v[170:173], v181 offset:36864
	ds_read_b128 v[174:177], v181 offset:37888
	ds_read_b128 v[184:187], v181 offset:38912
	ds_read_b128 v[188:191], v181 offset:39936
	global_load_lds_dwordx4 v[192:193], off
	v_lshl_add_u64 v[192:193], s[22:23], 0, v[228:229]
	s_mov_b32 m0, s27
	s_nop 0
	global_load_lds_dwordx4 v[192:193], off
	s_waitcnt lgkmcnt(8)
	s_barrier
	s_waitcnt lgkmcnt(0)
	s_waitcnt lgkmcnt(0)
	v_mfma_f32_16x16x32_bf16 v[126:129], v[138:141], v[154:157], v[126:129]
	v_mfma_f32_16x16x32_bf16 v[122:125], v[146:149], v[154:157], v[122:125]
	v_mfma_f32_16x16x32_bf16 v[114:117], v[138:141], v[162:165], v[114:117]
	v_mfma_f32_16x16x32_bf16 v[106:109], v[146:149], v[162:165], v[106:109]
	v_mfma_f32_16x16x32_bf16 v[94:97], v[138:141], v[170:173], v[94:97]
	v_mfma_f32_16x16x32_bf16 v[90:93], v[146:149], v[170:173], v[90:93]
	v_mfma_f32_16x16x32_bf16 v[82:85], v[138:141], v[184:187], v[82:85]
	v_mfma_f32_16x16x32_bf16 v[74:77], v[146:149], v[184:187], v[74:77]
	v_mfma_f32_16x16x32_bf16 v[126:129], v[142:145], v[158:161], v[126:129]
	v_mfma_f32_16x16x32_bf16 v[122:125], v[150:153], v[158:161], v[122:125]
	v_mfma_f32_16x16x32_bf16 v[114:117], v[142:145], v[166:169], v[114:117]
	v_mfma_f32_16x16x32_bf16 v[106:109], v[150:153], v[166:169], v[106:109]
	v_mfma_f32_16x16x32_bf16 v[94:97], v[142:145], v[174:177], v[94:97]
	v_mfma_f32_16x16x32_bf16 v[90:93], v[150:153], v[174:177], v[90:93]
	v_mfma_f32_16x16x32_bf16 v[82:85], v[142:145], v[188:191], v[82:85]
	v_mfma_f32_16x16x32_bf16 v[74:77], v[150:153], v[188:191], v[74:77]
	s_barrier
	s_add_i32 s22, 0, 0x1c000
	s_add_i32 s23, s44, s24
	v_add_u32_e32 v204, s22, v1
	v_lshl_add_u64 v[178:179], v[178:179], 0, s[0:1]
	s_mov_b32 m0, s23
	ds_read_b128 v[192:195], v204
	ds_read_b128 v[196:199], v204 offset:1024
	ds_read_b128 v[200:203], v204 offset:2048
	ds_read_b128 v[204:207], v204 offset:3072
	global_load_lds_dwordx4 v[178:179], off
	v_lshl_add_u64 v[178:179], v[208:209], 0, s[0:1]
	s_add_i32 m0, s23, 0x2000
	s_nop 0
	global_load_lds_dwordx4 v[178:179], off
	s_barrier
	s_waitcnt lgkmcnt(0)
	s_waitcnt lgkmcnt(0)
	v_mfma_f32_16x16x32_bf16 v[118:121], v[192:195], v[154:157], v[118:121]
	v_mfma_f32_16x16x32_bf16 v[110:113], v[200:203], v[154:157], v[110:113]
	v_mfma_f32_16x16x32_bf16 v[102:105], v[192:195], v[162:165], v[102:105]
	v_mfma_f32_16x16x32_bf16 v[98:101], v[200:203], v[162:165], v[98:101]
	v_mfma_f32_16x16x32_bf16 v[86:89], v[192:195], v[170:173], v[86:89]
	v_mfma_f32_16x16x32_bf16 v[78:81], v[200:203], v[170:173], v[78:81]
	v_mfma_f32_16x16x32_bf16 v[70:73], v[192:195], v[184:187], v[70:73]
	v_mfma_f32_16x16x32_bf16 v[66:69], v[200:203], v[184:187], v[66:69]
	v_mfma_f32_16x16x32_bf16 v[118:121], v[196:199], v[158:161], v[118:121]
	v_mfma_f32_16x16x32_bf16 v[110:113], v[204:207], v[158:161], v[110:113]
	v_mfma_f32_16x16x32_bf16 v[102:105], v[196:199], v[166:169], v[102:105]
	v_mfma_f32_16x16x32_bf16 v[98:101], v[204:207], v[166:169], v[98:101]
	v_mfma_f32_16x16x32_bf16 v[86:89], v[196:199], v[174:177], v[86:89]
	v_mfma_f32_16x16x32_bf16 v[78:81], v[204:207], v[174:177], v[78:81]
	v_mfma_f32_16x16x32_bf16 v[70:73], v[196:199], v[188:191], v[70:73]
	v_mfma_f32_16x16x32_bf16 v[66:69], v[204:207], v[188:191], v[66:69]
	s_mov_b32 m0, s34
	v_lshl_add_u64 v[178:179], v[210:211], 0, s[0:1]
	s_barrier
	ds_read_b128 v[154:157], v181 offset:49152
	ds_read_b128 v[158:161], v181 offset:50176
	ds_read_b128 v[162:165], v181 offset:51200
	ds_read_b128 v[166:169], v181 offset:52224
	ds_read_b128 v[170:173], v181 offset:53248
	ds_read_b128 v[174:177], v181 offset:54272
	ds_read_b128 v[184:187], v181 offset:55296
	ds_read_b128 v[188:191], v181 offset:56320
	global_load_lds_dwordx4 v[178:179], off
	v_lshl_add_u64 v[178:179], v[212:213], 0, s[0:1]
	s_mov_b32 m0, s35
	s_nop 0
	global_load_lds_dwordx4 v[178:179], off
	s_barrier
	s_waitcnt lgkmcnt(0)
	s_waitcnt lgkmcnt(0)
	v_mfma_f32_16x16x32_bf16 v[62:65], v[138:141], v[154:157], v[62:65]
	v_mfma_f32_16x16x32_bf16 v[58:61], v[146:149], v[154:157], v[58:61]
	v_mfma_f32_16x16x32_bf16 v[50:53], v[138:141], v[162:165], v[50:53]
	v_mfma_f32_16x16x32_bf16 v[42:45], v[146:149], v[162:165], v[42:45]
	v_mfma_f32_16x16x32_bf16 v[30:33], v[138:141], v[170:173], v[30:33]
	v_mfma_f32_16x16x32_bf16 v[26:29], v[146:149], v[170:173], v[26:29]
	v_mfma_f32_16x16x32_bf16 v[18:21], v[138:141], v[184:187], v[18:21]
	v_mfma_f32_16x16x32_bf16 v[10:13], v[146:149], v[184:187], v[10:13]
	v_mfma_f32_16x16x32_bf16 v[62:65], v[142:145], v[158:161], v[62:65]
	v_mfma_f32_16x16x32_bf16 v[58:61], v[150:153], v[158:161], v[58:61]
	v_mfma_f32_16x16x32_bf16 v[50:53], v[142:145], v[166:169], v[50:53]
	v_mfma_f32_16x16x32_bf16 v[42:45], v[150:153], v[166:169], v[42:45]
	v_mfma_f32_16x16x32_bf16 v[30:33], v[142:145], v[174:177], v[30:33]
	v_mfma_f32_16x16x32_bf16 v[26:29], v[150:153], v[174:177], v[26:29]
	v_mfma_f32_16x16x32_bf16 v[18:21], v[142:145], v[188:191], v[18:21]
	v_mfma_f32_16x16x32_bf16 v[10:13], v[150:153], v[188:191], v[10:13]
	s_barrier
	s_add_u32 s20, s20, 0x40080
	s_addc_u32 s21, s21, 0
	s_add_i32 s22, s22, s24
	v_lshl_add_u64 v[138:139], s[20:21], 0, v[226:227]
	s_mov_b32 m0, s22
	s_nop 0
	global_load_lds_dwordx4 v[138:139], off
	v_lshl_add_u64 v[138:139], s[20:21], 0, v[228:229]
	s_add_i32 m0, s22, 0x2000
	s_nop 0
	global_load_lds_dwordx4 v[138:139], off
	s_waitcnt vmcnt(6)
	s_barrier
	v_mfma_f32_16x16x32_bf16 v[54:57], v[192:195], v[154:157], v[54:57]
	v_mfma_f32_16x16x32_bf16 v[46:49], v[200:203], v[154:157], v[46:49]
	v_mfma_f32_16x16x32_bf16 v[38:41], v[192:195], v[162:165], v[38:41]
	v_mfma_f32_16x16x32_bf16 v[34:37], v[200:203], v[162:165], v[34:37]
	v_mfma_f32_16x16x32_bf16 v[22:25], v[192:195], v[170:173], v[22:25]
	v_mfma_f32_16x16x32_bf16 v[14:17], v[200:203], v[170:173], v[14:17]
	v_mfma_f32_16x16x32_bf16 v[6:9], v[192:195], v[184:187], v[6:9]
	v_mfma_f32_16x16x32_bf16 v[2:5], v[200:203], v[184:187], v[2:5]
	v_mfma_f32_16x16x32_bf16 v[54:57], v[196:199], v[158:161], v[54:57]
	v_mfma_f32_16x16x32_bf16 v[46:49], v[204:207], v[158:161], v[46:49]
	v_mfma_f32_16x16x32_bf16 v[38:41], v[196:199], v[166:169], v[38:41]
	v_mfma_f32_16x16x32_bf16 v[34:37], v[204:207], v[166:169], v[34:37]
	v_mfma_f32_16x16x32_bf16 v[22:25], v[196:199], v[174:177], v[22:25]
	v_mfma_f32_16x16x32_bf16 v[14:17], v[204:207], v[174:177], v[14:17]
	v_mfma_f32_16x16x32_bf16 v[6:9], v[196:199], v[188:191], v[6:9]
	v_mfma_f32_16x16x32_bf16 v[2:5], v[204:207], v[188:191], v[2:5]
	s_add_i32 s43, s43, 2
	s_add_u32 s18, s18, 0x100
	s_addc_u32 s19, s19, 0
	s_add_u32 s41, s41, 0x100
	s_addc_u32 s42, s42, 0
	s_cmp_gt_u32 s43, 13
	s_barrier
	s_cbranch_scc0 .LBB0_3266
	v_mov_b32_e32 v138, v238
	v_mov_b32_e32 v139, v239
	s_lshl_b32 s7, s16, 8
	s_add_i32 s7, s7, s31
	v_add_u32_e32 v138, s7, v138
	s_lshl_b32 s7, s14, 8
	s_or_b32 s7, s7, s33
	v_lshl_add_u32 v142, v139, 2, s7
	v_readlane_b32 s40, v253, 32
	v_ashrrev_i32_e32 v143, 31, v142
	v_readlane_b32 s41, v253, 33
	v_ashrrev_i32_e32 v139, 31, v138
	v_lshlrev_b64 v[144:145], 12, v[138:139]
	v_lshl_add_u64 v[140:141], v[142:143], 2, s[40:41]
	v_cmp_gt_i32_e32 vcc, s29, v138
	v_lshl_add_u64 v[158:159], v[140:141], 0, v[144:145]
	v_mov_b32_e32 v144, 0
	v_mov_b32_e32 v146, 0
	v_mov_b32_e32 v147, 0
	v_mov_b32_e32 v148, 0
	v_mov_b32_e32 v149, 0
	v_readlane_b32 s42, v253, 34
	v_readlane_b32 s43, v253, 35
	v_readlane_b32 s44, v253, 36
	v_readlane_b32 s45, v253, 37
	v_readlane_b32 s46, v253, 38
	v_readlane_b32 s47, v253, 39
	v_readlane_b32 s48, v253, 40
	v_readlane_b32 s49, v253, 41
	v_readlane_b32 s50, v253, 42
	v_readlane_b32 s51, v253, 43
	v_readlane_b32 s52, v253, 44
	v_readlane_b32 s53, v253, 45
	v_readlane_b32 s54, v253, 46
	v_readlane_b32 s55, v253, 47
	s_and_saveexec_b64 s[14:15], vcc
	s_cbranch_execz .LBB0_3269
	global_load_dwordx4 v[146:149], v[158:159], off
	s_waitcnt vmcnt(0)
	v_pk_mul_f32 v[148:149], v[148:149], s[2:3] op_sel_hi:[1,0]
	v_pk_mul_f32 v[146:147], v[146:147], s[2:3] op_sel_hi:[1,0]

.LBB0_3462:
	ds_read_b128 v[130:133], v154
	ds_read_b128 v[134:137], v154 offset:1024
	ds_read_b128 v[146:149], v154 offset:2048
	ds_read_b128 v[150:153], v154 offset:3072
	s_add_u32 s28, s26, 0xfffc0080
	s_addc_u32 s29, s27, -1
	s_cmp_eq_u32 s59, 12
	s_cselect_b32 s31, s19, s29
	s_cselect_b32 s30, s55, s28
	s_cselect_b32 s29, s17, s58
	s_cselect_b32 s28, s56, s57
	v_lshl_add_u64 v[192:193], s[26:27], 0, v[138:139]
	s_add_i32 m0, s36, 0xc000
	ds_read_b128 v[158:161], v155
	ds_read_b128 v[162:165], v155 offset:1024
	ds_read_b128 v[166:169], v155 offset:2048
	ds_read_b128 v[170:173], v155 offset:3072
	ds_read_b128 v[174:177], v155 offset:4096
	ds_read_b128 v[178:181], v155 offset:5120
	ds_read_b128 v[184:187], v155 offset:6144
	ds_read_b128 v[188:191], v155 offset:7168
	global_load_lds_dwordx4 v[192:193], off
	v_lshl_add_u64 v[192:193], s[26:27], 0, v[140:141]
	s_add_i32 m0, s36, 0xe000
	s_nop 0
	global_load_lds_dwordx4 v[192:193], off
	s_waitcnt lgkmcnt(8)
	s_barrier
	s_waitcnt lgkmcnt(0)
	s_waitcnt lgkmcnt(0)
	v_mfma_f32_16x16x32_bf16 v[126:129], v[130:133], v[158:161], v[126:129]
	v_mfma_f32_16x16x32_bf16 v[122:125], v[146:149], v[158:161], v[122:125]
	v_mfma_f32_16x16x32_bf16 v[118:121], v[130:133], v[166:169], v[118:121]
	v_mfma_f32_16x16x32_bf16 v[106:109], v[146:149], v[166:169], v[106:109]
	v_mfma_f32_16x16x32_bf16 v[102:105], v[130:133], v[174:177], v[102:105]
	v_mfma_f32_16x16x32_bf16 v[90:93], v[146:149], v[174:177], v[90:93]
	v_mfma_f32_16x16x32_bf16 v[86:89], v[130:133], v[184:187], v[86:89]
	v_mfma_f32_16x16x32_bf16 v[74:77], v[146:149], v[184:187], v[74:77]
	v_mfma_f32_16x16x32_bf16 v[126:129], v[134:137], v[162:165], v[126:129]
	v_mfma_f32_16x16x32_bf16 v[122:125], v[150:153], v[162:165], v[122:125]
	v_mfma_f32_16x16x32_bf16 v[118:121], v[134:137], v[170:173], v[118:121]
	v_mfma_f32_16x16x32_bf16 v[106:109], v[150:153], v[170:173], v[106:109]
	v_mfma_f32_16x16x32_bf16 v[102:105], v[134:137], v[178:181], v[102:105]
	v_mfma_f32_16x16x32_bf16 v[90:93], v[150:153], v[178:181], v[90:93]
	v_mfma_f32_16x16x32_bf16 v[86:89], v[134:137], v[188:191], v[86:89]
	v_mfma_f32_16x16x32_bf16 v[74:77], v[150:153], v[188:191], v[74:77]
	s_barrier
	s_add_i32 s60, s46, s33
	v_lshl_add_u64 v[208:209], s[28:29], 0, v[226:227]
	s_mov_b32 m0, s60
	ds_read_b128 v[192:195], v156
	ds_read_b128 v[196:199], v156 offset:1024
	ds_read_b128 v[200:203], v156 offset:2048
	ds_read_b128 v[204:207], v156 offset:3072
	global_load_lds_dwordx4 v[208:209], off
	v_lshl_add_u64 v[210:211], s[28:29], 0, v[228:229]
	s_add_i32 m0, s60, 0x2000
	s_nop 0
	global_load_lds_dwordx4 v[210:211], off
	s_barrier
	s_waitcnt lgkmcnt(0)
	s_waitcnt lgkmcnt(0)
	v_mfma_f32_16x16x32_bf16 v[114:117], v[192:195], v[158:161], v[114:117]
	v_mfma_f32_16x16x32_bf16 v[110:113], v[200:203], v[158:161], v[110:113]
	v_mfma_f32_16x16x32_bf16 v[98:101], v[192:195], v[166:169], v[98:101]
	v_mfma_f32_16x16x32_bf16 v[94:97], v[200:203], v[166:169], v[94:97]
	v_mfma_f32_16x16x32_bf16 v[82:85], v[192:195], v[174:177], v[82:85]
	v_mfma_f32_16x16x32_bf16 v[78:81], v[200:203], v[174:177], v[78:81]
	v_mfma_f32_16x16x32_bf16 v[70:73], v[192:195], v[184:187], v[70:73]
	v_mfma_f32_16x16x32_bf16 v[66:69], v[200:203], v[184:187], v[66:69]
	v_mfma_f32_16x16x32_bf16 v[114:117], v[196:199], v[162:165], v[114:117]
	v_mfma_f32_16x16x32_bf16 v[110:113], v[204:207], v[162:165], v[110:113]
	v_mfma_f32_16x16x32_bf16 v[98:101], v[196:199], v[170:173], v[98:101]
	v_mfma_f32_16x16x32_bf16 v[94:97], v[204:207], v[170:173], v[94:97]
	v_mfma_f32_16x16x32_bf16 v[82:85], v[196:199], v[178:181], v[82:85]
	v_mfma_f32_16x16x32_bf16 v[78:81], v[204:207], v[178:181], v[78:81]
	v_mfma_f32_16x16x32_bf16 v[70:73], v[196:199], v[188:191], v[70:73]
	v_mfma_f32_16x16x32_bf16 v[66:69], v[204:207], v[188:191], v[66:69]
	s_mov_b32 m0, s36
	v_lshl_add_u64 v[212:213], s[30:31], 0, v[226:227]
	s_barrier
	ds_read_b128 v[158:161], v155 offset:16384
	ds_read_b128 v[162:165], v155 offset:17408
	ds_read_b128 v[166:169], v155 offset:18432
	ds_read_b128 v[170:173], v155 offset:19456
	ds_read_b128 v[174:177], v155 offset:20480
	ds_read_b128 v[178:181], v155 offset:21504
	ds_read_b128 v[184:187], v155 offset:22528
	ds_read_b128 v[188:191], v155 offset:23552
	global_load_lds_dwordx4 v[212:213], off
	v_lshl_add_u64 v[214:215], s[30:31], 0, v[228:229]
	s_mov_b32 m0, s37
	s_nop 0
	global_load_lds_dwordx4 v[214:215], off
	s_barrier
	s_waitcnt lgkmcnt(0)
	s_waitcnt lgkmcnt(0)
	v_mfma_f32_16x16x32_bf16 v[62:65], v[130:133], v[158:161], v[62:65]
	v_mfma_f32_16x16x32_bf16 v[58:61], v[146:149], v[158:161], v[58:61]
	v_mfma_f32_16x16x32_bf16 v[54:57], v[130:133], v[166:169], v[54:57]
	v_mfma_f32_16x16x32_bf16 v[46:49], v[146:149], v[166:169], v[46:49]
	v_mfma_f32_16x16x32_bf16 v[38:41], v[130:133], v[174:177], v[38:41]
	v_mfma_f32_16x16x32_bf16 v[30:33], v[146:149], v[174:177], v[30:33]
	v_mfma_f32_16x16x32_bf16 v[22:25], v[130:133], v[184:187], v[22:25]
	v_mfma_f32_16x16x32_bf16 v[14:17], v[146:149], v[184:187], v[14:17]
	v_mfma_f32_16x16x32_bf16 v[62:65], v[134:137], v[162:165], v[62:65]
	v_mfma_f32_16x16x32_bf16 v[58:61], v[150:153], v[162:165], v[58:61]
	v_mfma_f32_16x16x32_bf16 v[54:57], v[134:137], v[170:173], v[54:57]
	v_mfma_f32_16x16x32_bf16 v[46:49], v[150:153], v[170:173], v[46:49]
	v_mfma_f32_16x16x32_bf16 v[38:41], v[134:137], v[178:181], v[38:41]
	v_mfma_f32_16x16x32_bf16 v[30:33], v[150:153], v[178:181], v[30:33]
	v_mfma_f32_16x16x32_bf16 v[22:25], v[134:137], v[188:191], v[22:25]
	v_mfma_f32_16x16x32_bf16 v[14:17], v[150:153], v[188:191], v[14:17]
	s_barrier
	s_add_u32 s60, s28, 0x40000
	s_addc_u32 s61, s29, 0
	s_add_i32 s62, s47, s33
	v_lshl_add_u64 v[130:131], s[60:61], 0, v[226:227]
	s_mov_b32 m0, s62
	s_nop 0
	global_load_lds_dwordx4 v[130:131], off
	v_lshl_add_u64 v[130:131], s[60:61], 0, v[228:229]
	s_add_i32 m0, s62, 0x2000
	s_nop 0
	global_load_lds_dwordx4 v[130:131], off
	s_waitcnt vmcnt(6)
	s_barrier
	v_mfma_f32_16x16x32_bf16 v[50:53], v[192:195], v[158:161], v[50:53]
	v_mfma_f32_16x16x32_bf16 v[42:45], v[200:203], v[158:161], v[42:45]
	v_mfma_f32_16x16x32_bf16 v[34:37], v[192:195], v[166:169], v[34:37]
	v_mfma_f32_16x16x32_bf16 v[26:29], v[200:203], v[166:169], v[26:29]
	v_mfma_f32_16x16x32_bf16 v[18:21], v[192:195], v[174:177], v[18:21]
	v_mfma_f32_16x16x32_bf16 v[10:13], v[200:203], v[174:177], v[10:13]
	v_mfma_f32_16x16x32_bf16 v[6:9], v[192:195], v[184:187], v[6:9]
	v_mfma_f32_16x16x32_bf16 v[2:5], v[200:203], v[184:187], v[2:5]
	v_mfma_f32_16x16x32_bf16 v[50:53], v[196:199], v[162:165], v[50:53]
	v_mfma_f32_16x16x32_bf16 v[42:45], v[204:207], v[162:165], v[42:45]
	v_mfma_f32_16x16x32_bf16 v[34:37], v[196:199], v[170:173], v[34:37]
	v_mfma_f32_16x16x32_bf16 v[26:29], v[204:207], v[170:173], v[26:29]
	v_mfma_f32_16x16x32_bf16 v[18:21], v[196:199], v[178:181], v[18:21]
	v_mfma_f32_16x16x32_bf16 v[10:13], v[204:207], v[178:181], v[10:13]
	v_mfma_f32_16x16x32_bf16 v[6:9], v[196:199], v[188:191], v[6:9]
	v_mfma_f32_16x16x32_bf16 v[2:5], v[204:207], v[188:191], v[2:5]
	s_add_i32 s60, 0, 0x18000
	v_add_u32_e32 v150, s60, v1
	s_barrier
	ds_read_b128 v[130:133], v150
	ds_read_b128 v[134:137], v150 offset:1024
	ds_read_b128 v[146:149], v150 offset:2048
	ds_read_b128 v[150:153], v150 offset:3072
	s_add_u32 s30, s30, 0x40000
	s_addc_u32 s31, s31, 0
	s_mov_b32 m0, s38
	v_lshl_add_u64 v[192:193], s[30:31], 0, v[226:227]
	ds_read_b128 v[158:161], v155 offset:32768
	ds_read_b128 v[162:165], v155 offset:33792
	ds_read_b128 v[166:169], v155 offset:34816
	ds_read_b128 v[170:173], v155 offset:35840
	ds_read_b128 v[174:177], v155 offset:36864
	ds_read_b128 v[178:181], v155 offset:37888
	ds_read_b128 v[184:187], v155 offset:38912
	ds_read_b128 v[188:191], v155 offset:39936
	global_load_lds_dwordx4 v[192:193], off
	v_lshl_add_u64 v[192:193], s[30:31], 0, v[228:229]
	s_mov_b32 m0, s39
	s_nop 0
	global_load_lds_dwordx4 v[192:193], off
	s_waitcnt lgkmcnt(8)
	s_barrier
	s_waitcnt lgkmcnt(0)
	s_waitcnt lgkmcnt(0)
	v_mfma_f32_16x16x32_bf16 v[126:129], v[130:133], v[158:161], v[126:129]
	v_mfma_f32_16x16x32_bf16 v[122:125], v[146:149], v[158:161], v[122:125]
	v_mfma_f32_16x16x32_bf16 v[118:121], v[130:133], v[166:169], v[118:121]
	v_mfma_f32_16x16x32_bf16 v[106:109], v[146:149], v[166:169], v[106:109]
	v_mfma_f32_16x16x32_bf16 v[102:105], v[130:133], v[174:177], v[102:105]
	v_mfma_f32_16x16x32_bf16 v[90:93], v[146:149], v[174:177], v[90:93]
	v_mfma_f32_16x16x32_bf16 v[86:89], v[130:133], v[184:187], v[86:89]
	v_mfma_f32_16x16x32_bf16 v[74:77], v[146:149], v[184:187], v[74:77]
	v_mfma_f32_16x16x32_bf16 v[126:129], v[134:137], v[162:165], v[126:129]
	v_mfma_f32_16x16x32_bf16 v[122:125], v[150:153], v[162:165], v[122:125]
	v_mfma_f32_16x16x32_bf16 v[118:121], v[134:137], v[170:173], v[118:121]
	v_mfma_f32_16x16x32_bf16 v[106:109], v[150:153], v[170:173], v[106:109]
	v_mfma_f32_16x16x32_bf16 v[102:105], v[134:137], v[178:181], v[102:105]
	v_mfma_f32_16x16x32_bf16 v[90:93], v[150:153], v[178:181], v[90:93]
	v_mfma_f32_16x16x32_bf16 v[86:89], v[134:137], v[188:191], v[86:89]
	v_mfma_f32_16x16x32_bf16 v[74:77], v[150:153], v[188:191], v[74:77]
	s_barrier
	s_add_i32 s30, 0, 0x1c000
	s_add_i32 s31, s60, s33
	v_add_u32_e32 v157, s30, v1
	v_lshl_add_u64 v[208:209], v[208:209], 0, s[0:1]
	s_mov_b32 m0, s31
	ds_read_b128 v[192:195], v157
	ds_read_b128 v[196:199], v157 offset:1024
	ds_read_b128 v[200:203], v157 offset:2048
	ds_read_b128 v[204:207], v157 offset:3072
	global_load_lds_dwordx4 v[208:209], off
	v_lshl_add_u64 v[208:209], v[210:211], 0, s[0:1]
	s_add_i32 m0, s31, 0x2000
	s_nop 0
	global_load_lds_dwordx4 v[208:209], off
	s_barrier
	s_waitcnt lgkmcnt(0)
	s_waitcnt lgkmcnt(0)
	v_mfma_f32_16x16x32_bf16 v[114:117], v[192:195], v[158:161], v[114:117]
	v_mfma_f32_16x16x32_bf16 v[110:113], v[200:203], v[158:161], v[110:113]
	v_mfma_f32_16x16x32_bf16 v[98:101], v[192:195], v[166:169], v[98:101]
	v_mfma_f32_16x16x32_bf16 v[94:97], v[200:203], v[166:169], v[94:97]
	v_mfma_f32_16x16x32_bf16 v[82:85], v[192:195], v[174:177], v[82:85]
	v_mfma_f32_16x16x32_bf16 v[78:81], v[200:203], v[174:177], v[78:81]
	v_mfma_f32_16x16x32_bf16 v[70:73], v[192:195], v[184:187], v[70:73]
	v_mfma_f32_16x16x32_bf16 v[66:69], v[200:203], v[184:187], v[66:69]
	v_mfma_f32_16x16x32_bf16 v[114:117], v[196:199], v[162:165], v[114:117]
	v_mfma_f32_16x16x32_bf16 v[110:113], v[204:207], v[162:165], v[110:113]
	v_mfma_f32_16x16x32_bf16 v[98:101], v[196:199], v[170:173], v[98:101]
	v_mfma_f32_16x16x32_bf16 v[94:97], v[204:207], v[170:173], v[94:97]
	v_mfma_f32_16x16x32_bf16 v[82:85], v[196:199], v[178:181], v[82:85]
	v_mfma_f32_16x16x32_bf16 v[78:81], v[204:207], v[178:181], v[78:81]
	v_mfma_f32_16x16x32_bf16 v[70:73], v[196:199], v[188:191], v[70:73]
	v_mfma_f32_16x16x32_bf16 v[66:69], v[204:207], v[188:191], v[66:69]
	s_mov_b32 m0, s43
	v_lshl_add_u64 v[208:209], v[212:213], 0, s[0:1]
	s_barrier
	ds_read_b128 v[158:161], v155 offset:49152
	ds_read_b128 v[162:165], v155 offset:50176
	ds_read_b128 v[166:169], v155 offset:51200
	ds_read_b128 v[170:173], v155 offset:52224
	ds_read_b128 v[174:177], v155 offset:53248
	ds_read_b128 v[178:181], v155 offset:54272
	ds_read_b128 v[184:187], v155 offset:55296
	ds_read_b128 v[188:191], v155 offset:56320
	global_load_lds_dwordx4 v[208:209], off
	v_lshl_add_u64 v[208:209], v[214:215], 0, s[0:1]
	s_mov_b32 m0, s44
	s_nop 0
	global_load_lds_dwordx4 v[208:209], off
	s_barrier
	s_waitcnt lgkmcnt(0)
	s_waitcnt lgkmcnt(0)
	v_mfma_f32_16x16x32_bf16 v[62:65], v[130:133], v[158:161], v[62:65]
	v_mfma_f32_16x16x32_bf16 v[58:61], v[146:149], v[158:161], v[58:61]
	v_mfma_f32_16x16x32_bf16 v[54:57], v[130:133], v[166:169], v[54:57]
	v_mfma_f32_16x16x32_bf16 v[46:49], v[146:149], v[166:169], v[46:49]
	v_mfma_f32_16x16x32_bf16 v[38:41], v[130:133], v[174:177], v[38:41]
	v_mfma_f32_16x16x32_bf16 v[30:33], v[146:149], v[174:177], v[30:33]
	v_mfma_f32_16x16x32_bf16 v[22:25], v[130:133], v[184:187], v[22:25]
	v_mfma_f32_16x16x32_bf16 v[14:17], v[146:149], v[184:187], v[14:17]
	v_mfma_f32_16x16x32_bf16 v[62:65], v[134:137], v[162:165], v[62:65]
	v_mfma_f32_16x16x32_bf16 v[58:61], v[150:153], v[162:165], v[58:61]
	v_mfma_f32_16x16x32_bf16 v[54:57], v[134:137], v[170:173], v[54:57]
	v_mfma_f32_16x16x32_bf16 v[46:49], v[150:153], v[170:173], v[46:49]
	v_mfma_f32_16x16x32_bf16 v[38:41], v[134:137], v[178:181], v[38:41]
	v_mfma_f32_16x16x32_bf16 v[30:33], v[150:153], v[178:181], v[30:33]
	v_mfma_f32_16x16x32_bf16 v[22:25], v[134:137], v[188:191], v[22:25]
	v_mfma_f32_16x16x32_bf16 v[14:17], v[150:153], v[188:191], v[14:17]
	s_barrier
	s_add_u32 s28, s28, 0x40080
	s_addc_u32 s29, s29, 0
	s_add_i32 s30, s30, s33
	v_lshl_add_u64 v[130:131], s[28:29], 0, v[226:227]
	s_mov_b32 m0, s30
	s_nop 0
	global_load_lds_dwordx4 v[130:131], off
	v_lshl_add_u64 v[130:131], s[28:29], 0, v[228:229]
	s_add_i32 m0, s30, 0x2000
	s_nop 0
	global_load_lds_dwordx4 v[130:131], off
	s_waitcnt vmcnt(6)
	s_barrier
	v_mfma_f32_16x16x32_bf16 v[50:53], v[192:195], v[158:161], v[50:53]
	v_mfma_f32_16x16x32_bf16 v[42:45], v[200:203], v[158:161], v[42:45]
	v_mfma_f32_16x16x32_bf16 v[34:37], v[192:195], v[166:169], v[34:37]
	v_mfma_f32_16x16x32_bf16 v[26:29], v[200:203], v[166:169], v[26:29]
	v_mfma_f32_16x16x32_bf16 v[18:21], v[192:195], v[174:177], v[18:21]
	v_mfma_f32_16x16x32_bf16 v[10:13], v[200:203], v[174:177], v[10:13]
	v_mfma_f32_16x16x32_bf16 v[6:9], v[192:195], v[184:187], v[6:9]
	v_mfma_f32_16x16x32_bf16 v[2:5], v[200:203], v[184:187], v[2:5]
	v_mfma_f32_16x16x32_bf16 v[50:53], v[196:199], v[162:165], v[50:53]
	v_mfma_f32_16x16x32_bf16 v[42:45], v[204:207], v[162:165], v[42:45]
	v_mfma_f32_16x16x32_bf16 v[34:37], v[196:199], v[170:173], v[34:37]
	v_mfma_f32_16x16x32_bf16 v[26:29], v[204:207], v[170:173], v[26:29]
	v_mfma_f32_16x16x32_bf16 v[18:21], v[196:199], v[178:181], v[18:21]
	v_mfma_f32_16x16x32_bf16 v[10:13], v[204:207], v[178:181], v[10:13]
	v_mfma_f32_16x16x32_bf16 v[6:9], v[196:199], v[188:191], v[6:9]
	v_mfma_f32_16x16x32_bf16 v[2:5], v[204:207], v[188:191], v[2:5]
	s_add_i32 s59, s59, 2
	s_add_u32 s26, s26, 0x100
	s_addc_u32 s27, s27, 0
	s_add_u32 s57, s57, 0x100
	s_addc_u32 s58, s58, 0
	s_cmp_gt_u32 s59, 13
	s_barrier
	s_cbranch_scc0 .LBB0_3462
	s_lshl_b32 s17, s24, 8
	v_mov_b32_e32 v130, v238
	v_mov_b32_e32 v131, v239
	s_add_i32 s17, s17, s41
	s_nop 0
	v_add_u32_e32 v148, s17, v130
	s_lshl_b32 s17, s25, 8
	s_or_b32 s17, s17, s42
	v_lshl_add_u32 v146, v131, 2, s17
	s_cmp_lt_i32 s25, 8
	v_ashrrev_i32_e32 v147, 31, v146
	s_mov_b64 s[24:25], -1
	v_ashrrev_i32_e32 v149, 31, v148
	s_cbranch_scc1 .LBB0_3465
	v_readlane_b32 s68, v251, 51
	v_readlane_b32 s72, v251, 55
	v_readlane_b32 s73, v251, 56
	v_lshlrev_b64 v[130:131], 12, v[148:149]
	v_mul_f32_e32 v166, 0xbfb8aa3b, v127
	v_lshl_add_u64 v[152:153], v[146:147], 2, s[72:73]
	v_lshl_add_u64 v[130:131], v[152:153], 0, v[130:131]
	v_add_co_u32_e32 v132, vcc, 0xffffe000, v130
	v_mul_f32_e32 v167, 0xbfb8aa3b, v128
	s_nop 0
	v_addc_co_u32_e32 v133, vcc, -1, v131, vcc
	v_add_co_u32_e32 v130, vcc, 0xfffff000, v130
	global_load_dwordx4 v[134:137], v[132:133], off
	s_nop 0
	v_addc_co_u32_e32 v131, vcc, -1, v131, vcc
	global_load_dwordx4 v[158:161], v[130:131], off offset:-4032
	global_load_dwordx4 v[162:165], v[130:131], off offset:-3584
	v_mul_f32_e32 v168, 0xbfb8aa3b, v129
	v_mul_f32_e32 v169, 0xbfb8aa3b, v122
	v_exp_f32_e32 v183, v166
	v_exp_f32_e32 v188, v167
	v_exp_f32_e32 v189, v168
	v_exp_f32_e32 v190, v169
	global_load_dwordx4 v[166:169], v[130:131], off offset:-3520
	v_add_u32_e32 v184, 16, v148
	v_ashrrev_i32_e32 v185, 31, v184
	v_readlane_b32 s74, v251, 57
	v_readlane_b32 s75, v251, 58
	v_lshlrev_b64 v[132:133], 11, v[148:149]
	v_lshlrev_b64 v[130:131], 12, v[184:185]
	v_lshlrev_b64 v[150:151], 1, v[146:147]
	v_lshl_add_u64 v[132:133], s[74:75], 0, v[132:133]
	v_lshl_add_u64 v[130:131], v[152:153], 0, v[130:131]
	v_lshl_add_u64 v[186:187], v[132:133], 0, v[150:151]
	v_add_co_u32_e32 v132, vcc, s48, v130
	v_mul_f32_e32 v170, 0xbfb8aa3b, v123
	s_nop 0
	v_addc_co_u32_e32 v133, vcc, -1, v131, vcc
	v_add_co_u32_e32 v130, vcc, s49, v130
	v_mul_f32_e32 v171, 0xbfb8aa3b, v124
	v_mul_f32_e32 v172, 0xbfb8aa3b, v125
	v_mul_f32_e32 v173, 0xbfb8aa3b, v114
	v_mul_f32_e32 v174, 0xbfb8aa3b, v115
	v_mul_f32_e32 v175, 0xbfb8aa3b, v116
	v_addc_co_u32_e32 v131, vcc, -1, v131, vcc
	v_exp_f32_e32 v191, v170
	v_exp_f32_e32 v192, v171
	v_exp_f32_e32 v193, v172
	v_exp_f32_e32 v194, v173
	v_exp_f32_e32 v197, v174
	v_exp_f32_e32 v198, v175
	global_load_dwordx4 v[170:173], v[132:133], off
	global_load_dwordx4 v[174:177], v[130:131], off offset:-4032
	global_load_dwordx4 v[178:181], v[130:131], off offset:-3584
	s_nop 0
	global_load_dwordx4 v[130:133], v[130:131], off offset:-3520
	v_mul_f32_e32 v157, 0xbfb8aa3b, v126
	v_exp_f32_e32 v157, v157
	v_add_f32_e32 v183, 1.0, v183
	v_add_f32_e32 v195, 1.0, v188
	v_add_f32_e32 v196, 1.0, v189
	v_add_f32_e32 v157, 1.0, v157
	v_add_f32_e32 v199, 1.0, v190
	v_add_f32_e32 v200, 1.0, v191
	v_add_f32_e32 v201, 1.0, v192
	v_add_f32_e32 v202, 1.0, v193
	v_rcp_f32_e32 v188, v157
	v_rcp_f32_e32 v189, v183
	v_rcp_f32_e32 v190, v195
	v_rcp_f32_e32 v191, v196
	v_add_f32_e32 v203, 1.0, v194
	v_rcp_f32_e32 v194, v201
	v_rcp_f32_e32 v195, v202
	v_rcp_f32_e32 v192, v199
	v_rcp_f32_e32 v193, v200
	v_rcp_f32_e32 v196, v203
	v_mul_f32_e32 v183, 0xbfb8aa3b, v104
	v_exp_f32_e32 v183, v183
	s_mov_b64 s[24:25], 0
	v_readlane_b32 s69, v251, 52
	v_readlane_b32 s70, v251, 53
	v_add_f32_e32 v183, 1.0, v183
	v_readlane_b32 s71, v251, 54
	v_readlane_b32 s76, v251, 59
	v_readlane_b32 s77, v251, 60
	v_readlane_b32 s78, v251, 61
	v_readlane_b32 s79, v251, 62
	v_readlane_b32 s80, v251, 63
	v_readlane_b32 s81, v252, 0
	v_readlane_b32 s82, v252, 1
	v_readlane_b32 s83, v252, 2
	s_waitcnt vmcnt(0)
	v_pk_mul_f32 v[136:137], v[190:191], v[136:137]
	v_pk_mul_f32 v[134:135], v[188:189], v[134:135]
	v_mul_f32_e32 v189, 0xbfb8aa3b, v105
	v_cvt_pk_bf16_f32 v134, v134, v135
	v_cvt_pk_bf16_f32 v135, v136, v137
	v_pk_mul_f32 v[136:137], v[194:195], v[160:161]
	v_pk_mul_f32 v[158:159], v[192:193], v[158:159]
	global_store_dwordx2 v[186:187], v[134:135], off offset:-4096
	v_cvt_pk_bf16_f32 v134, v158, v159
	v_cvt_pk_bf16_f32 v135, v136, v137
	v_add_f32_e32 v136, 1.0, v197
	v_rcp_f32_e32 v197, v136
	v_mul_f32_e32 v136, 0xbfb8aa3b, v110
	v_exp_f32_e32 v157, v136
	global_store_dwordx2 v[186:187], v[134:135], off offset:-4064
	v_pk_mul_f32 v[136:137], v[196:197], v[162:163]
	v_mul_f32_e32 v134, 0xbfb8aa3b, v117
	v_cvt_pk_bf16_f32 v136, v136, v137
	v_add_f32_e32 v137, 1.0, v157
	v_exp_f32_e32 v135, v134
	v_rcp_f32_e32 v158, v137
	v_mul_f32_e32 v137, 0xbfb8aa3b, v111
	v_mul_f32_e32 v157, 0xbfb8aa3b, v112
	v_exp_f32_e32 v137, v137
	v_exp_f32_e32 v157, v157
	v_mul_f32_e32 v159, 0xbfb8aa3b, v113
	v_exp_f32_e32 v159, v159
	v_add_f32_e32 v134, 1.0, v198
	v_add_f32_e32 v135, 1.0, v135
	v_rcp_f32_e32 v134, v134
	v_rcp_f32_e32 v135, v135
	v_add_f32_e32 v137, 1.0, v137
	v_add_f32_e32 v157, 1.0, v157
	v_rcp_f32_e32 v160, v157
	v_add_f32_e32 v157, 1.0, v159
	v_rcp_f32_e32 v159, v137
	v_rcp_f32_e32 v161, v157
	v_pk_mul_f32 v[134:135], v[134:135], v[164:165]
	v_mul_f32_e32 v157, 0xbfb8aa3b, v120
	v_cvt_pk_bf16_f32 v137, v134, v135
	global_store_dwordx2 v[186:187], v[136:137], off offset:-3840
	v_pk_mul_f32 v[136:137], v[158:159], v[166:167]
	v_pk_mul_f32 v[134:135], v[160:161], v[168:169]
	v_cvt_pk_bf16_f32 v136, v136, v137
	v_exp_f32_e32 v157, v157
	v_cvt_pk_bf16_f32 v137, v134, v135
	global_store_dwordx2 v[186:187], v[136:137], off offset:-3808
	v_mul_f32_e32 v134, 0xbfb8aa3b, v118
	v_mul_f32_e32 v137, 0xbfb8aa3b, v119
	v_mul_f32_e32 v158, 0xbfb8aa3b, v121
	v_exp_f32_e32 v136, v134
	v_exp_f32_e32 v137, v137
	v_exp_f32_e32 v159, v158
	v_add_f32_e32 v157, 1.0, v157
	v_add_f32_e32 v136, 1.0, v136
	v_add_f32_e32 v137, 1.0, v137
	v_rcp_f32_e32 v158, v157
	v_add_f32_e32 v157, 1.0, v159
	v_rcp_f32_e32 v136, v136
	v_rcp_f32_e32 v159, v157
	v_rcp_f32_e32 v137, v137
	v_mul_f32_e32 v157, 0xbfb8aa3b, v106
	v_exp_f32_e32 v157, v157
	v_mul_f32_e32 v161, 0xbfb8aa3b, v109
	v_pk_mul_f32 v[136:137], v[136:137], v[170:171]
	v_exp_f32_e32 v161, v161
	v_cvt_pk_bf16_f32 v136, v136, v137
	v_add_f32_e32 v137, 1.0, v157
	v_mul_f32_e32 v157, 0xbfb8aa3b, v108
	v_rcp_f32_e32 v160, v137
	v_mul_f32_e32 v137, 0xbfb8aa3b, v107
	v_exp_f32_e32 v157, v157
	v_exp_f32_e32 v137, v137
	v_lshlrev_b64 v[134:135], 11, v[184:185]
	v_lshl_add_u64 v[134:135], s[74:75], 0, v[134:135]
	v_add_f32_e32 v157, 1.0, v157
	v_add_f32_e32 v137, 1.0, v137
	v_rcp_f32_e32 v162, v157
	v_add_f32_e32 v157, 1.0, v161
	v_rcp_f32_e32 v163, v157
	v_rcp_f32_e32 v161, v137
	v_mul_f32_e32 v157, 0xbfb8aa3b, v98
	v_exp_f32_e32 v157, v157
	v_lshl_add_u64 v[134:135], v[134:135], 0, v[150:151]
	v_pk_mul_f32 v[158:159], v[158:159], v[172:173]
	v_add_u32_e32 v184, 32, v148
	v_cvt_pk_bf16_f32 v137, v158, v159
	global_store_dwordx2 v[134:135], v[136:137], off offset:-4096
	v_pk_mul_f32 v[136:137], v[162:163], v[176:177]
	v_pk_mul_f32 v[158:159], v[160:161], v[174:175]
	v_mul_f32_e32 v161, 0xbfb8aa3b, v97
	v_cvt_pk_bf16_f32 v158, v158, v159
	v_cvt_pk_bf16_f32 v159, v136, v137
	v_add_f32_e32 v136, 1.0, v157
	v_mul_f32_e32 v157, 0xbfb8aa3b, v100
	global_store_dwordx2 v[134:135], v[158:159], off offset:-4064
	v_mul_f32_e32 v137, 0xbfb8aa3b, v99
	v_exp_f32_e32 v157, v157
	v_mul_f32_e32 v158, 0xbfb8aa3b, v101
	v_exp_f32_e32 v137, v137
	v_exp_f32_e32 v159, v158
	v_add_f32_e32 v157, 1.0, v157
	v_rcp_f32_e32 v158, v157
	v_add_f32_e32 v137, 1.0, v137
	v_add_f32_e32 v157, 1.0, v159
	v_rcp_f32_e32 v136, v136
	v_rcp_f32_e32 v159, v157
	v_rcp_f32_e32 v137, v137
	v_mul_f32_e32 v157, 0xbfb8aa3b, v94
	v_exp_f32_e32 v157, v157
	v_exp_f32_e32 v161, v161
	v_pk_mul_f32 v[136:137], v[136:137], v[178:179]
	v_pk_mul_f32 v[158:159], v[158:159], v[180:181]
	v_cvt_pk_bf16_f32 v136, v136, v137
	v_add_f32_e32 v137, 1.0, v157
	v_rcp_f32_e32 v160, v137
	v_mul_f32_e32 v137, 0xbfb8aa3b, v95
	v_mul_f32_e32 v157, 0xbfb8aa3b, v96
	v_exp_f32_e32 v137, v137
	v_exp_f32_e32 v157, v157
	v_ashrrev_i32_e32 v185, 31, v184
	v_add_u32_e32 v186, 48, v148
	v_add_f32_e32 v137, 1.0, v137
	v_add_f32_e32 v157, 1.0, v157
	v_rcp_f32_e32 v162, v157
	v_add_f32_e32 v157, 1.0, v161
	v_rcp_f32_e32 v161, v137
	v_rcp_f32_e32 v163, v157
	v_cvt_pk_bf16_f32 v137, v158, v159
	global_store_dwordx2 v[134:135], v[136:137], off offset:-3840
	v_pk_mul_f32 v[130:131], v[160:161], v[130:131]
	v_pk_mul_f32 v[132:133], v[162:163], v[132:133]
	v_cvt_pk_bf16_f32 v130, v130, v131
	v_ashrrev_i32_e32 v187, 31, v186
	v_cvt_pk_bf16_f32 v131, v132, v133
	global_store_dwordx2 v[134:135], v[130:131], off offset:-3808
	v_lshlrev_b64 v[130:131], 12, v[184:185]
	v_lshl_add_u64 v[130:131], v[152:153], 0, v[130:131]
	v_add_co_u32_e32 v132, vcc, s48, v130
	v_mul_f32_e32 v157, 0xbfb8aa3b, v102
	s_nop 0
	v_addc_co_u32_e32 v133, vcc, -1, v131, vcc
	global_load_dwordx4 v[158:161], v[132:133], off
	v_add_co_u32_e32 v130, vcc, s49, v130
	v_exp_f32_e32 v157, v157
	s_nop 0
	v_addc_co_u32_e32 v131, vcc, -1, v131, vcc
	global_load_dwordx4 v[162:165], v[130:131], off offset:-4032
	global_load_dwordx4 v[166:169], v[130:131], off offset:-3584
	global_load_dwordx4 v[170:173], v[130:131], off offset:-3520
	v_lshlrev_b64 v[130:131], 12, v[186:187]
	v_lshl_add_u64 v[130:131], v[152:153], 0, v[130:131]
	v_add_co_u32_e32 v132, vcc, s48, v130
	v_add_f32_e32 v157, 1.0, v157
	s_nop 0
	v_addc_co_u32_e32 v133, vcc, -1, v131, vcc
	v_add_co_u32_e32 v130, vcc, s49, v130
	v_rcp_f32_e32 v188, v157
	s_nop 0
	v_addc_co_u32_e32 v131, vcc, -1, v131, vcc
	global_load_dwordx4 v[174:177], v[132:133], off
	global_load_dwordx4 v[178:181], v[130:131], off offset:-4032
	global_load_dwordx4 v[134:137], v[130:131], off offset:-3584
	s_nop 0
	global_load_dwordx4 v[130:133], v[130:131], off offset:-3520
	v_mul_f32_e32 v157, 0xbfb8aa3b, v103
	v_exp_f32_e32 v157, v157
	v_exp_f32_e32 v189, v189
	v_rcp_f32_e32 v190, v183
	v_add_f32_e32 v157, 1.0, v157
	v_add_f32_e32 v183, 1.0, v189
	v_rcp_f32_e32 v189, v157
	v_mul_f32_e32 v157, 0xbfb8aa3b, v90
	v_exp_f32_e32 v157, v157
	v_rcp_f32_e32 v191, v183
	v_mul_f32_e32 v183, 0xbfb8aa3b, v93
	v_exp_f32_e32 v183, v183
	v_add_f32_e32 v157, 1.0, v157
	v_lshlrev_b64 v[184:185], 11, v[184:185]
	v_lshl_add_u64 v[184:185], s[74:75], 0, v[184:185]
	v_lshl_add_u64 v[184:185], v[184:185], 0, v[150:151]
	s_waitcnt vmcnt(0)
	v_pk_mul_f32 v[158:159], v[188:189], v[158:159]
	s_nop 0
	v_cvt_pk_bf16_f32 v158, v158, v159
	v_mul_f32_e32 v159, 0xbfb8aa3b, v92
	v_rcp_f32_e32 v188, v157
	v_mul_f32_e32 v157, 0xbfb8aa3b, v91
	v_exp_f32_e32 v159, v159
	v_exp_f32_e32 v157, v157
	v_pk_mul_f32 v[160:161], v[190:191], v[160:161]
	v_add_f32_e32 v159, 1.0, v159
	v_add_f32_e32 v157, 1.0, v157
	v_rcp_f32_e32 v190, v159
	v_add_f32_e32 v159, 1.0, v183
	v_rcp_f32_e32 v191, v159
	v_rcp_f32_e32 v189, v157
	v_mul_f32_e32 v157, 0xbfb8aa3b, v82
	v_exp_f32_e32 v157, v157
	v_cvt_pk_bf16_f32 v159, v160, v161
	global_store_dwordx2 v[184:185], v[158:159], off offset:-4096
	v_pk_mul_f32 v[158:159], v[190:191], v[164:165]
	v_pk_mul_f32 v[160:161], v[188:189], v[162:163]
	v_add_f32_e32 v157, 1.0, v157
	v_cvt_pk_bf16_f32 v160, v160, v161
	v_cvt_pk_bf16_f32 v161, v158, v159
	v_mul_f32_e32 v159, 0xbfb8aa3b, v84
	global_store_dwordx2 v[184:185], v[160:161], off offset:-4064
	v_rcp_f32_e32 v158, v157
	v_mul_f32_e32 v157, 0xbfb8aa3b, v83
	v_exp_f32_e32 v159, v159
	v_mul_f32_e32 v160, 0xbfb8aa3b, v85
	v_exp_f32_e32 v157, v157
	v_exp_f32_e32 v161, v160
	v_add_f32_e32 v159, 1.0, v159
	v_rcp_f32_e32 v160, v159
	v_add_f32_e32 v157, 1.0, v157
	v_add_f32_e32 v159, 1.0, v161
	v_rcp_f32_e32 v161, v159
	v_rcp_f32_e32 v159, v157
	v_mul_f32_e32 v157, 0xbfb8aa3b, v78
	v_exp_f32_e32 v157, v157
	v_mul_f32_e32 v163, 0xbfb8aa3b, v81
	v_pk_mul_f32 v[158:159], v[158:159], v[166:167]
	v_exp_f32_e32 v163, v163
	v_add_f32_e32 v157, 1.0, v157
	v_cvt_pk_bf16_f32 v158, v158, v159
	v_rcp_f32_e32 v162, v157
	v_mul_f32_e32 v157, 0xbfb8aa3b, v79
	v_mul_f32_e32 v159, 0xbfb8aa3b, v80
	v_exp_f32_e32 v157, v157
	v_exp_f32_e32 v159, v159
	v_pk_mul_f32 v[160:161], v[160:161], v[168:169]
	v_mul_f32_e32 v183, 0xbfb8aa3b, v64
	v_add_f32_e32 v157, 1.0, v157
	v_add_f32_e32 v159, 1.0, v159
	v_rcp_f32_e32 v164, v159
	v_add_f32_e32 v159, 1.0, v163
	v_rcp_f32_e32 v163, v157
	v_rcp_f32_e32 v165, v159
	v_mul_f32_e32 v157, 0xbfb8aa3b, v86
	v_exp_f32_e32 v157, v157
	v_cvt_pk_bf16_f32 v159, v160, v161
	v_pk_mul_f32 v[160:161], v[162:163], v[170:171]
	global_store_dwordx2 v[184:185], v[158:159], off offset:-3840
	v_pk_mul_f32 v[158:159], v[164:165], v[172:173]
	v_cvt_pk_bf16_f32 v160, v160, v161
	v_add_f32_e32 v157, 1.0, v157
	v_cvt_pk_bf16_f32 v161, v158, v159
	global_store_dwordx2 v[184:185], v[160:161], off offset:-3808
	v_mul_f32_e32 v161, 0xbfb8aa3b, v88
	v_rcp_f32_e32 v160, v157
	v_mul_f32_e32 v157, 0xbfb8aa3b, v87
	v_exp_f32_e32 v161, v161
	v_mul_f32_e32 v162, 0xbfb8aa3b, v89
	v_exp_f32_e32 v157, v157
	v_exp_f32_e32 v163, v162
	v_add_f32_e32 v161, 1.0, v161
	v_rcp_f32_e32 v162, v161
	v_add_f32_e32 v157, 1.0, v157
	v_add_f32_e32 v161, 1.0, v163
	v_rcp_f32_e32 v163, v161
	v_rcp_f32_e32 v161, v157
	v_mul_f32_e32 v157, 0xbfb8aa3b, v74
	v_exp_f32_e32 v157, v157
	v_mul_f32_e32 v165, 0xbfb8aa3b, v77
	v_pk_mul_f32 v[160:161], v[160:161], v[174:175]
	v_exp_f32_e32 v165, v165
	v_cvt_pk_bf16_f32 v160, v160, v161
	v_add_f32_e32 v157, 1.0, v157
	v_mul_f32_e32 v161, 0xbfb8aa3b, v76
	v_rcp_f32_e32 v164, v157
	v_mul_f32_e32 v157, 0xbfb8aa3b, v75
	v_exp_f32_e32 v161, v161
	v_exp_f32_e32 v157, v157
	v_lshlrev_b64 v[158:159], 11, v[186:187]
	v_lshl_add_u64 v[158:159], s[74:75], 0, v[158:159]
	v_add_f32_e32 v161, 1.0, v161
	v_add_f32_e32 v157, 1.0, v157
	v_rcp_f32_e32 v166, v161
	v_add_f32_e32 v161, 1.0, v165
	v_rcp_f32_e32 v167, v161
	v_rcp_f32_e32 v165, v157
	v_mul_f32_e32 v157, 0xbfb8aa3b, v70
	v_exp_f32_e32 v157, v157
	v_lshl_add_u64 v[158:159], v[158:159], 0, v[150:151]
	v_pk_mul_f32 v[162:163], v[162:163], v[176:177]
	v_add_u32_e32 v184, 0x80, v148
	v_cvt_pk_bf16_f32 v161, v162, v163
	global_store_dwordx2 v[158:159], v[160:161], off offset:-4096
	v_pk_mul_f32 v[160:161], v[166:167], v[180:181]
	v_pk_mul_f32 v[162:163], v[164:165], v[178:179]
	v_add_f32_e32 v157, 1.0, v157
	v_cvt_pk_bf16_f32 v162, v162, v163
	v_cvt_pk_bf16_f32 v163, v160, v161
	v_mul_f32_e32 v161, 0xbfb8aa3b, v72
	global_store_dwordx2 v[158:159], v[162:163], off offset:-4064
	v_rcp_f32_e32 v160, v157
	v_mul_f32_e32 v157, 0xbfb8aa3b, v71
	v_exp_f32_e32 v161, v161
	v_mul_f32_e32 v162, 0xbfb8aa3b, v73
	v_exp_f32_e32 v157, v157
	v_exp_f32_e32 v163, v162
	v_add_f32_e32 v161, 1.0, v161
	v_rcp_f32_e32 v162, v161
	v_add_f32_e32 v157, 1.0, v157
	v_add_f32_e32 v161, 1.0, v163
	v_rcp_f32_e32 v163, v161
	v_rcp_f32_e32 v161, v157
	v_mul_f32_e32 v157, 0xbfb8aa3b, v66
	v_exp_f32_e32 v157, v157
	v_pk_mul_f32 v[136:137], v[162:163], v[136:137]
	v_pk_mul_f32 v[134:135], v[160:161], v[134:135]
	v_mul_f32_e32 v161, 0xbfb8aa3b, v69
	v_cvt_pk_bf16_f32 v134, v134, v135
	v_add_f32_e32 v135, 1.0, v157
	v_rcp_f32_e32 v160, v135
	v_mul_f32_e32 v135, 0xbfb8aa3b, v67
	v_mul_f32_e32 v157, 0xbfb8aa3b, v68
	v_exp_f32_e32 v135, v135
	v_exp_f32_e32 v157, v157
	v_exp_f32_e32 v161, v161
	v_ashrrev_i32_e32 v185, 31, v184
	v_add_f32_e32 v135, 1.0, v135
	v_add_f32_e32 v157, 1.0, v157
	v_rcp_f32_e32 v162, v157
	v_add_f32_e32 v157, 1.0, v161
	v_rcp_f32_e32 v161, v135
	v_rcp_f32_e32 v163, v157
	v_cvt_pk_bf16_f32 v135, v136, v137
	global_store_dwordx2 v[158:159], v[134:135], off offset:-3840
	v_pk_mul_f32 v[130:131], v[160:161], v[130:131]
	v_pk_mul_f32 v[132:133], v[162:163], v[132:133]
	v_cvt_pk_bf16_f32 v130, v130, v131
	v_add_u32_e32 v186, 0x90, v148
	v_cvt_pk_bf16_f32 v131, v132, v133
	global_store_dwordx2 v[158:159], v[130:131], off offset:-3808
	v_lshlrev_b64 v[130:131], 12, v[184:185]
	v_lshl_add_u64 v[130:131], v[152:153], 0, v[130:131]
	v_add_co_u32_e32 v132, vcc, s48, v130
	v_ashrrev_i32_e32 v187, 31, v186
	s_nop 0
	v_addc_co_u32_e32 v133, vcc, -1, v131, vcc
	global_load_dwordx4 v[158:161], v[132:133], off
	v_add_co_u32_e32 v130, vcc, s49, v130
	v_mul_f32_e32 v157, 0xbfb8aa3b, v62
	s_nop 0
	v_addc_co_u32_e32 v131, vcc, -1, v131, vcc
	global_load_dwordx4 v[162:165], v[130:131], off offset:-4032
	global_load_dwordx4 v[166:169], v[130:131], off offset:-3584
	global_load_dwordx4 v[170:173], v[130:131], off offset:-3520
	v_lshlrev_b64 v[130:131], 12, v[186:187]
	v_lshl_add_u64 v[130:131], v[152:153], 0, v[130:131]
	v_add_co_u32_e32 v132, vcc, s48, v130
	v_exp_f32_e32 v157, v157
	s_nop 0
	v_addc_co_u32_e32 v133, vcc, -1, v131, vcc
	v_add_co_u32_e32 v130, vcc, s49, v130
	v_add_f32_e32 v157, 1.0, v157
	s_nop 0
	v_addc_co_u32_e32 v131, vcc, -1, v131, vcc
	global_load_dwordx4 v[174:177], v[132:133], off
	global_load_dwordx4 v[178:181], v[130:131], off offset:-4032
	global_load_dwordx4 v[134:137], v[130:131], off offset:-3584
	s_nop 0
	global_load_dwordx4 v[130:133], v[130:131], off offset:-3520
	v_rcp_f32_e32 v188, v157
	v_mul_f32_e32 v157, 0xbfb8aa3b, v63
	v_exp_f32_e32 v157, v157
	v_exp_f32_e32 v183, v183
	v_mul_f32_e32 v189, 0xbfb8aa3b, v65
	v_exp_f32_e32 v189, v189
	v_add_f32_e32 v157, 1.0, v157
	v_add_f32_e32 v183, 1.0, v183
	v_rcp_f32_e32 v190, v183
	v_add_f32_e32 v183, 1.0, v189
	v_rcp_f32_e32 v189, v157
	v_mul_f32_e32 v157, 0xbfb8aa3b, v58
	v_exp_f32_e32 v157, v157
	v_rcp_f32_e32 v191, v183
	v_mul_f32_e32 v183, 0xbfb8aa3b, v61
	v_add_f32_e32 v157, 1.0, v157
	v_exp_f32_e32 v183, v183
	v_lshlrev_b64 v[184:185], 11, v[184:185]
	v_lshl_add_u64 v[184:185], s[74:75], 0, v[184:185]
	v_lshl_add_u64 v[184:185], v[184:185], 0, v[150:151]
	s_waitcnt vmcnt(0)
	v_pk_mul_f32 v[158:159], v[188:189], v[158:159]
	s_nop 0
	v_cvt_pk_bf16_f32 v158, v158, v159
	v_mul_f32_e32 v159, 0xbfb8aa3b, v60
	v_rcp_f32_e32 v188, v157
	v_mul_f32_e32 v157, 0xbfb8aa3b, v59
	v_exp_f32_e32 v159, v159
	v_exp_f32_e32 v157, v157
	v_pk_mul_f32 v[160:161], v[190:191], v[160:161]
	v_add_f32_e32 v159, 1.0, v159
	v_add_f32_e32 v157, 1.0, v157
	v_rcp_f32_e32 v190, v159
	v_add_f32_e32 v159, 1.0, v183
	v_rcp_f32_e32 v191, v159
	v_rcp_f32_e32 v189, v157
	v_mul_f32_e32 v157, 0xbfb8aa3b, v50
	v_exp_f32_e32 v157, v157
	v_cvt_pk_bf16_f32 v159, v160, v161
	global_store_dwordx2 v[184:185], v[158:159], off offset:-4096
	v_pk_mul_f32 v[158:159], v[190:191], v[164:165]
	v_pk_mul_f32 v[160:161], v[188:189], v[162:163]
	v_add_f32_e32 v157, 1.0, v157
	v_cvt_pk_bf16_f32 v160, v160, v161
	v_cvt_pk_bf16_f32 v161, v158, v159
	v_mul_f32_e32 v159, 0xbfb8aa3b, v52
	global_store_dwordx2 v[184:185], v[160:161], off offset:-4064
	v_rcp_f32_e32 v158, v157
	v_mul_f32_e32 v157, 0xbfb8aa3b, v51
	v_exp_f32_e32 v159, v159
	v_mul_f32_e32 v160, 0xbfb8aa3b, v53
	v_exp_f32_e32 v157, v157
	v_exp_f32_e32 v161, v160
	v_add_f32_e32 v159, 1.0, v159
	v_rcp_f32_e32 v160, v159
	v_add_f32_e32 v157, 1.0, v157
	v_add_f32_e32 v159, 1.0, v161
	v_rcp_f32_e32 v161, v159
	v_rcp_f32_e32 v159, v157
	v_mul_f32_e32 v157, 0xbfb8aa3b, v42
	v_exp_f32_e32 v157, v157
	v_mul_f32_e32 v163, 0xbfb8aa3b, v45
	v_pk_mul_f32 v[158:159], v[158:159], v[166:167]
	v_exp_f32_e32 v163, v163
	v_add_f32_e32 v157, 1.0, v157
	v_cvt_pk_bf16_f32 v158, v158, v159
	v_rcp_f32_e32 v162, v157
	v_mul_f32_e32 v157, 0xbfb8aa3b, v43
	v_mul_f32_e32 v159, 0xbfb8aa3b, v44
	v_exp_f32_e32 v157, v157
	v_exp_f32_e32 v159, v159
	v_pk_mul_f32 v[160:161], v[160:161], v[168:169]
	v_mul_f32_e32 v183, 0xbfb8aa3b, v40
	v_add_f32_e32 v157, 1.0, v157
	v_add_f32_e32 v159, 1.0, v159
	v_rcp_f32_e32 v164, v159
	v_add_f32_e32 v159, 1.0, v163
	v_rcp_f32_e32 v163, v157
	v_rcp_f32_e32 v165, v159
	v_mul_f32_e32 v157, 0xbfb8aa3b, v54
	v_exp_f32_e32 v157, v157
	v_cvt_pk_bf16_f32 v159, v160, v161
	v_pk_mul_f32 v[160:161], v[162:163], v[170:171]
	global_store_dwordx2 v[184:185], v[158:159], off offset:-3840
	v_pk_mul_f32 v[158:159], v[164:165], v[172:173]
	v_cvt_pk_bf16_f32 v160, v160, v161
	v_add_f32_e32 v157, 1.0, v157
	v_cvt_pk_bf16_f32 v161, v158, v159
	global_store_dwordx2 v[184:185], v[160:161], off offset:-3808
	v_mul_f32_e32 v161, 0xbfb8aa3b, v56
	v_rcp_f32_e32 v160, v157
	v_mul_f32_e32 v157, 0xbfb8aa3b, v55
	v_exp_f32_e32 v161, v161
	v_mul_f32_e32 v162, 0xbfb8aa3b, v57
	v_exp_f32_e32 v157, v157
	v_exp_f32_e32 v163, v162
	v_add_f32_e32 v161, 1.0, v161
	v_rcp_f32_e32 v162, v161
	v_add_f32_e32 v157, 1.0, v157
	v_add_f32_e32 v161, 1.0, v163
	v_rcp_f32_e32 v163, v161
	v_rcp_f32_e32 v161, v157
	v_mul_f32_e32 v157, 0xbfb8aa3b, v46
	v_exp_f32_e32 v157, v157
	v_mul_f32_e32 v165, 0xbfb8aa3b, v49
	v_pk_mul_f32 v[160:161], v[160:161], v[174:175]
	v_exp_f32_e32 v165, v165
	v_cvt_pk_bf16_f32 v160, v160, v161
	v_add_f32_e32 v157, 1.0, v157
	v_mul_f32_e32 v161, 0xbfb8aa3b, v48
	v_rcp_f32_e32 v164, v157
	v_mul_f32_e32 v157, 0xbfb8aa3b, v47
	v_exp_f32_e32 v161, v161
	v_exp_f32_e32 v157, v157
	v_lshlrev_b64 v[158:159], 11, v[186:187]
	v_lshl_add_u64 v[158:159], s[74:75], 0, v[158:159]
	v_add_f32_e32 v161, 1.0, v161
	v_add_f32_e32 v157, 1.0, v157
	v_rcp_f32_e32 v166, v161
	v_add_f32_e32 v161, 1.0, v165
	v_rcp_f32_e32 v167, v161
	v_rcp_f32_e32 v165, v157
	v_mul_f32_e32 v157, 0xbfb8aa3b, v34
	v_exp_f32_e32 v157, v157
	v_lshl_add_u64 v[158:159], v[158:159], 0, v[150:151]
	v_pk_mul_f32 v[162:163], v[162:163], v[176:177]
	v_add_u32_e32 v184, 0xa0, v148
	v_cvt_pk_bf16_f32 v161, v162, v163
	global_store_dwordx2 v[158:159], v[160:161], off offset:-4096
	v_pk_mul_f32 v[160:161], v[166:167], v[180:181]
	v_pk_mul_f32 v[162:163], v[164:165], v[178:179]
	v_add_f32_e32 v157, 1.0, v157
	v_cvt_pk_bf16_f32 v162, v162, v163
	v_cvt_pk_bf16_f32 v163, v160, v161
	v_mul_f32_e32 v161, 0xbfb8aa3b, v36
	global_store_dwordx2 v[158:159], v[162:163], off offset:-4064
	v_rcp_f32_e32 v160, v157
	v_mul_f32_e32 v157, 0xbfb8aa3b, v35
	v_exp_f32_e32 v161, v161
	v_mul_f32_e32 v162, 0xbfb8aa3b, v37
	v_exp_f32_e32 v157, v157
	v_exp_f32_e32 v163, v162
	v_add_f32_e32 v161, 1.0, v161
	v_rcp_f32_e32 v162, v161
	v_add_f32_e32 v157, 1.0, v157
	v_add_f32_e32 v161, 1.0, v163
	v_rcp_f32_e32 v163, v161
	v_rcp_f32_e32 v161, v157
	v_mul_f32_e32 v157, 0xbfb8aa3b, v26
	v_exp_f32_e32 v157, v157
	v_pk_mul_f32 v[136:137], v[162:163], v[136:137]
	v_pk_mul_f32 v[134:135], v[160:161], v[134:135]
	v_mul_f32_e32 v161, 0xbfb8aa3b, v29
	v_cvt_pk_bf16_f32 v134, v134, v135
	v_add_f32_e32 v135, 1.0, v157
	v_rcp_f32_e32 v160, v135
	v_mul_f32_e32 v135, 0xbfb8aa3b, v27
	v_mul_f32_e32 v157, 0xbfb8aa3b, v28
	v_exp_f32_e32 v135, v135
	v_exp_f32_e32 v157, v157
	v_exp_f32_e32 v161, v161
	v_ashrrev_i32_e32 v185, 31, v184
	v_add_f32_e32 v135, 1.0, v135
	v_add_f32_e32 v157, 1.0, v157
	v_rcp_f32_e32 v162, v157
	v_add_f32_e32 v157, 1.0, v161
	v_rcp_f32_e32 v161, v135
	v_rcp_f32_e32 v163, v157
	v_cvt_pk_bf16_f32 v135, v136, v137
	global_store_dwordx2 v[158:159], v[134:135], off offset:-3840
	v_pk_mul_f32 v[130:131], v[160:161], v[130:131]
	v_pk_mul_f32 v[132:133], v[162:163], v[132:133]
	v_cvt_pk_bf16_f32 v130, v130, v131
	v_add_u32_e32 v186, 0xb0, v148
	v_cvt_pk_bf16_f32 v131, v132, v133
	global_store_dwordx2 v[158:159], v[130:131], off offset:-3808
	v_lshlrev_b64 v[130:131], 12, v[184:185]
	v_lshl_add_u64 v[130:131], v[152:153], 0, v[130:131]
	v_add_co_u32_e32 v132, vcc, s48, v130
	v_ashrrev_i32_e32 v187, 31, v186
	s_nop 0
	v_addc_co_u32_e32 v133, vcc, -1, v131, vcc
	global_load_dwordx4 v[158:161], v[132:133], off
	v_add_co_u32_e32 v130, vcc, s49, v130
	v_exp_f32_e32 v183, v183
	s_nop 0
	v_addc_co_u32_e32 v131, vcc, -1, v131, vcc
	global_load_dwordx4 v[162:165], v[130:131], off offset:-4032
	global_load_dwordx4 v[166:169], v[130:131], off offset:-3584
	global_load_dwordx4 v[170:173], v[130:131], off offset:-3520
	v_lshlrev_b64 v[130:131], 12, v[186:187]
	v_lshl_add_u64 v[130:131], v[152:153], 0, v[130:131]
	v_add_co_u32_e32 v132, vcc, s48, v130
	v_mul_f32_e32 v152, 0xbfb8aa3b, v38
	s_nop 0
	v_addc_co_u32_e32 v133, vcc, -1, v131, vcc
	v_add_co_u32_e32 v130, vcc, s49, v130
	v_exp_f32_e32 v157, v152
	s_nop 0
	v_addc_co_u32_e32 v131, vcc, -1, v131, vcc
	global_load_dwordx4 v[174:177], v[132:133], off
	global_load_dwordx4 v[178:181], v[130:131], off offset:-4032
	global_load_dwordx4 v[134:137], v[130:131], off offset:-3584
	s_nop 0
	global_load_dwordx4 v[130:133], v[130:131], off offset:-3520
	v_add_f32_e32 v157, 1.0, v157
	v_lshlrev_b64 v[152:153], 11, v[184:185]
	v_rcp_f32_e32 v184, v157
	v_mul_f32_e32 v157, 0xbfb8aa3b, v39
	v_exp_f32_e32 v157, v157
	v_mul_f32_e32 v185, 0xbfb8aa3b, v41
	v_exp_f32_e32 v185, v185
	v_add_f32_e32 v183, 1.0, v183
	v_add_f32_e32 v157, 1.0, v157
	v_rcp_f32_e32 v188, v183
	v_add_f32_e32 v183, 1.0, v185
	v_rcp_f32_e32 v185, v157
	v_mul_f32_e32 v157, 0xbfb8aa3b, v30
	v_exp_f32_e32 v157, v157
	v_rcp_f32_e32 v189, v183
	v_mul_f32_e32 v183, 0xbfb8aa3b, v33
	v_add_f32_e32 v157, 1.0, v157
	v_exp_f32_e32 v183, v183
	v_lshl_add_u64 v[152:153], s[74:75], 0, v[152:153]
	v_lshl_add_u64 v[152:153], v[152:153], 0, v[150:151]
	s_waitcnt vmcnt(0)
	v_pk_mul_f32 v[158:159], v[184:185], v[158:159]
	s_nop 0
	v_cvt_pk_bf16_f32 v158, v158, v159
	v_mul_f32_e32 v159, 0xbfb8aa3b, v32
	v_rcp_f32_e32 v184, v157
	v_mul_f32_e32 v157, 0xbfb8aa3b, v31
	v_exp_f32_e32 v159, v159
	v_exp_f32_e32 v157, v157
	v_pk_mul_f32 v[160:161], v[188:189], v[160:161]
	v_add_f32_e32 v159, 1.0, v159
	v_add_f32_e32 v157, 1.0, v157
	v_rcp_f32_e32 v188, v159
	v_add_f32_e32 v159, 1.0, v183
	v_rcp_f32_e32 v189, v159
	v_rcp_f32_e32 v185, v157
	v_mul_f32_e32 v157, 0xbfb8aa3b, v18
	v_exp_f32_e32 v157, v157
	v_cvt_pk_bf16_f32 v159, v160, v161
	global_store_dwordx2 v[152:153], v[158:159], off offset:-4096
	v_pk_mul_f32 v[158:159], v[188:189], v[164:165]
	v_pk_mul_f32 v[160:161], v[184:185], v[162:163]
	v_add_f32_e32 v157, 1.0, v157
	v_cvt_pk_bf16_f32 v160, v160, v161
	v_cvt_pk_bf16_f32 v161, v158, v159
	v_mul_f32_e32 v159, 0xbfb8aa3b, v20
	global_store_dwordx2 v[152:153], v[160:161], off offset:-4064
	v_rcp_f32_e32 v158, v157
	v_mul_f32_e32 v157, 0xbfb8aa3b, v19
	v_exp_f32_e32 v159, v159
	v_mul_f32_e32 v160, 0xbfb8aa3b, v21
	v_exp_f32_e32 v157, v157
	v_exp_f32_e32 v161, v160
	v_add_f32_e32 v159, 1.0, v159
	v_rcp_f32_e32 v160, v159
	v_add_f32_e32 v157, 1.0, v157
	v_add_f32_e32 v159, 1.0, v161
	v_rcp_f32_e32 v161, v159
	v_rcp_f32_e32 v159, v157
	v_mul_f32_e32 v157, 0xbfb8aa3b, v10
	v_exp_f32_e32 v157, v157
	v_mul_f32_e32 v163, 0xbfb8aa3b, v13
	v_pk_mul_f32 v[158:159], v[158:159], v[166:167]
	v_exp_f32_e32 v163, v163
	v_add_f32_e32 v157, 1.0, v157
	v_cvt_pk_bf16_f32 v158, v158, v159
	v_rcp_f32_e32 v162, v157
	v_mul_f32_e32 v157, 0xbfb8aa3b, v11
	v_mul_f32_e32 v159, 0xbfb8aa3b, v12
	v_exp_f32_e32 v157, v157
	v_exp_f32_e32 v159, v159
	v_pk_mul_f32 v[160:161], v[160:161], v[168:169]
	v_add_f32_e32 v157, 1.0, v157
	v_add_f32_e32 v159, 1.0, v159
	v_rcp_f32_e32 v164, v159
	v_add_f32_e32 v159, 1.0, v163
	v_rcp_f32_e32 v163, v157
	v_rcp_f32_e32 v165, v159
	v_cvt_pk_bf16_f32 v159, v160, v161
	global_store_dwordx2 v[152:153], v[158:159], off offset:-3840
	v_pk_mul_f32 v[160:161], v[162:163], v[170:171]
	v_pk_mul_f32 v[158:159], v[164:165], v[172:173]
	v_cvt_pk_bf16_f32 v160, v160, v161
	s_nop 0
	v_cvt_pk_bf16_f32 v161, v158, v159
	global_store_dwordx2 v[152:153], v[160:161], off offset:-3808
	v_mul_f32_e32 v152, 0xbfb8aa3b, v22
	v_exp_f32_e32 v157, v152
	v_lshlrev_b64 v[152:153], 11, v[186:187]
	v_lshl_add_u64 v[152:153], s[74:75], 0, v[152:153]
	v_lshl_add_u64 v[150:151], v[152:153], 0, v[150:151]
	v_add_f32_e32 v152, 1.0, v157
	v_mul_f32_e32 v157, 0xbfb8aa3b, v24
	v_mul_f32_e32 v153, 0xbfb8aa3b, v23
	v_exp_f32_e32 v157, v157
	v_mul_f32_e32 v158, 0xbfb8aa3b, v25
	v_exp_f32_e32 v153, v153
	v_exp_f32_e32 v159, v158
	v_add_f32_e32 v157, 1.0, v157
	v_rcp_f32_e32 v158, v157
	v_add_f32_e32 v153, 1.0, v153
	v_add_f32_e32 v157, 1.0, v159
	v_rcp_f32_e32 v152, v152
	v_rcp_f32_e32 v159, v157
	v_rcp_f32_e32 v153, v153
	v_mul_f32_e32 v157, 0xbfb8aa3b, v14
	v_exp_f32_e32 v157, v157
	v_mul_f32_e32 v161, 0xbfb8aa3b, v17
	v_pk_mul_f32 v[152:153], v[152:153], v[174:175]
	v_exp_f32_e32 v161, v161
	v_cvt_pk_bf16_f32 v152, v152, v153
	v_add_f32_e32 v153, 1.0, v157
	v_mul_f32_e32 v157, 0xbfb8aa3b, v16
	v_rcp_f32_e32 v160, v153
	v_mul_f32_e32 v153, 0xbfb8aa3b, v15
	v_exp_f32_e32 v157, v157
	v_exp_f32_e32 v153, v153
	v_pk_mul_f32 v[158:159], v[158:159], v[176:177]
	v_add_f32_e32 v157, 1.0, v157
	v_add_f32_e32 v153, 1.0, v153
	v_rcp_f32_e32 v162, v157
	v_add_f32_e32 v157, 1.0, v161
	v_rcp_f32_e32 v163, v157
	v_rcp_f32_e32 v161, v153
	v_mul_f32_e32 v157, 0xbfb8aa3b, v6
	v_exp_f32_e32 v157, v157
	v_cvt_pk_bf16_f32 v153, v158, v159
	global_store_dwordx2 v[150:151], v[152:153], off offset:-4096
	v_pk_mul_f32 v[152:153], v[162:163], v[180:181]
	v_pk_mul_f32 v[158:159], v[160:161], v[178:179]
	s_nop 0
	v_cvt_pk_bf16_f32 v158, v158, v159
	v_cvt_pk_bf16_f32 v159, v152, v153
	v_add_f32_e32 v152, 1.0, v157
	v_mul_f32_e32 v157, 0xbfb8aa3b, v8
	global_store_dwordx2 v[150:151], v[158:159], off offset:-4064
	v_mul_f32_e32 v153, 0xbfb8aa3b, v7
	v_exp_f32_e32 v157, v157
	v_mul_f32_e32 v158, 0xbfb8aa3b, v9
	v_exp_f32_e32 v153, v153
	v_exp_f32_e32 v159, v158
	v_add_f32_e32 v157, 1.0, v157
	v_rcp_f32_e32 v158, v157
	v_add_f32_e32 v153, 1.0, v153
	v_add_f32_e32 v157, 1.0, v159
	v_rcp_f32_e32 v152, v152
	v_rcp_f32_e32 v159, v157
	v_rcp_f32_e32 v153, v153
	v_mul_f32_e32 v157, 0xbfb8aa3b, v2
	v_exp_f32_e32 v157, v157
	v_pk_mul_f32 v[136:137], v[158:159], v[136:137]
	v_pk_mul_f32 v[134:135], v[152:153], v[134:135]
	v_mul_f32_e32 v153, 0xbfb8aa3b, v4
	v_cvt_pk_bf16_f32 v134, v134, v135
	v_add_f32_e32 v135, 1.0, v157
	v_rcp_f32_e32 v152, v135
	v_mul_f32_e32 v135, 0xbfb8aa3b, v3
	v_exp_f32_e32 v153, v153
	v_mul_f32_e32 v157, 0xbfb8aa3b, v5
	v_exp_f32_e32 v135, v135
	v_exp_f32_e32 v157, v157
	v_add_f32_e32 v153, 1.0, v153
	v_rcp_f32_e32 v158, v153
	v_add_f32_e32 v135, 1.0, v135
	v_add_f32_e32 v153, 1.0, v157
	v_rcp_f32_e32 v159, v153
	v_rcp_f32_e32 v153, v135
	v_cvt_pk_bf16_f32 v135, v136, v137
	global_store_dwordx2 v[150:151], v[134:135], off offset:-3840
	v_pk_mul_f32 v[132:133], v[158:159], v[132:133]
	v_pk_mul_f32 v[130:131], v[152:153], v[130:131]
	s_nop 0
	v_cvt_pk_bf16_f32 v130, v130, v131
	v_cvt_pk_bf16_f32 v131, v132, v133
	global_store_dwordx2 v[150:151], v[130:131], off offset:-3808
